# MFMA order: P1 renamed blocks also paired/k-alternated by hand, second 16-block of each segment starts on the operand the first ended with
# speedup vs baseline: 1.0061x; 1.0061x over previous
; #define PG8_STAGE(bufoff, gbase, voff) do { _Pragma("unroll") for (int _i = 0; _i < 2; ++_i) \
;         __builtin_amdgcn_global_load_lds((const unsigned*)((const char*)(gbase) + (voff)[_i]), (PG8_LAS unsigned*)(lds + (bufoff) + ldsw + _i * 8192), 16, 0, 0); } while (0)
; #define PG8_LDA(dst, b, h) do { _Pragma("unroll") for (int m = 0; m < 4; ++m) _Pragma("unroll") for (int k = 0; k < 2; ++k) dst[m][k] = *(const PG8_LAS bf16x8*)(lds + PG8_SA(b, h) + aoff + m * 2048 + k * 1024); } while (0)
; #define PG8_LDB(dst, b, h) do { _Pragma("unroll") for (int n = 0; n < 2; ++n) _Pragma("unroll") for (int k = 0; k < 2; ++k) dst[n][k] = *(const PG8_LAS bf16x8*)(lds + PG8_SB(b, h) + boff + n * 2048 + k * 1024); } while (0)
; #define PG8_MMA(ai, bj, At, Bt) do { __builtin_amdgcn_s_setprio(1); _Pragma("unroll") for (int m = 0; m < 4; ++m) _Pragma("unroll") for (int n = 0; n < 2; ++n) _Pragma("unroll") for (int k = 0; k < 2; ++k) \
;         acc[ai][bj][m][n] = __builtin_amdgcn_mfma_f32_16x16x32_bf16(Bt[n][k], At[m][k], acc[ai][bj][m][n], 0, 0, 0); __builtin_amdgcn_s_setprio(0); } while (0)
; #define PG8_WAIT_V(n) asm volatile("s_waitcnt vmcnt(" #n ")" ::: "memory")
; #define PG8_WAIT_L(n) asm volatile("s_waitcnt lgkmcnt(" #n ")" ::: "memory")
; #define PG8_BAR __builtin_amdgcn_s_barrier()
; #define PG8_SCHED __builtin_amdgcn_sched_barrier(0)
; template <class Epi, class Sched, bool ALIGN_EPI = false, bool SP2 = false>
; __device__ __forceinline__ void gemm_phase(PG8_LAS unsigned char* lds, const Gemm g, const Sched& S, const Epi& E) {
;     ...
;             const bool last = (t == nt - 2);
;             const char* a1 = cA + (size_t)(t + 1) * kstep;
;             const char* a2 = last ? nA : cA + (size_t)(t + 2) * kstep; const char* b2 = last ? nB : cB + (size_t)(t + 2) * kstep;
;             const char* a3 = a2 + kstep; const char* b3 = b2 + kstep;
;             if (last && has_next) S.a_ready(nxt);
;             if constexpr (SP2) {
;             PG8_LDB(B0, 0, 0); PG8_LDB(B1, 0, 1); PG8_SCHED; PG8_LDA(At, 0, 0); PG8_STAGE(PG8_SA(1, 1), a1 + hstep, voffA);
;             PG8_WAIT_V(8); PG8_WAIT_L(0); PG8_BAR; PG8_MMA(0, 0, At, B0); PG8_MMA(0, 1, At, B1); PG8_BAR; PG8_SCHED;
;             PG8_LDA(At, 0, 1); PG8_STAGE(PG8_SB(0, 0), b2, voffB); PG8_STAGE(PG8_SB(0, 1), b2 + hstep, voffB); PG8_STAGE(PG8_SA(0, 0), a2, voffA);
.LBB0_139:
	ds_read_b128 v[2:5], v187
	ds_read_b128 v[6:9], v187 offset:1024
	ds_read_b128 v[138:141], v187 offset:2048
	ds_read_b128 v[142:145], v187 offset:3072
	ds_read_b128 v[146:149], v197
	ds_read_b128 v[150:153], v197 offset:1024
	ds_read_b128 v[154:157], v197 offset:2048
	ds_read_b128 v[158:161], v197 offset:3072
	s_add_u32 s14, s12, 0xfff00080
	s_addc_u32 s15, s13, -1
	s_cmp_eq_u32 s33, 60
	s_cselect_b32 s17, s2, s15
	s_cselect_b32 s16, s11, s14
	s_cselect_b32 s15, s26, s30
	s_cselect_b32 s14, s28, s29
	v_lshl_add_u64 v[162:163], s[12:13], 0, v[188:189]
	s_add_i32 m0, s27, 0xc000
	ds_read_b128 v[202:205], v199
	ds_read_b128 v[206:209], v199 offset:1024
	ds_read_b128 v[214:217], v199 offset:2048
	ds_read_b128 v[218:221], v199 offset:3072
	ds_read_b128 v[222:225], v199 offset:4096
	ds_read_b128 v[226:229], v199 offset:5120
	ds_read_b128 v[230:233], v199 offset:6144
	ds_read_b128 v[234:237], v199 offset:7168
	global_load_lds_dwordx4 v[162:163], off
	v_lshl_add_u64 v[162:163], s[12:13], 0, v[190:191]
	s_add_i32 m0, s27, 0xe000
	s_nop 0
	global_load_lds_dwordx4 v[162:163], off
	s_waitcnt vmcnt(8)
	s_waitcnt lgkmcnt(0)
	s_setprio 1
	s_barrier
	v_mfma_f32_16x16x32_bf16 v[134:137], v[2:5], v[202:205], v[134:137]
	v_mfma_f32_16x16x32_bf16 v[134:137], v[6:9], v[206:209], v[134:137]
	v_mfma_f32_16x16x32_bf16 v[118:121], v[6:9], v[218:221], v[118:121]
	v_mfma_f32_16x16x32_bf16 v[118:121], v[2:5], v[214:217], v[118:121]
	v_mfma_f32_16x16x32_bf16 v[102:105], v[2:5], v[222:225], v[102:105]
	v_mfma_f32_16x16x32_bf16 v[102:105], v[6:9], v[226:229], v[102:105]
	v_mfma_f32_16x16x32_bf16 v[86:89], v[6:9], v[234:237], v[86:89]
	v_mfma_f32_16x16x32_bf16 v[86:89], v[2:5], v[230:233], v[86:89]
	v_mfma_f32_16x16x32_bf16 v[82:85], v[138:141], v[230:233], v[82:85]
	v_mfma_f32_16x16x32_bf16 v[82:85], v[142:145], v[234:237], v[82:85]
	v_mfma_f32_16x16x32_bf16 v[130:133], v[142:145], v[206:209], v[130:133]
	v_mfma_f32_16x16x32_bf16 v[130:133], v[138:141], v[202:205], v[130:133]
	v_mfma_f32_16x16x32_bf16 v[114:117], v[138:141], v[214:217], v[114:117]
	v_mfma_f32_16x16x32_bf16 v[114:117], v[142:145], v[218:221], v[114:117]
	v_mfma_f32_16x16x32_bf16 v[98:101], v[142:145], v[226:229], v[98:101]
	v_mfma_f32_16x16x32_bf16 v[98:101], v[138:141], v[222:225], v[98:101]
	s_setprio 0
	s_setprio 1
	v_mfma_f32_16x16x32_bf16 v[94:97], v[146:149], v[222:225], v[94:97]
	v_mfma_f32_16x16x32_bf16 v[94:97], v[150:153], v[226:229], v[94:97]
	v_mfma_f32_16x16x32_bf16 v[126:129], v[150:153], v[206:209], v[126:129]
	v_mfma_f32_16x16x32_bf16 v[126:129], v[146:149], v[202:205], v[126:129]
	v_mfma_f32_16x16x32_bf16 v[110:113], v[146:149], v[214:217], v[110:113]
	v_mfma_f32_16x16x32_bf16 v[110:113], v[150:153], v[218:221], v[110:113]
	v_mfma_f32_16x16x32_bf16 v[78:81], v[150:153], v[234:237], v[78:81]
	v_mfma_f32_16x16x32_bf16 v[78:81], v[146:149], v[230:233], v[78:81]
	v_mfma_f32_16x16x32_bf16 v[74:77], v[154:157], v[230:233], v[74:77]
	v_mfma_f32_16x16x32_bf16 v[74:77], v[158:161], v[234:237], v[74:77]
	v_mfma_f32_16x16x32_bf16 v[122:125], v[158:161], v[206:209], v[122:125]
	v_mfma_f32_16x16x32_bf16 v[122:125], v[154:157], v[202:205], v[122:125]
	v_mfma_f32_16x16x32_bf16 v[106:109], v[154:157], v[214:217], v[106:109]
	v_mfma_f32_16x16x32_bf16 v[106:109], v[158:161], v[218:221], v[106:109]
	v_mfma_f32_16x16x32_bf16 v[90:93], v[158:161], v[226:229], v[90:93]
	v_mfma_f32_16x16x32_bf16 v[90:93], v[154:157], v[222:225], v[90:93]
	s_barrier
	s_setprio 0
	s_add_i32 s34, s41, s25
	v_lshl_add_u64 v[162:163], s[14:15], 0, v[168:169]
	s_mov_b32 m0, s34
	ds_read_b128 v[202:205], v199 offset:16384
	ds_read_b128 v[206:209], v199 offset:17408
	ds_read_b128 v[214:217], v199 offset:18432
	ds_read_b128 v[218:221], v199 offset:19456
	ds_read_b128 v[222:225], v199 offset:20480
	ds_read_b128 v[226:229], v199 offset:21504
	ds_read_b128 v[230:233], v199 offset:22528
	ds_read_b128 v[234:237], v199 offset:23552
	global_load_lds_dwordx4 v[162:163], off
	s_add_i32 m0, s34, 0x2000
	s_add_u32 s34, s14, 0x100000
	v_lshl_add_u64 v[210:211], s[14:15], 0, v[172:173]
	s_addc_u32 s35, s15, 0
	s_add_i32 s79, s92, s25
	global_load_lds_dwordx4 v[210:211], off
	v_lshl_add_u64 v[238:239], s[34:35], 0, v[168:169]
	s_mov_b32 m0, s79
	v_lshl_add_u64 v[240:241], s[16:17], 0, v[170:171]
	global_load_lds_dwordx4 v[238:239], off
	v_lshl_add_u64 v[238:239], s[34:35], 0, v[172:173]
	s_add_i32 m0, s79, 0x2000
	s_nop 0
	global_load_lds_dwordx4 v[238:239], off
	v_lshl_add_u64 v[238:239], s[16:17], 0, v[164:165]
	s_mov_b32 m0, s27
	s_nop 0
	global_load_lds_dwordx4 v[238:239], off
	s_mov_b32 m0, s39
	s_nop 0
	global_load_lds_dwordx4 v[240:241], off
	s_waitcnt vmcnt(8)
	s_waitcnt lgkmcnt(0)
	s_setprio 1
	s_barrier
; #define PG8_STAGE(bufoff, gbase, voff) do { _Pragma("unroll") for (int _i = 0; _i < 2; ++_i) \
;         __builtin_amdgcn_global_load_lds((const unsigned*)((const char*)(gbase) + (voff)[_i]), (PG8_LAS unsigned*)(lds + (bufoff) + ldsw + _i * 8192), 16, 0, 0); } while (0)
; #define PG8_LDA(dst, b, h) do { _Pragma("unroll") for (int m = 0; m < 4; ++m) _Pragma("unroll") for (int k = 0; k < 2; ++k) dst[m][k] = *(const PG8_LAS bf16x8*)(lds + PG8_SA(b, h) + aoff + m * 2048 + k * 1024); } while (0)
; #define PG8_LDB(dst, b, h) do { _Pragma("unroll") for (int n = 0; n < 2; ++n) _Pragma("unroll") for (int k = 0; k < 2; ++k) dst[n][k] = *(const PG8_LAS bf16x8*)(lds + PG8_SB(b, h) + boff + n * 2048 + k * 1024); } while (0)
; #define PG8_MMA(ai, bj, At, Bt) do { __builtin_amdgcn_s_setprio(1); _Pragma("unroll") for (int m = 0; m < 4; ++m) _Pragma("unroll") for (int n = 0; n < 2; ++n) _Pragma("unroll") for (int k = 0; k < 2; ++k) \
;         acc[ai][bj][m][n] = __builtin_amdgcn_mfma_f32_16x16x32_bf16(Bt[n][k], At[m][k], acc[ai][bj][m][n], 0, 0, 0); __builtin_amdgcn_s_setprio(0); } while (0)
; #define PG8_WAIT_V(n) asm volatile("s_waitcnt vmcnt(" #n ")" ::: "memory")
; #define PG8_WAIT_L(n) asm volatile("s_waitcnt lgkmcnt(" #n ")" ::: "memory")
; #define PG8_BAR __builtin_amdgcn_s_barrier()
; #define PG8_SCHED __builtin_amdgcn_sched_barrier(0)
; template <class Epi, class Sched, bool ALIGN_EPI = false, bool SP2 = false>
; __device__ __forceinline__ void gemm_phase(PG8_LAS unsigned char* lds, const Gemm g, const Sched& S, const Epi& E) {
;     ...
;             PG8_WAIT_V(8); PG8_WAIT_L(0); PG8_BAR; PG8_MMA(1, 0, At, B0); PG8_MMA(1, 1, At, B1); PG8_BAR; PG8_SCHED;
;             PG8_LDB(B0, 1, 0); PG8_LDB(B1, 1, 1); PG8_SCHED; PG8_LDA(At, 1, 0); PG8_STAGE(PG8_SA(0, 1), a2 + hstep, voffA);
;             PG8_WAIT_V(8); PG8_WAIT_L(0); PG8_BAR; PG8_MMA(0, 0, At, B0); PG8_MMA(0, 1, At, B1); PG8_BAR; PG8_SCHED;
	v_mfma_f32_16x16x32_bf16 v[70:73], v[6:9], v[206:209], v[70:73]
	v_mfma_f32_16x16x32_bf16 v[70:73], v[2:5], v[202:205], v[70:73]
	v_mfma_f32_16x16x32_bf16 v[54:57], v[2:5], v[214:217], v[54:57]
	v_mfma_f32_16x16x32_bf16 v[54:57], v[6:9], v[218:221], v[54:57]
	v_mfma_f32_16x16x32_bf16 v[38:41], v[6:9], v[226:229], v[38:41]
	v_mfma_f32_16x16x32_bf16 v[38:41], v[2:5], v[222:225], v[38:41]
	v_mfma_f32_16x16x32_bf16 v[2:5], v[2:5], v[230:233], v[22:25]
	v_mfma_f32_16x16x32_bf16 v[2:5], v[6:9], v[234:237], v[2:5]
	v_mfma_f32_16x16x32_bf16 v[6:9], v[142:145], v[234:237], v[18:21]
	v_mfma_f32_16x16x32_bf16 v[6:9], v[138:141], v[230:233], v[6:9]
	v_mfma_f32_16x16x32_bf16 v[66:69], v[138:141], v[202:205], v[66:69]
	v_mfma_f32_16x16x32_bf16 v[66:69], v[142:145], v[206:209], v[66:69]
	v_mfma_f32_16x16x32_bf16 v[50:53], v[142:145], v[218:221], v[50:53]
	v_mfma_f32_16x16x32_bf16 v[50:53], v[138:141], v[214:217], v[50:53]
	v_mfma_f32_16x16x32_bf16 v[34:37], v[138:141], v[222:225], v[34:37]
	v_mfma_f32_16x16x32_bf16 v[34:37], v[142:145], v[226:229], v[34:37]
	s_setprio 0
	s_setprio 1
	v_mfma_f32_16x16x32_bf16 v[18:21], v[150:153], v[226:229], v[30:33]
	v_mfma_f32_16x16x32_bf16 v[30:33], v[146:149], v[222:225], v[18:21]
	v_mfma_f32_16x16x32_bf16 v[14:17], v[146:149], v[230:233], v[14:17]
	v_mfma_f32_16x16x32_bf16 v[14:17], v[150:153], v[234:237], v[14:17]
	v_mfma_f32_16x16x32_bf16 v[18:21], v[150:153], v[206:209], v[62:65]
	v_mfma_f32_16x16x32_bf16 v[62:65], v[146:149], v[202:205], v[18:21]
	v_mfma_f32_16x16x32_bf16 v[18:21], v[146:149], v[214:217], v[46:49]
	v_mfma_f32_16x16x32_bf16 v[46:49], v[150:153], v[218:221], v[18:21]
	v_mfma_f32_16x16x32_bf16 v[18:21], v[158:161], v[218:221], v[42:45]
	v_mfma_f32_16x16x32_bf16 v[42:45], v[154:157], v[214:217], v[18:21]
	v_mfma_f32_16x16x32_bf16 v[18:21], v[154:157], v[222:225], v[26:29]
	v_mfma_f32_16x16x32_bf16 v[26:29], v[158:161], v[226:229], v[18:21]
	v_mfma_f32_16x16x32_bf16 v[10:13], v[158:161], v[234:237], v[10:13]
	v_mfma_f32_16x16x32_bf16 v[10:13], v[154:157], v[230:233], v[10:13]
	v_mfma_f32_16x16x32_bf16 v[18:21], v[154:157], v[202:205], v[58:61]
	v_mfma_f32_16x16x32_bf16 v[58:61], v[158:161], v[206:209], v[18:21]
	s_barrier
	s_setprio 0
	s_add_i32 s34, 0, 0x18000
	s_add_i32 s35, 0, 0x1c000
	v_add_u32_e32 v142, s34, v179
	v_add_u32_e32 v158, s35, v179
	ds_read_b128 v[18:21], v142
	ds_read_b128 v[22:25], v142 offset:1024
	ds_read_b128 v[138:141], v142 offset:2048
	ds_read_b128 v[142:145], v142 offset:3072
	ds_read_b128 v[146:149], v158
	ds_read_b128 v[150:153], v158 offset:1024
	ds_read_b128 v[154:157], v158 offset:2048
	ds_read_b128 v[158:161], v158 offset:3072
	s_add_u32 s16, s16, 0x100000
	s_addc_u32 s17, s17, 0
	s_mov_b32 m0, s71
	v_lshl_add_u64 v[242:243], s[16:17], 0, v[164:165]
	ds_read_b128 v[202:205], v199 offset:32768
	ds_read_b128 v[206:209], v199 offset:33792
	ds_read_b128 v[214:217], v199 offset:34816
	ds_read_b128 v[218:221], v199 offset:35840
	ds_read_b128 v[222:225], v199 offset:36864
	ds_read_b128 v[226:229], v199 offset:37888
	ds_read_b128 v[230:233], v199 offset:38912
	ds_read_b128 v[234:237], v199 offset:39936
	global_load_lds_dwordx4 v[242:243], off
	v_lshl_add_u64 v[242:243], s[16:17], 0, v[170:171]
	s_mov_b32 m0, s87
	s_nop 0
	global_load_lds_dwordx4 v[242:243], off
	s_waitcnt vmcnt(8)
	s_waitcnt lgkmcnt(0)
	s_setprio 1
	s_barrier
	v_mfma_f32_16x16x32_bf16 v[134:137], v[18:21], v[202:205], v[134:137]
	v_mfma_f32_16x16x32_bf16 v[134:137], v[22:25], v[206:209], v[134:137]
	v_mfma_f32_16x16x32_bf16 v[118:121], v[22:25], v[218:221], v[118:121]
	v_mfma_f32_16x16x32_bf16 v[118:121], v[18:21], v[214:217], v[118:121]
	v_mfma_f32_16x16x32_bf16 v[102:105], v[18:21], v[222:225], v[102:105]
	v_mfma_f32_16x16x32_bf16 v[102:105], v[22:25], v[226:229], v[102:105]
	v_mfma_f32_16x16x32_bf16 v[86:89], v[22:25], v[234:237], v[86:89]
	v_mfma_f32_16x16x32_bf16 v[86:89], v[18:21], v[230:233], v[86:89]
	v_mfma_f32_16x16x32_bf16 v[82:85], v[138:141], v[230:233], v[82:85]
	v_mfma_f32_16x16x32_bf16 v[82:85], v[142:145], v[234:237], v[82:85]
	v_mfma_f32_16x16x32_bf16 v[130:133], v[142:145], v[206:209], v[130:133]
	v_mfma_f32_16x16x32_bf16 v[130:133], v[138:141], v[202:205], v[130:133]
	v_mfma_f32_16x16x32_bf16 v[114:117], v[138:141], v[214:217], v[114:117]
	v_mfma_f32_16x16x32_bf16 v[114:117], v[142:145], v[218:221], v[114:117]
	v_mfma_f32_16x16x32_bf16 v[98:101], v[142:145], v[226:229], v[98:101]
	v_mfma_f32_16x16x32_bf16 v[98:101], v[138:141], v[222:225], v[98:101]
	s_setprio 0
	s_setprio 1
	v_mfma_f32_16x16x32_bf16 v[94:97], v[146:149], v[222:225], v[94:97]
	v_mfma_f32_16x16x32_bf16 v[94:97], v[150:153], v[226:229], v[94:97]
	v_mfma_f32_16x16x32_bf16 v[126:129], v[150:153], v[206:209], v[126:129]
	v_mfma_f32_16x16x32_bf16 v[126:129], v[146:149], v[202:205], v[126:129]
	v_mfma_f32_16x16x32_bf16 v[110:113], v[146:149], v[214:217], v[110:113]
	v_mfma_f32_16x16x32_bf16 v[110:113], v[150:153], v[218:221], v[110:113]
	v_mfma_f32_16x16x32_bf16 v[78:81], v[150:153], v[234:237], v[78:81]
	v_mfma_f32_16x16x32_bf16 v[78:81], v[146:149], v[230:233], v[78:81]
	v_mfma_f32_16x16x32_bf16 v[74:77], v[154:157], v[230:233], v[74:77]
	v_mfma_f32_16x16x32_bf16 v[74:77], v[158:161], v[234:237], v[74:77]
	v_mfma_f32_16x16x32_bf16 v[122:125], v[158:161], v[206:209], v[122:125]
	v_mfma_f32_16x16x32_bf16 v[122:125], v[154:157], v[202:205], v[122:125]
	v_mfma_f32_16x16x32_bf16 v[106:109], v[154:157], v[214:217], v[106:109]
	v_mfma_f32_16x16x32_bf16 v[106:109], v[158:161], v[218:221], v[106:109]
	v_mfma_f32_16x16x32_bf16 v[90:93], v[158:161], v[226:229], v[90:93]
	v_mfma_f32_16x16x32_bf16 v[90:93], v[154:157], v[222:225], v[90:93]
	s_barrier
; #define PG8_STAGE(bufoff, gbase, voff) do { _Pragma("unroll") for (int _i = 0; _i < 2; ++_i) \
;         __builtin_amdgcn_global_load_lds((const unsigned*)((const char*)(gbase) + (voff)[_i]), (PG8_LAS unsigned*)(lds + (bufoff) + ldsw + _i * 8192), 16, 0, 0); } while (0)
; #define PG8_LDA(dst, b, h) do { _Pragma("unroll") for (int m = 0; m < 4; ++m) _Pragma("unroll") for (int k = 0; k < 2; ++k) dst[m][k] = *(const PG8_LAS bf16x8*)(lds + PG8_SA(b, h) + aoff + m * 2048 + k * 1024); } while (0)
; #define PG8_MMA(ai, bj, At, Bt) do { __builtin_amdgcn_s_setprio(1); _Pragma("unroll") for (int m = 0; m < 4; ++m) _Pragma("unroll") for (int n = 0; n < 2; ++n) _Pragma("unroll") for (int k = 0; k < 2; ++k) \
;         acc[ai][bj][m][n] = __builtin_amdgcn_mfma_f32_16x16x32_bf16(Bt[n][k], At[m][k], acc[ai][bj][m][n], 0, 0, 0); __builtin_amdgcn_s_setprio(0); } while (0)
; #define PG8_WAIT_V(n) asm volatile("s_waitcnt vmcnt(" #n ")" ::: "memory")
; #define PG8_WAIT_L(n) asm volatile("s_waitcnt lgkmcnt(" #n ")" ::: "memory")
; #define PG8_BAR __builtin_amdgcn_s_barrier()
; #define PG8_SCHED __builtin_amdgcn_sched_barrier(0)
; template <class Epi, class Sched, bool ALIGN_EPI = false, bool SP2 = false>
; __device__ __forceinline__ void gemm_phase(PG8_LAS unsigned char* lds, const Gemm g, const Sched& S, const Epi& E) {
;     ...
;             PG8_LDA(At, 1, 1); PG8_STAGE(PG8_SB(1, 0), b3, voffB); PG8_STAGE(PG8_SB(1, 1), b3 + hstep, voffB); PG8_STAGE(PG8_SA(1, 0), a3, voffA);
;             PG8_WAIT_V(8); PG8_WAIT_L(0); PG8_BAR; PG8_MMA(1, 0, At, B0); PG8_MMA(1, 1, At, B1); PG8_BAR; PG8_SCHED;
;     ...
;         if constexpr (ALIGN_EPI) { if (wr == 0) PG8_BAR; }
	s_setprio 0
	s_add_i32 s16, s34, s25
	v_lshl_add_u64 v[162:163], v[162:163], 0, s[46:47]
	s_mov_b32 m0, s16
	ds_read_b128 v[202:205], v199 offset:49152
	ds_read_b128 v[206:209], v199 offset:50176
	ds_read_b128 v[214:217], v199 offset:51200
	ds_read_b128 v[218:221], v199 offset:52224
	ds_read_b128 v[222:225], v199 offset:53248
	ds_read_b128 v[226:229], v199 offset:54272
	ds_read_b128 v[230:233], v199 offset:55296
	ds_read_b128 v[234:237], v199 offset:56320
	global_load_lds_dwordx4 v[162:163], off
	s_add_i32 m0, s16, 0x2000
	s_add_u32 s14, s14, 0x100080
	v_lshl_add_u64 v[162:163], v[210:211], 0, s[46:47]
	s_addc_u32 s15, s15, 0
	s_add_i32 s16, s35, s25
	global_load_lds_dwordx4 v[162:163], off
	v_lshl_add_u64 v[162:163], s[14:15], 0, v[168:169]
	s_mov_b32 m0, s16
	s_nop 0
	global_load_lds_dwordx4 v[162:163], off
	v_lshl_add_u64 v[162:163], s[14:15], 0, v[172:173]
	s_add_i32 m0, s16, 0x2000
	s_nop 0
	global_load_lds_dwordx4 v[162:163], off
	v_lshl_add_u64 v[162:163], v[238:239], 0, s[46:47]
	s_mov_b32 m0, s95
	s_nop 0
	global_load_lds_dwordx4 v[162:163], off
	v_lshl_add_u64 v[162:163], v[240:241], 0, s[46:47]
	s_mov_b32 m0, s96
	s_nop 0
	global_load_lds_dwordx4 v[162:163], off
	s_waitcnt vmcnt(8)
	s_waitcnt lgkmcnt(0)
	s_setprio 1
	s_barrier
	v_mfma_f32_16x16x32_bf16 v[70:73], v[18:21], v[202:205], v[70:73]
	v_mfma_f32_16x16x32_bf16 v[70:73], v[22:25], v[206:209], v[70:73]
	v_mfma_f32_16x16x32_bf16 v[54:57], v[22:25], v[218:221], v[54:57]
	v_mfma_f32_16x16x32_bf16 v[54:57], v[18:21], v[214:217], v[54:57]
	v_mfma_f32_16x16x32_bf16 v[38:41], v[18:21], v[222:225], v[38:41]
	v_mfma_f32_16x16x32_bf16 v[38:41], v[22:25], v[226:229], v[38:41]
	v_mfma_f32_16x16x32_bf16 v[2:5], v[22:25], v[234:237], v[2:5]
	v_mfma_f32_16x16x32_bf16 v[22:25], v[18:21], v[230:233], v[2:5]
	v_mfma_f32_16x16x32_bf16 v[2:5], v[138:141], v[230:233], v[6:9]
	v_mfma_f32_16x16x32_bf16 v[18:21], v[142:145], v[234:237], v[2:5]
	v_mfma_f32_16x16x32_bf16 v[66:69], v[142:145], v[206:209], v[66:69]
	v_mfma_f32_16x16x32_bf16 v[66:69], v[138:141], v[202:205], v[66:69]
	v_mfma_f32_16x16x32_bf16 v[50:53], v[138:141], v[214:217], v[50:53]
	v_mfma_f32_16x16x32_bf16 v[50:53], v[142:145], v[218:221], v[50:53]
	v_mfma_f32_16x16x32_bf16 v[34:37], v[142:145], v[226:229], v[34:37]
	v_mfma_f32_16x16x32_bf16 v[34:37], v[138:141], v[222:225], v[34:37]
	s_setprio 0
	s_setprio 1
	v_mfma_f32_16x16x32_bf16 v[2:5], v[146:149], v[222:225], v[30:33]
	v_mfma_f32_16x16x32_bf16 v[30:33], v[150:153], v[226:229], v[2:5]
	v_mfma_f32_16x16x32_bf16 v[2:5], v[150:153], v[234:237], v[14:17]
	v_mfma_f32_16x16x32_bf16 v[14:17], v[146:149], v[230:233], v[2:5]
	v_mfma_f32_16x16x32_bf16 v[2:5], v[146:149], v[202:205], v[62:65]
	v_mfma_f32_16x16x32_bf16 v[62:65], v[150:153], v[206:209], v[2:5]
	v_mfma_f32_16x16x32_bf16 v[2:5], v[150:153], v[218:221], v[46:49]
	v_mfma_f32_16x16x32_bf16 v[46:49], v[146:149], v[214:217], v[2:5]
	v_mfma_f32_16x16x32_bf16 v[2:5], v[154:157], v[214:217], v[42:45]
	v_mfma_f32_16x16x32_bf16 v[42:45], v[158:161], v[218:221], v[2:5]
	v_mfma_f32_16x16x32_bf16 v[2:5], v[158:161], v[226:229], v[26:29]
	v_mfma_f32_16x16x32_bf16 v[26:29], v[154:157], v[222:225], v[2:5]
	v_mfma_f32_16x16x32_bf16 v[2:5], v[154:157], v[230:233], v[10:13]
	v_mfma_f32_16x16x32_bf16 v[10:13], v[158:161], v[234:237], v[2:5]
	v_mfma_f32_16x16x32_bf16 v[2:5], v[158:161], v[206:209], v[58:61]
	v_mfma_f32_16x16x32_bf16 v[58:61], v[154:157], v[202:205], v[2:5]
	s_barrier
	s_setprio 0
	s_add_i32 s33, s33, 2
	s_add_u32 s12, s12, 0x100
	s_addc_u32 s13, s13, 0
	s_add_u32 s29, s29, 0x100
	s_addc_u32 s30, s30, 0
	s_cmp_gt_u32 s33, 61
	s_cbranch_scc0 .LBB0_139
	s_and_b64 vcc, exec, s[48:49]
	s_cbranch_vccz .LBB0_142
	s_barrier

; #define PG8_STAGE(bufoff, gbase, voff) do { _Pragma("unroll") for (int _i = 0; _i < 2; ++_i) \
;         __builtin_amdgcn_global_load_lds((const unsigned*)((const char*)(gbase) + (voff)[_i]), (PG8_LAS unsigned*)(lds + (bufoff) + ldsw + _i * 8192), 16, 0, 0); } while (0)
; #define PG8_LDA(dst, b, h) do { _Pragma("unroll") for (int m = 0; m < 4; ++m) _Pragma("unroll") for (int k = 0; k < 2; ++k) dst[m][k] = *(const PG8_LAS bf16x8*)(lds + PG8_SA(b, h) + aoff + m * 2048 + k * 1024); } while (0)
; #define PG8_LDB(dst, b, h) do { _Pragma("unroll") for (int n = 0; n < 2; ++n) _Pragma("unroll") for (int k = 0; k < 2; ++k) dst[n][k] = *(const PG8_LAS bf16x8*)(lds + PG8_SB(b, h) + boff + n * 2048 + k * 1024); } while (0)
; #define PG8_MMA(ai, bj, At, Bt) do { __builtin_amdgcn_s_setprio(1); _Pragma("unroll") for (int m = 0; m < 4; ++m) _Pragma("unroll") for (int n = 0; n < 2; ++n) _Pragma("unroll") for (int k = 0; k < 2; ++k) \
;         acc[ai][bj][m][n] = __builtin_amdgcn_mfma_f32_16x16x32_bf16(Bt[n][k], At[m][k], acc[ai][bj][m][n], 0, 0, 0); __builtin_amdgcn_s_setprio(0); } while (0)
; #define PG8_WAIT_V(n) asm volatile("s_waitcnt vmcnt(" #n ")" ::: "memory")
; #define PG8_WAIT_L(n) asm volatile("s_waitcnt lgkmcnt(" #n ")" ::: "memory")
; #define PG8_BAR __builtin_amdgcn_s_barrier()
; #define PG8_SCHED __builtin_amdgcn_sched_barrier(0)
; template <class Epi, class Sched, bool ALIGN_EPI = false, bool SP2 = false>
; __device__ __forceinline__ void gemm_phase(PG8_LAS unsigned char* lds, const Gemm g, const Sched& S, const Epi& E) {
;     ...
;             const bool last = (t == nt - 2);
;             const char* a1 = cA + (size_t)(t + 1) * kstep;
;             const char* a2 = last ? nA : cA + (size_t)(t + 2) * kstep; const char* b2 = last ? nB : cB + (size_t)(t + 2) * kstep;
;             const char* a3 = a2 + kstep; const char* b3 = b2 + kstep;
;             if (last && has_next) S.a_ready(nxt);
;             if constexpr (SP2) {
;             PG8_LDB(B0, 0, 0); PG8_LDB(B1, 0, 1); PG8_SCHED; PG8_LDA(At, 0, 0); PG8_STAGE(PG8_SA(1, 1), a1 + hstep, voffA);
;             PG8_WAIT_V(8); PG8_WAIT_L(0); PG8_BAR; PG8_MMA(0, 0, At, B0); PG8_MMA(0, 1, At, B1); PG8_BAR; PG8_SCHED;
;             PG8_LDA(At, 0, 1); PG8_STAGE(PG8_SB(0, 0), b2, voffB); PG8_STAGE(PG8_SB(0, 1), b2 + hstep, voffB); PG8_STAGE(PG8_SA(0, 0), a2, voffA);
.LBB0_1062:
	ds_read_b128 v[146:149], v155
	ds_read_b128 v[158:161], v155 offset:1024
	ds_read_b128 v[168:171], v155 offset:2048
	ds_read_b128 v[172:175], v155 offset:3072
	ds_read_b128 v[176:179], v156
	ds_read_b128 v[180:183], v156 offset:1024
	ds_read_b128 v[184:187], v156 offset:2048
	ds_read_b128 v[188:191], v156 offset:3072
	s_add_u32 s72, s70, 0xfff80080
	s_addc_u32 s73, s71, -1
	s_cmp_eq_u32 s77, 28
	s_cselect_b32 s75, s34, s73
	s_cselect_b32 s74, s35, s72
	s_cselect_b32 s73, s61, s76
	s_cselect_b32 s72, s63, s69
	v_lshl_add_u64 v[150:151], s[70:71], 0, v[138:139]
	s_add_i32 m0, s25, 0xc000
	ds_read_b128 v[200:203], v157
	ds_read_b128 v[204:207], v157 offset:1024
	ds_read_b128 v[208:211], v157 offset:2048
	ds_read_b128 v[212:215], v157 offset:3072
	ds_read_b128 v[216:219], v157 offset:4096
	ds_read_b128 v[220:223], v157 offset:5120
	ds_read_b128 v[224:227], v157 offset:6144
	ds_read_b128 v[228:231], v157 offset:7168
	global_load_lds_dwordx4 v[150:151], off
	v_lshl_add_u64 v[150:151], s[70:71], 0, v[140:141]
	s_add_i32 m0, s25, 0xe000
	s_nop 0
	global_load_lds_dwordx4 v[150:151], off
	s_waitcnt vmcnt(8)
	s_waitcnt lgkmcnt(0)
	s_setprio 1
	s_barrier
	v_mfma_f32_16x16x32_bf16 v[126:129], v[146:149], v[200:203], v[126:129]
	v_mfma_f32_16x16x32_bf16 v[126:129], v[158:161], v[204:207], v[126:129]
	v_mfma_f32_16x16x32_bf16 v[110:113], v[158:161], v[212:215], v[110:113]
	v_mfma_f32_16x16x32_bf16 v[110:113], v[146:149], v[208:211], v[110:113]
	v_mfma_f32_16x16x32_bf16 v[94:97], v[146:149], v[216:219], v[94:97]
	v_mfma_f32_16x16x32_bf16 v[94:97], v[158:161], v[220:223], v[94:97]
	v_mfma_f32_16x16x32_bf16 v[78:81], v[158:161], v[228:231], v[78:81]
	v_mfma_f32_16x16x32_bf16 v[78:81], v[146:149], v[224:227], v[78:81]
	v_mfma_f32_16x16x32_bf16 v[74:77], v[168:171], v[224:227], v[74:77]
	v_mfma_f32_16x16x32_bf16 v[74:77], v[172:175], v[228:231], v[74:77]
	v_mfma_f32_16x16x32_bf16 v[122:125], v[172:175], v[204:207], v[122:125]
	v_mfma_f32_16x16x32_bf16 v[122:125], v[168:171], v[200:203], v[122:125]
	v_mfma_f32_16x16x32_bf16 v[106:109], v[168:171], v[208:211], v[106:109]
	v_mfma_f32_16x16x32_bf16 v[106:109], v[172:175], v[212:215], v[106:109]
	v_mfma_f32_16x16x32_bf16 v[90:93], v[172:175], v[220:223], v[90:93]
	v_mfma_f32_16x16x32_bf16 v[90:93], v[168:171], v[216:219], v[90:93]
	s_setprio 0
	s_setprio 1
	v_mfma_f32_16x16x32_bf16 v[86:89], v[176:179], v[216:219], v[86:89]
	v_mfma_f32_16x16x32_bf16 v[86:89], v[180:183], v[220:223], v[86:89]
	v_mfma_f32_16x16x32_bf16 v[118:121], v[180:183], v[204:207], v[118:121]
	v_mfma_f32_16x16x32_bf16 v[118:121], v[176:179], v[200:203], v[118:121]
	v_mfma_f32_16x16x32_bf16 v[102:105], v[176:179], v[208:211], v[102:105]
	v_mfma_f32_16x16x32_bf16 v[102:105], v[180:183], v[212:215], v[102:105]
	v_mfma_f32_16x16x32_bf16 v[70:73], v[180:183], v[228:231], v[70:73]
	v_mfma_f32_16x16x32_bf16 v[70:73], v[176:179], v[224:227], v[70:73]
	v_mfma_f32_16x16x32_bf16 v[66:69], v[184:187], v[224:227], v[66:69]
	v_mfma_f32_16x16x32_bf16 v[66:69], v[188:191], v[228:231], v[66:69]
	v_mfma_f32_16x16x32_bf16 v[114:117], v[188:191], v[204:207], v[114:117]
	v_mfma_f32_16x16x32_bf16 v[114:117], v[184:187], v[200:203], v[114:117]
	v_mfma_f32_16x16x32_bf16 v[98:101], v[184:187], v[208:211], v[98:101]
	v_mfma_f32_16x16x32_bf16 v[98:101], v[188:191], v[212:215], v[98:101]
	v_mfma_f32_16x16x32_bf16 v[82:85], v[188:191], v[220:223], v[82:85]
	v_mfma_f32_16x16x32_bf16 v[82:85], v[184:187], v[216:219], v[82:85]
	s_barrier
	s_setprio 0
	s_add_i32 s78, s31, s2
	v_lshl_add_u64 v[150:151], s[72:73], 0, v[134:135]
	s_mov_b32 m0, s78
	ds_read_b128 v[200:203], v157 offset:16384
	ds_read_b128 v[204:207], v157 offset:17408
	ds_read_b128 v[208:211], v157 offset:18432
	ds_read_b128 v[212:215], v157 offset:19456
	ds_read_b128 v[216:219], v157 offset:20480
	ds_read_b128 v[220:223], v157 offset:21504
	ds_read_b128 v[224:227], v157 offset:22528
	ds_read_b128 v[228:231], v157 offset:23552
	global_load_lds_dwordx4 v[150:151], off
	s_add_i32 m0, s78, 0x2000
	s_add_u32 s78, s72, 0x80000
	v_lshl_add_u64 v[162:163], s[72:73], 0, v[130:131]
	s_addc_u32 s79, s73, 0
	s_add_i32 s80, s40, s2
	global_load_lds_dwordx4 v[162:163], off
	v_lshl_add_u64 v[192:193], s[78:79], 0, v[134:135]
	s_mov_b32 m0, s80
	v_lshl_add_u64 v[232:233], s[74:75], 0, v[132:133]
	global_load_lds_dwordx4 v[192:193], off
	v_lshl_add_u64 v[192:193], s[78:79], 0, v[130:131]
	s_add_i32 m0, s80, 0x2000
	s_nop 0
	global_load_lds_dwordx4 v[192:193], off
	v_lshl_add_u64 v[192:193], s[74:75], 0, v[136:137]
	s_mov_b32 m0, s25
	s_nop 0
	global_load_lds_dwordx4 v[192:193], off
	s_mov_b32 m0, s26
	s_nop 0
	global_load_lds_dwordx4 v[232:233], off
	s_waitcnt vmcnt(8)
	s_waitcnt lgkmcnt(0)
	s_setprio 1
	s_barrier
; #define PG8_STAGE(bufoff, gbase, voff) do { _Pragma("unroll") for (int _i = 0; _i < 2; ++_i) \
;         __builtin_amdgcn_global_load_lds((const unsigned*)((const char*)(gbase) + (voff)[_i]), (PG8_LAS unsigned*)(lds + (bufoff) + ldsw + _i * 8192), 16, 0, 0); } while (0)
; #define PG8_LDA(dst, b, h) do { _Pragma("unroll") for (int m = 0; m < 4; ++m) _Pragma("unroll") for (int k = 0; k < 2; ++k) dst[m][k] = *(const PG8_LAS bf16x8*)(lds + PG8_SA(b, h) + aoff + m * 2048 + k * 1024); } while (0)
; #define PG8_LDB(dst, b, h) do { _Pragma("unroll") for (int n = 0; n < 2; ++n) _Pragma("unroll") for (int k = 0; k < 2; ++k) dst[n][k] = *(const PG8_LAS bf16x8*)(lds + PG8_SB(b, h) + boff + n * 2048 + k * 1024); } while (0)
; #define PG8_MMA(ai, bj, At, Bt) do { __builtin_amdgcn_s_setprio(1); _Pragma("unroll") for (int m = 0; m < 4; ++m) _Pragma("unroll") for (int n = 0; n < 2; ++n) _Pragma("unroll") for (int k = 0; k < 2; ++k) \
;         acc[ai][bj][m][n] = __builtin_amdgcn_mfma_f32_16x16x32_bf16(Bt[n][k], At[m][k], acc[ai][bj][m][n], 0, 0, 0); __builtin_amdgcn_s_setprio(0); } while (0)
; #define PG8_WAIT_V(n) asm volatile("s_waitcnt vmcnt(" #n ")" ::: "memory")
; #define PG8_WAIT_L(n) asm volatile("s_waitcnt lgkmcnt(" #n ")" ::: "memory")
; #define PG8_BAR __builtin_amdgcn_s_barrier()
; #define PG8_SCHED __builtin_amdgcn_sched_barrier(0)
; template <class Epi, class Sched, bool ALIGN_EPI = false, bool SP2 = false>
; __device__ __forceinline__ void gemm_phase(PG8_LAS unsigned char* lds, const Gemm g, const Sched& S, const Epi& E) {
;     ...
;             PG8_WAIT_V(8); PG8_WAIT_L(0); PG8_BAR; PG8_MMA(1, 0, At, B0); PG8_MMA(1, 1, At, B1); PG8_BAR; PG8_SCHED;
;             PG8_LDB(B0, 1, 0); PG8_LDB(B1, 1, 1); PG8_SCHED; PG8_LDA(At, 1, 0); PG8_STAGE(PG8_SA(0, 1), a2 + hstep, voffA);
;             PG8_WAIT_V(8); PG8_WAIT_L(0); PG8_BAR; PG8_MMA(0, 0, At, B0); PG8_MMA(0, 1, At, B1); PG8_BAR; PG8_SCHED;
	v_mfma_f32_16x16x32_bf16 v[62:65], v[146:149], v[200:203], v[62:65]
	v_mfma_f32_16x16x32_bf16 v[62:65], v[158:161], v[204:207], v[62:65]
	v_mfma_f32_16x16x32_bf16 v[46:49], v[158:161], v[212:215], v[46:49]
	v_mfma_f32_16x16x32_bf16 v[46:49], v[146:149], v[208:211], v[46:49]
	v_mfma_f32_16x16x32_bf16 v[30:33], v[146:149], v[216:219], v[30:33]
	v_mfma_f32_16x16x32_bf16 v[30:33], v[158:161], v[220:223], v[30:33]
	v_mfma_f32_16x16x32_bf16 v[14:17], v[158:161], v[228:231], v[14:17]
	v_mfma_f32_16x16x32_bf16 v[14:17], v[146:149], v[224:227], v[14:17]
	v_mfma_f32_16x16x32_bf16 v[10:13], v[168:171], v[224:227], v[10:13]
	v_mfma_f32_16x16x32_bf16 v[10:13], v[172:175], v[228:231], v[10:13]
	v_mfma_f32_16x16x32_bf16 v[58:61], v[172:175], v[204:207], v[58:61]
	v_mfma_f32_16x16x32_bf16 v[58:61], v[168:171], v[200:203], v[58:61]
	v_mfma_f32_16x16x32_bf16 v[42:45], v[168:171], v[208:211], v[42:45]
	v_mfma_f32_16x16x32_bf16 v[42:45], v[172:175], v[212:215], v[42:45]
	v_mfma_f32_16x16x32_bf16 v[26:29], v[172:175], v[220:223], v[26:29]
	v_mfma_f32_16x16x32_bf16 v[26:29], v[168:171], v[216:219], v[26:29]
	s_setprio 0
	s_setprio 1
	v_mfma_f32_16x16x32_bf16 v[22:25], v[176:179], v[216:219], v[22:25]
	v_mfma_f32_16x16x32_bf16 v[22:25], v[180:183], v[220:223], v[22:25]
	v_mfma_f32_16x16x32_bf16 v[54:57], v[180:183], v[204:207], v[54:57]
	v_mfma_f32_16x16x32_bf16 v[54:57], v[176:179], v[200:203], v[54:57]
	v_mfma_f32_16x16x32_bf16 v[38:41], v[176:179], v[208:211], v[38:41]
	v_mfma_f32_16x16x32_bf16 v[38:41], v[180:183], v[212:215], v[38:41]
	v_mfma_f32_16x16x32_bf16 v[6:9], v[180:183], v[228:231], v[6:9]
	v_mfma_f32_16x16x32_bf16 v[6:9], v[176:179], v[224:227], v[6:9]
	v_mfma_f32_16x16x32_bf16 v[2:5], v[184:187], v[224:227], v[2:5]
	v_mfma_f32_16x16x32_bf16 v[2:5], v[188:191], v[228:231], v[2:5]
	v_mfma_f32_16x16x32_bf16 v[50:53], v[188:191], v[204:207], v[50:53]
	v_mfma_f32_16x16x32_bf16 v[50:53], v[184:187], v[200:203], v[50:53]
	v_mfma_f32_16x16x32_bf16 v[34:37], v[184:187], v[208:211], v[34:37]
	v_mfma_f32_16x16x32_bf16 v[34:37], v[188:191], v[212:215], v[34:37]
	v_mfma_f32_16x16x32_bf16 v[18:21], v[188:191], v[220:223], v[18:21]
	v_mfma_f32_16x16x32_bf16 v[18:21], v[184:187], v[216:219], v[18:21]
	s_barrier
	s_setprio 0
	s_add_i32 s78, 0, 0x18000
	v_add_u32_e32 v166, s78, v153
	s_add_i32 s79, 0, 0x1c000
	ds_read_b128 v[146:149], v166
	ds_read_b128 v[158:161], v166 offset:1024
	ds_read_b128 v[168:171], v166 offset:2048
	ds_read_b128 v[172:175], v166 offset:3072
	v_add_u32_e32 v166, s79, v153
	ds_read_b128 v[176:179], v166
	ds_read_b128 v[180:183], v166 offset:1024
	ds_read_b128 v[184:187], v166 offset:2048
	ds_read_b128 v[188:191], v166 offset:3072
	s_add_u32 s74, s74, 0x80000
	s_addc_u32 s75, s75, 0
	s_mov_b32 m0, s27
	v_lshl_add_u64 v[240:241], s[74:75], 0, v[136:137]
	ds_read_b128 v[200:203], v157 offset:32768
	ds_read_b128 v[204:207], v157 offset:33792
	ds_read_b128 v[208:211], v157 offset:34816
	ds_read_b128 v[212:215], v157 offset:35840
	ds_read_b128 v[216:219], v157 offset:36864
	ds_read_b128 v[220:223], v157 offset:37888
	ds_read_b128 v[224:227], v157 offset:38912
	ds_read_b128 v[228:231], v157 offset:39936
	global_load_lds_dwordx4 v[240:241], off
	v_lshl_add_u64 v[240:241], s[74:75], 0, v[132:133]
	s_mov_b32 m0, s28
	s_nop 0
	global_load_lds_dwordx4 v[240:241], off
	s_waitcnt vmcnt(8)
	s_waitcnt lgkmcnt(0)
	s_setprio 1
	s_barrier
	v_mfma_f32_16x16x32_bf16 v[126:129], v[146:149], v[200:203], v[126:129]
	v_mfma_f32_16x16x32_bf16 v[126:129], v[158:161], v[204:207], v[126:129]
	v_mfma_f32_16x16x32_bf16 v[110:113], v[158:161], v[212:215], v[110:113]
	v_mfma_f32_16x16x32_bf16 v[110:113], v[146:149], v[208:211], v[110:113]
	v_mfma_f32_16x16x32_bf16 v[94:97], v[146:149], v[216:219], v[94:97]
	v_mfma_f32_16x16x32_bf16 v[94:97], v[158:161], v[220:223], v[94:97]
	v_mfma_f32_16x16x32_bf16 v[78:81], v[158:161], v[228:231], v[78:81]
	v_mfma_f32_16x16x32_bf16 v[78:81], v[146:149], v[224:227], v[78:81]
	v_mfma_f32_16x16x32_bf16 v[74:77], v[168:171], v[224:227], v[74:77]
	v_mfma_f32_16x16x32_bf16 v[74:77], v[172:175], v[228:231], v[74:77]
	v_mfma_f32_16x16x32_bf16 v[122:125], v[172:175], v[204:207], v[122:125]
	v_mfma_f32_16x16x32_bf16 v[122:125], v[168:171], v[200:203], v[122:125]
	v_mfma_f32_16x16x32_bf16 v[106:109], v[168:171], v[208:211], v[106:109]
	v_mfma_f32_16x16x32_bf16 v[106:109], v[172:175], v[212:215], v[106:109]
	v_mfma_f32_16x16x32_bf16 v[90:93], v[172:175], v[220:223], v[90:93]
	v_mfma_f32_16x16x32_bf16 v[90:93], v[168:171], v[216:219], v[90:93]
	s_setprio 0
	s_setprio 1
	v_mfma_f32_16x16x32_bf16 v[86:89], v[176:179], v[216:219], v[86:89]
	v_mfma_f32_16x16x32_bf16 v[86:89], v[180:183], v[220:223], v[86:89]
	v_mfma_f32_16x16x32_bf16 v[118:121], v[180:183], v[204:207], v[118:121]
	v_mfma_f32_16x16x32_bf16 v[118:121], v[176:179], v[200:203], v[118:121]
	v_mfma_f32_16x16x32_bf16 v[102:105], v[176:179], v[208:211], v[102:105]
	v_mfma_f32_16x16x32_bf16 v[102:105], v[180:183], v[212:215], v[102:105]
	v_mfma_f32_16x16x32_bf16 v[70:73], v[180:183], v[228:231], v[70:73]
	v_mfma_f32_16x16x32_bf16 v[70:73], v[176:179], v[224:227], v[70:73]
	v_mfma_f32_16x16x32_bf16 v[66:69], v[184:187], v[224:227], v[66:69]
	v_mfma_f32_16x16x32_bf16 v[66:69], v[188:191], v[228:231], v[66:69]
	v_mfma_f32_16x16x32_bf16 v[114:117], v[188:191], v[204:207], v[114:117]
	v_mfma_f32_16x16x32_bf16 v[114:117], v[184:187], v[200:203], v[114:117]
	v_mfma_f32_16x16x32_bf16 v[98:101], v[184:187], v[208:211], v[98:101]
	v_mfma_f32_16x16x32_bf16 v[98:101], v[188:191], v[212:215], v[98:101]
	v_mfma_f32_16x16x32_bf16 v[82:85], v[188:191], v[220:223], v[82:85]
	v_mfma_f32_16x16x32_bf16 v[82:85], v[184:187], v[216:219], v[82:85]
	s_barrier
; #define PG8_STAGE(bufoff, gbase, voff) do { _Pragma("unroll") for (int _i = 0; _i < 2; ++_i) \
;         __builtin_amdgcn_global_load_lds((const unsigned*)((const char*)(gbase) + (voff)[_i]), (PG8_LAS unsigned*)(lds + (bufoff) + ldsw + _i * 8192), 16, 0, 0); } while (0)
; #define PG8_LDA(dst, b, h) do { _Pragma("unroll") for (int m = 0; m < 4; ++m) _Pragma("unroll") for (int k = 0; k < 2; ++k) dst[m][k] = *(const PG8_LAS bf16x8*)(lds + PG8_SA(b, h) + aoff + m * 2048 + k * 1024); } while (0)
; #define PG8_MMA(ai, bj, At, Bt) do { __builtin_amdgcn_s_setprio(1); _Pragma("unroll") for (int m = 0; m < 4; ++m) _Pragma("unroll") for (int n = 0; n < 2; ++n) _Pragma("unroll") for (int k = 0; k < 2; ++k) \
;         acc[ai][bj][m][n] = __builtin_amdgcn_mfma_f32_16x16x32_bf16(Bt[n][k], At[m][k], acc[ai][bj][m][n], 0, 0, 0); __builtin_amdgcn_s_setprio(0); } while (0)
; #define PG8_WAIT_V(n) asm volatile("s_waitcnt vmcnt(" #n ")" ::: "memory")
; #define PG8_WAIT_L(n) asm volatile("s_waitcnt lgkmcnt(" #n ")" ::: "memory")
; #define PG8_BAR __builtin_amdgcn_s_barrier()
; #define PG8_SCHED __builtin_amdgcn_sched_barrier(0)
; template <class Epi, class Sched, bool ALIGN_EPI = false, bool SP2 = false>
; __device__ __forceinline__ void gemm_phase(PG8_LAS unsigned char* lds, const Gemm g, const Sched& S, const Epi& E) {
;     ...
;             PG8_LDA(At, 1, 1); PG8_STAGE(PG8_SB(1, 0), b3, voffB); PG8_STAGE(PG8_SB(1, 1), b3 + hstep, voffB); PG8_STAGE(PG8_SA(1, 0), a3, voffA);
;             PG8_WAIT_V(8); PG8_WAIT_L(0); PG8_BAR; PG8_MMA(1, 0, At, B0); PG8_MMA(1, 1, At, B1); PG8_BAR; PG8_SCHED;
;     ...
;         if constexpr (ALIGN_EPI) { if (wr == 0) PG8_BAR; }
	s_setprio 0
	s_add_i32 s74, s78, s2
	v_lshl_add_u64 v[150:151], v[150:151], 0, s[10:11]
	s_mov_b32 m0, s74
	ds_read_b128 v[200:203], v157 offset:49152
	ds_read_b128 v[204:207], v157 offset:50176
	ds_read_b128 v[208:211], v157 offset:51200
	ds_read_b128 v[212:215], v157 offset:52224
	ds_read_b128 v[216:219], v157 offset:53248
	ds_read_b128 v[220:223], v157 offset:54272
	ds_read_b128 v[224:227], v157 offset:55296
	ds_read_b128 v[228:231], v157 offset:56320
	global_load_lds_dwordx4 v[150:151], off
	s_add_i32 m0, s74, 0x2000
	s_add_u32 s72, s72, 0x80080
	v_lshl_add_u64 v[150:151], v[162:163], 0, s[10:11]
	s_addc_u32 s73, s73, 0
	s_add_i32 s74, s79, s2
	global_load_lds_dwordx4 v[150:151], off
	v_lshl_add_u64 v[150:151], s[72:73], 0, v[134:135]
	s_mov_b32 m0, s74
	s_nop 0
	global_load_lds_dwordx4 v[150:151], off
	v_lshl_add_u64 v[150:151], s[72:73], 0, v[130:131]
	s_add_i32 m0, s74, 0x2000
	s_nop 0
	global_load_lds_dwordx4 v[150:151], off
	v_lshl_add_u64 v[150:151], v[192:193], 0, s[10:11]
	s_mov_b32 m0, s30
	s_nop 0
	global_load_lds_dwordx4 v[150:151], off
	v_lshl_add_u64 v[150:151], v[232:233], 0, s[10:11]
	s_mov_b32 m0, s33
	s_nop 0
	global_load_lds_dwordx4 v[150:151], off
	s_waitcnt vmcnt(8)
	s_waitcnt lgkmcnt(0)
	s_setprio 1
	s_barrier
	v_mfma_f32_16x16x32_bf16 v[62:65], v[146:149], v[200:203], v[62:65]
	v_mfma_f32_16x16x32_bf16 v[62:65], v[158:161], v[204:207], v[62:65]
	v_mfma_f32_16x16x32_bf16 v[46:49], v[158:161], v[212:215], v[46:49]
	v_mfma_f32_16x16x32_bf16 v[46:49], v[146:149], v[208:211], v[46:49]
	v_mfma_f32_16x16x32_bf16 v[30:33], v[146:149], v[216:219], v[30:33]
	v_mfma_f32_16x16x32_bf16 v[30:33], v[158:161], v[220:223], v[30:33]
	v_mfma_f32_16x16x32_bf16 v[14:17], v[158:161], v[228:231], v[14:17]
	v_mfma_f32_16x16x32_bf16 v[14:17], v[146:149], v[224:227], v[14:17]
	v_mfma_f32_16x16x32_bf16 v[10:13], v[168:171], v[224:227], v[10:13]
	v_mfma_f32_16x16x32_bf16 v[10:13], v[172:175], v[228:231], v[10:13]
	v_mfma_f32_16x16x32_bf16 v[58:61], v[172:175], v[204:207], v[58:61]
	v_mfma_f32_16x16x32_bf16 v[58:61], v[168:171], v[200:203], v[58:61]
	v_mfma_f32_16x16x32_bf16 v[42:45], v[168:171], v[208:211], v[42:45]
	v_mfma_f32_16x16x32_bf16 v[42:45], v[172:175], v[212:215], v[42:45]
	v_mfma_f32_16x16x32_bf16 v[26:29], v[172:175], v[220:223], v[26:29]
	v_mfma_f32_16x16x32_bf16 v[26:29], v[168:171], v[216:219], v[26:29]
	s_setprio 0
	s_setprio 1
	v_mfma_f32_16x16x32_bf16 v[22:25], v[176:179], v[216:219], v[22:25]
	v_mfma_f32_16x16x32_bf16 v[22:25], v[180:183], v[220:223], v[22:25]
	v_mfma_f32_16x16x32_bf16 v[54:57], v[180:183], v[204:207], v[54:57]
	v_mfma_f32_16x16x32_bf16 v[54:57], v[176:179], v[200:203], v[54:57]
	v_mfma_f32_16x16x32_bf16 v[38:41], v[176:179], v[208:211], v[38:41]
	v_mfma_f32_16x16x32_bf16 v[38:41], v[180:183], v[212:215], v[38:41]
	v_mfma_f32_16x16x32_bf16 v[6:9], v[180:183], v[228:231], v[6:9]
	v_mfma_f32_16x16x32_bf16 v[6:9], v[176:179], v[224:227], v[6:9]
	v_mfma_f32_16x16x32_bf16 v[2:5], v[184:187], v[224:227], v[2:5]
	v_mfma_f32_16x16x32_bf16 v[2:5], v[188:191], v[228:231], v[2:5]
	v_mfma_f32_16x16x32_bf16 v[50:53], v[188:191], v[204:207], v[50:53]
	v_mfma_f32_16x16x32_bf16 v[50:53], v[184:187], v[200:203], v[50:53]
	v_mfma_f32_16x16x32_bf16 v[34:37], v[184:187], v[208:211], v[34:37]
	v_mfma_f32_16x16x32_bf16 v[34:37], v[188:191], v[212:215], v[34:37]
	v_mfma_f32_16x16x32_bf16 v[18:21], v[188:191], v[220:223], v[18:21]
	v_mfma_f32_16x16x32_bf16 v[18:21], v[184:187], v[216:219], v[18:21]
	s_barrier
	s_setprio 0
	s_add_i32 s77, s77, 2
	s_add_u32 s70, s70, 0x100
	s_addc_u32 s71, s71, 0
	s_add_u32 s69, s69, 0x100
	s_addc_u32 s76, s76, 0
	s_cmp_gt_u32 s77, 29
	s_cbranch_scc0 .LBB0_1062
	s_and_b64 vcc, exec, s[48:49]
	s_cbranch_vccz .LBB0_1065
	s_barrier

; #define PG8_STAGE(bufoff, gbase, voff) do { _Pragma("unroll") for (int _i = 0; _i < 2; ++_i) \
;         __builtin_amdgcn_global_load_lds((const unsigned*)((const char*)(gbase) + (voff)[_i]), (PG8_LAS unsigned*)(lds + (bufoff) + ldsw + _i * 8192), 16, 0, 0); } while (0)
; #define PG8_LDA(dst, b, h) do { _Pragma("unroll") for (int m = 0; m < 4; ++m) _Pragma("unroll") for (int k = 0; k < 2; ++k) dst[m][k] = *(const PG8_LAS bf16x8*)(lds + PG8_SA(b, h) + aoff + m * 2048 + k * 1024); } while (0)
; #define PG8_LDB(dst, b, h) do { _Pragma("unroll") for (int n = 0; n < 2; ++n) _Pragma("unroll") for (int k = 0; k < 2; ++k) dst[n][k] = *(const PG8_LAS bf16x8*)(lds + PG8_SB(b, h) + boff + n * 2048 + k * 1024); } while (0)
; #define PG8_MMA(ai, bj, At, Bt) do { __builtin_amdgcn_s_setprio(1); _Pragma("unroll") for (int m = 0; m < 4; ++m) _Pragma("unroll") for (int n = 0; n < 2; ++n) _Pragma("unroll") for (int k = 0; k < 2; ++k) \
;         acc[ai][bj][m][n] = __builtin_amdgcn_mfma_f32_16x16x32_bf16(Bt[n][k], At[m][k], acc[ai][bj][m][n], 0, 0, 0); __builtin_amdgcn_s_setprio(0); } while (0)
; #define PG8_WAIT_V(n) asm volatile("s_waitcnt vmcnt(" #n ")" ::: "memory")
; #define PG8_WAIT_L(n) asm volatile("s_waitcnt lgkmcnt(" #n ")" ::: "memory")
; #define PG8_BAR __builtin_amdgcn_s_barrier()
; #define PG8_SCHED __builtin_amdgcn_sched_barrier(0)
; template <class Epi, class Sched, bool ALIGN_EPI = false, bool SP2 = false>
; __device__ __forceinline__ void gemm_phase(PG8_LAS unsigned char* lds, const Gemm g, const Sched& S, const Epi& E) {
;     ...
;             const bool last = (t == nt - 2);
;             const char* a1 = cA + (size_t)(t + 1) * kstep;
;             const char* a2 = last ? nA : cA + (size_t)(t + 2) * kstep; const char* b2 = last ? nB : cB + (size_t)(t + 2) * kstep;
;             const char* a3 = a2 + kstep; const char* b3 = b2 + kstep;
;             if (last && has_next) S.a_ready(nxt);
;             if constexpr (SP2) {
;             PG8_LDB(B0, 0, 0); PG8_LDB(B1, 0, 1); PG8_SCHED; PG8_LDA(At, 0, 0); PG8_STAGE(PG8_SA(1, 1), a1 + hstep, voffA);
;             PG8_WAIT_V(8); PG8_WAIT_L(0); PG8_BAR; PG8_MMA(0, 0, At, B0); PG8_MMA(0, 1, At, B1); PG8_BAR; PG8_SCHED;
;             PG8_LDA(At, 0, 1); PG8_STAGE(PG8_SB(0, 0), b2, voffB); PG8_STAGE(PG8_SB(0, 1), b2 + hstep, voffB); PG8_STAGE(PG8_SA(0, 0), a2, voffA);
.LBB0_1078:
	ds_read_b128 v[146:149], v155
	ds_read_b128 v[158:161], v155 offset:1024
	ds_read_b128 v[168:171], v155 offset:2048
	ds_read_b128 v[172:175], v155 offset:3072
	ds_read_b128 v[176:179], v156
	ds_read_b128 v[180:183], v156 offset:1024
	ds_read_b128 v[184:187], v156 offset:2048
	ds_read_b128 v[188:191], v156 offset:3072
	s_add_u32 s68, s66, 0xfff80080
	s_addc_u32 s69, s67, -1
	s_cmp_eq_u32 s73, 28
	s_cselect_b32 s71, s34, s69
	s_cselect_b32 s70, s35, s68
	s_cselect_b32 s69, s57, s72
	s_cselect_b32 s68, s59, s65
	v_lshl_add_u64 v[150:151], s[66:67], 0, v[138:139]
	s_add_i32 m0, s25, 0xc000
	ds_read_b128 v[200:203], v157
	ds_read_b128 v[204:207], v157 offset:1024
	ds_read_b128 v[208:211], v157 offset:2048
	ds_read_b128 v[212:215], v157 offset:3072
	ds_read_b128 v[216:219], v157 offset:4096
	ds_read_b128 v[220:223], v157 offset:5120
	ds_read_b128 v[224:227], v157 offset:6144
	ds_read_b128 v[228:231], v157 offset:7168
	global_load_lds_dwordx4 v[150:151], off
	v_lshl_add_u64 v[150:151], s[66:67], 0, v[140:141]
	s_add_i32 m0, s25, 0xe000
	s_nop 0
	global_load_lds_dwordx4 v[150:151], off
	s_waitcnt vmcnt(8)
	s_waitcnt lgkmcnt(0)
	s_setprio 1
	s_barrier
	v_mfma_f32_16x16x32_bf16 v[126:129], v[146:149], v[200:203], v[126:129]
	v_mfma_f32_16x16x32_bf16 v[126:129], v[158:161], v[204:207], v[126:129]
	v_mfma_f32_16x16x32_bf16 v[110:113], v[158:161], v[212:215], v[110:113]
	v_mfma_f32_16x16x32_bf16 v[110:113], v[146:149], v[208:211], v[110:113]
	v_mfma_f32_16x16x32_bf16 v[94:97], v[146:149], v[216:219], v[94:97]
	v_mfma_f32_16x16x32_bf16 v[94:97], v[158:161], v[220:223], v[94:97]
	v_mfma_f32_16x16x32_bf16 v[78:81], v[158:161], v[228:231], v[78:81]
	v_mfma_f32_16x16x32_bf16 v[78:81], v[146:149], v[224:227], v[78:81]
	v_mfma_f32_16x16x32_bf16 v[74:77], v[168:171], v[224:227], v[74:77]
	v_mfma_f32_16x16x32_bf16 v[74:77], v[172:175], v[228:231], v[74:77]
	v_mfma_f32_16x16x32_bf16 v[122:125], v[172:175], v[204:207], v[122:125]
	v_mfma_f32_16x16x32_bf16 v[122:125], v[168:171], v[200:203], v[122:125]
	v_mfma_f32_16x16x32_bf16 v[106:109], v[168:171], v[208:211], v[106:109]
	v_mfma_f32_16x16x32_bf16 v[106:109], v[172:175], v[212:215], v[106:109]
	v_mfma_f32_16x16x32_bf16 v[90:93], v[172:175], v[220:223], v[90:93]
	v_mfma_f32_16x16x32_bf16 v[90:93], v[168:171], v[216:219], v[90:93]
	s_setprio 0
	s_setprio 1
	v_mfma_f32_16x16x32_bf16 v[86:89], v[176:179], v[216:219], v[86:89]
	v_mfma_f32_16x16x32_bf16 v[86:89], v[180:183], v[220:223], v[86:89]
	v_mfma_f32_16x16x32_bf16 v[118:121], v[180:183], v[204:207], v[118:121]
	v_mfma_f32_16x16x32_bf16 v[118:121], v[176:179], v[200:203], v[118:121]
	v_mfma_f32_16x16x32_bf16 v[102:105], v[176:179], v[208:211], v[102:105]
	v_mfma_f32_16x16x32_bf16 v[102:105], v[180:183], v[212:215], v[102:105]
	v_mfma_f32_16x16x32_bf16 v[70:73], v[180:183], v[228:231], v[70:73]
	v_mfma_f32_16x16x32_bf16 v[70:73], v[176:179], v[224:227], v[70:73]
	v_mfma_f32_16x16x32_bf16 v[66:69], v[184:187], v[224:227], v[66:69]
	v_mfma_f32_16x16x32_bf16 v[66:69], v[188:191], v[228:231], v[66:69]
	v_mfma_f32_16x16x32_bf16 v[114:117], v[188:191], v[204:207], v[114:117]
	v_mfma_f32_16x16x32_bf16 v[114:117], v[184:187], v[200:203], v[114:117]
	v_mfma_f32_16x16x32_bf16 v[98:101], v[184:187], v[208:211], v[98:101]
	v_mfma_f32_16x16x32_bf16 v[98:101], v[188:191], v[212:215], v[98:101]
	v_mfma_f32_16x16x32_bf16 v[82:85], v[188:191], v[220:223], v[82:85]
	v_mfma_f32_16x16x32_bf16 v[82:85], v[184:187], v[216:219], v[82:85]
	s_barrier
	s_setprio 0
	s_add_i32 s74, s31, s2
	v_lshl_add_u64 v[150:151], s[68:69], 0, v[134:135]
	s_mov_b32 m0, s74
	ds_read_b128 v[200:203], v157 offset:16384
	ds_read_b128 v[204:207], v157 offset:17408
	ds_read_b128 v[208:211], v157 offset:18432
	ds_read_b128 v[212:215], v157 offset:19456
	ds_read_b128 v[216:219], v157 offset:20480
	ds_read_b128 v[220:223], v157 offset:21504
	ds_read_b128 v[224:227], v157 offset:22528
	ds_read_b128 v[228:231], v157 offset:23552
	global_load_lds_dwordx4 v[150:151], off
	s_add_i32 m0, s74, 0x2000
	s_add_u32 s74, s68, 0x80000
	v_lshl_add_u64 v[162:163], s[68:69], 0, v[130:131]
	s_addc_u32 s75, s69, 0
	s_add_i32 s76, s40, s2
	global_load_lds_dwordx4 v[162:163], off
	v_lshl_add_u64 v[192:193], s[74:75], 0, v[134:135]
	s_mov_b32 m0, s76
	v_lshl_add_u64 v[232:233], s[70:71], 0, v[132:133]
	global_load_lds_dwordx4 v[192:193], off
	v_lshl_add_u64 v[192:193], s[74:75], 0, v[130:131]
	s_add_i32 m0, s76, 0x2000
	s_nop 0
	global_load_lds_dwordx4 v[192:193], off
	v_lshl_add_u64 v[192:193], s[70:71], 0, v[136:137]
	s_mov_b32 m0, s25
	s_nop 0
	global_load_lds_dwordx4 v[192:193], off
	s_mov_b32 m0, s26
	s_nop 0
	global_load_lds_dwordx4 v[232:233], off
	s_waitcnt vmcnt(8)
	s_waitcnt lgkmcnt(0)
	s_setprio 1
	s_barrier
; #define PG8_STAGE(bufoff, gbase, voff) do { _Pragma("unroll") for (int _i = 0; _i < 2; ++_i) \
;         __builtin_amdgcn_global_load_lds((const unsigned*)((const char*)(gbase) + (voff)[_i]), (PG8_LAS unsigned*)(lds + (bufoff) + ldsw + _i * 8192), 16, 0, 0); } while (0)
; #define PG8_LDA(dst, b, h) do { _Pragma("unroll") for (int m = 0; m < 4; ++m) _Pragma("unroll") for (int k = 0; k < 2; ++k) dst[m][k] = *(const PG8_LAS bf16x8*)(lds + PG8_SA(b, h) + aoff + m * 2048 + k * 1024); } while (0)
; #define PG8_LDB(dst, b, h) do { _Pragma("unroll") for (int n = 0; n < 2; ++n) _Pragma("unroll") for (int k = 0; k < 2; ++k) dst[n][k] = *(const PG8_LAS bf16x8*)(lds + PG8_SB(b, h) + boff + n * 2048 + k * 1024); } while (0)
; #define PG8_MMA(ai, bj, At, Bt) do { __builtin_amdgcn_s_setprio(1); _Pragma("unroll") for (int m = 0; m < 4; ++m) _Pragma("unroll") for (int n = 0; n < 2; ++n) _Pragma("unroll") for (int k = 0; k < 2; ++k) \
;         acc[ai][bj][m][n] = __builtin_amdgcn_mfma_f32_16x16x32_bf16(Bt[n][k], At[m][k], acc[ai][bj][m][n], 0, 0, 0); __builtin_amdgcn_s_setprio(0); } while (0)
; #define PG8_WAIT_V(n) asm volatile("s_waitcnt vmcnt(" #n ")" ::: "memory")
; #define PG8_WAIT_L(n) asm volatile("s_waitcnt lgkmcnt(" #n ")" ::: "memory")
; #define PG8_BAR __builtin_amdgcn_s_barrier()
; #define PG8_SCHED __builtin_amdgcn_sched_barrier(0)
; template <class Epi, class Sched, bool ALIGN_EPI = false, bool SP2 = false>
; __device__ __forceinline__ void gemm_phase(PG8_LAS unsigned char* lds, const Gemm g, const Sched& S, const Epi& E) {
;     ...
;             PG8_WAIT_V(8); PG8_WAIT_L(0); PG8_BAR; PG8_MMA(1, 0, At, B0); PG8_MMA(1, 1, At, B1); PG8_BAR; PG8_SCHED;
;             PG8_LDB(B0, 1, 0); PG8_LDB(B1, 1, 1); PG8_SCHED; PG8_LDA(At, 1, 0); PG8_STAGE(PG8_SA(0, 1), a2 + hstep, voffA);
;             PG8_WAIT_V(8); PG8_WAIT_L(0); PG8_BAR; PG8_MMA(0, 0, At, B0); PG8_MMA(0, 1, At, B1); PG8_BAR; PG8_SCHED;
	v_mfma_f32_16x16x32_bf16 v[62:65], v[146:149], v[200:203], v[62:65]
	v_mfma_f32_16x16x32_bf16 v[62:65], v[158:161], v[204:207], v[62:65]
	v_mfma_f32_16x16x32_bf16 v[46:49], v[158:161], v[212:215], v[46:49]
	v_mfma_f32_16x16x32_bf16 v[46:49], v[146:149], v[208:211], v[46:49]
	v_mfma_f32_16x16x32_bf16 v[30:33], v[146:149], v[216:219], v[30:33]
	v_mfma_f32_16x16x32_bf16 v[30:33], v[158:161], v[220:223], v[30:33]
	v_mfma_f32_16x16x32_bf16 v[14:17], v[158:161], v[228:231], v[14:17]
	v_mfma_f32_16x16x32_bf16 v[14:17], v[146:149], v[224:227], v[14:17]
	v_mfma_f32_16x16x32_bf16 v[10:13], v[168:171], v[224:227], v[10:13]
	v_mfma_f32_16x16x32_bf16 v[10:13], v[172:175], v[228:231], v[10:13]
	v_mfma_f32_16x16x32_bf16 v[58:61], v[172:175], v[204:207], v[58:61]
	v_mfma_f32_16x16x32_bf16 v[58:61], v[168:171], v[200:203], v[58:61]
	v_mfma_f32_16x16x32_bf16 v[42:45], v[168:171], v[208:211], v[42:45]
	v_mfma_f32_16x16x32_bf16 v[42:45], v[172:175], v[212:215], v[42:45]
	v_mfma_f32_16x16x32_bf16 v[26:29], v[172:175], v[220:223], v[26:29]
	v_mfma_f32_16x16x32_bf16 v[26:29], v[168:171], v[216:219], v[26:29]
	s_setprio 0
	s_setprio 1
	v_mfma_f32_16x16x32_bf16 v[22:25], v[176:179], v[216:219], v[22:25]
	v_mfma_f32_16x16x32_bf16 v[22:25], v[180:183], v[220:223], v[22:25]
	v_mfma_f32_16x16x32_bf16 v[54:57], v[180:183], v[204:207], v[54:57]
	v_mfma_f32_16x16x32_bf16 v[54:57], v[176:179], v[200:203], v[54:57]
	v_mfma_f32_16x16x32_bf16 v[38:41], v[176:179], v[208:211], v[38:41]
	v_mfma_f32_16x16x32_bf16 v[38:41], v[180:183], v[212:215], v[38:41]
	v_mfma_f32_16x16x32_bf16 v[6:9], v[180:183], v[228:231], v[6:9]
	v_mfma_f32_16x16x32_bf16 v[6:9], v[176:179], v[224:227], v[6:9]
	v_mfma_f32_16x16x32_bf16 v[2:5], v[184:187], v[224:227], v[2:5]
	v_mfma_f32_16x16x32_bf16 v[2:5], v[188:191], v[228:231], v[2:5]
	v_mfma_f32_16x16x32_bf16 v[50:53], v[188:191], v[204:207], v[50:53]
	v_mfma_f32_16x16x32_bf16 v[50:53], v[184:187], v[200:203], v[50:53]
	v_mfma_f32_16x16x32_bf16 v[34:37], v[184:187], v[208:211], v[34:37]
	v_mfma_f32_16x16x32_bf16 v[34:37], v[188:191], v[212:215], v[34:37]
	v_mfma_f32_16x16x32_bf16 v[18:21], v[188:191], v[220:223], v[18:21]
	v_mfma_f32_16x16x32_bf16 v[18:21], v[184:187], v[216:219], v[18:21]
	s_barrier
	s_setprio 0
	s_add_i32 s74, 0, 0x18000
	v_add_u32_e32 v166, s74, v153
	s_add_i32 s75, 0, 0x1c000
	ds_read_b128 v[146:149], v166
	ds_read_b128 v[158:161], v166 offset:1024
	ds_read_b128 v[168:171], v166 offset:2048
	ds_read_b128 v[172:175], v166 offset:3072
	v_add_u32_e32 v166, s75, v153
	ds_read_b128 v[176:179], v166
	ds_read_b128 v[180:183], v166 offset:1024
	ds_read_b128 v[184:187], v166 offset:2048
	ds_read_b128 v[188:191], v166 offset:3072
	s_add_u32 s70, s70, 0x80000
	s_addc_u32 s71, s71, 0
	s_mov_b32 m0, s27
	v_lshl_add_u64 v[240:241], s[70:71], 0, v[136:137]
	ds_read_b128 v[200:203], v157 offset:32768
	ds_read_b128 v[204:207], v157 offset:33792
	ds_read_b128 v[208:211], v157 offset:34816
	ds_read_b128 v[212:215], v157 offset:35840
	ds_read_b128 v[216:219], v157 offset:36864
	ds_read_b128 v[220:223], v157 offset:37888
	ds_read_b128 v[224:227], v157 offset:38912
	ds_read_b128 v[228:231], v157 offset:39936
	global_load_lds_dwordx4 v[240:241], off
	v_lshl_add_u64 v[240:241], s[70:71], 0, v[132:133]
	s_mov_b32 m0, s28
	s_nop 0
	global_load_lds_dwordx4 v[240:241], off
	s_waitcnt vmcnt(8)
	s_waitcnt lgkmcnt(0)
	s_setprio 1
	s_barrier
	v_mfma_f32_16x16x32_bf16 v[126:129], v[146:149], v[200:203], v[126:129]
	v_mfma_f32_16x16x32_bf16 v[126:129], v[158:161], v[204:207], v[126:129]
	v_mfma_f32_16x16x32_bf16 v[110:113], v[158:161], v[212:215], v[110:113]
	v_mfma_f32_16x16x32_bf16 v[110:113], v[146:149], v[208:211], v[110:113]
	v_mfma_f32_16x16x32_bf16 v[94:97], v[146:149], v[216:219], v[94:97]
	v_mfma_f32_16x16x32_bf16 v[94:97], v[158:161], v[220:223], v[94:97]
	v_mfma_f32_16x16x32_bf16 v[78:81], v[158:161], v[228:231], v[78:81]
	v_mfma_f32_16x16x32_bf16 v[78:81], v[146:149], v[224:227], v[78:81]
	v_mfma_f32_16x16x32_bf16 v[74:77], v[168:171], v[224:227], v[74:77]
	v_mfma_f32_16x16x32_bf16 v[74:77], v[172:175], v[228:231], v[74:77]
	v_mfma_f32_16x16x32_bf16 v[122:125], v[172:175], v[204:207], v[122:125]
	v_mfma_f32_16x16x32_bf16 v[122:125], v[168:171], v[200:203], v[122:125]
	v_mfma_f32_16x16x32_bf16 v[106:109], v[168:171], v[208:211], v[106:109]
	v_mfma_f32_16x16x32_bf16 v[106:109], v[172:175], v[212:215], v[106:109]
	v_mfma_f32_16x16x32_bf16 v[90:93], v[172:175], v[220:223], v[90:93]
	v_mfma_f32_16x16x32_bf16 v[90:93], v[168:171], v[216:219], v[90:93]
	s_setprio 0
	s_setprio 1
	v_mfma_f32_16x16x32_bf16 v[86:89], v[176:179], v[216:219], v[86:89]
	v_mfma_f32_16x16x32_bf16 v[86:89], v[180:183], v[220:223], v[86:89]
	v_mfma_f32_16x16x32_bf16 v[118:121], v[180:183], v[204:207], v[118:121]
	v_mfma_f32_16x16x32_bf16 v[118:121], v[176:179], v[200:203], v[118:121]
	v_mfma_f32_16x16x32_bf16 v[102:105], v[176:179], v[208:211], v[102:105]
	v_mfma_f32_16x16x32_bf16 v[102:105], v[180:183], v[212:215], v[102:105]
	v_mfma_f32_16x16x32_bf16 v[70:73], v[180:183], v[228:231], v[70:73]
	v_mfma_f32_16x16x32_bf16 v[70:73], v[176:179], v[224:227], v[70:73]
	v_mfma_f32_16x16x32_bf16 v[66:69], v[184:187], v[224:227], v[66:69]
	v_mfma_f32_16x16x32_bf16 v[66:69], v[188:191], v[228:231], v[66:69]
	v_mfma_f32_16x16x32_bf16 v[114:117], v[188:191], v[204:207], v[114:117]
	v_mfma_f32_16x16x32_bf16 v[114:117], v[184:187], v[200:203], v[114:117]
	v_mfma_f32_16x16x32_bf16 v[98:101], v[184:187], v[208:211], v[98:101]
	v_mfma_f32_16x16x32_bf16 v[98:101], v[188:191], v[212:215], v[98:101]
	v_mfma_f32_16x16x32_bf16 v[82:85], v[188:191], v[220:223], v[82:85]
	v_mfma_f32_16x16x32_bf16 v[82:85], v[184:187], v[216:219], v[82:85]
	s_barrier
; #define PG8_STAGE(bufoff, gbase, voff) do { _Pragma("unroll") for (int _i = 0; _i < 2; ++_i) \
;         __builtin_amdgcn_global_load_lds((const unsigned*)((const char*)(gbase) + (voff)[_i]), (PG8_LAS unsigned*)(lds + (bufoff) + ldsw + _i * 8192), 16, 0, 0); } while (0)
; #define PG8_LDA(dst, b, h) do { _Pragma("unroll") for (int m = 0; m < 4; ++m) _Pragma("unroll") for (int k = 0; k < 2; ++k) dst[m][k] = *(const PG8_LAS bf16x8*)(lds + PG8_SA(b, h) + aoff + m * 2048 + k * 1024); } while (0)
; #define PG8_MMA(ai, bj, At, Bt) do { __builtin_amdgcn_s_setprio(1); _Pragma("unroll") for (int m = 0; m < 4; ++m) _Pragma("unroll") for (int n = 0; n < 2; ++n) _Pragma("unroll") for (int k = 0; k < 2; ++k) \
;         acc[ai][bj][m][n] = __builtin_amdgcn_mfma_f32_16x16x32_bf16(Bt[n][k], At[m][k], acc[ai][bj][m][n], 0, 0, 0); __builtin_amdgcn_s_setprio(0); } while (0)
; #define PG8_WAIT_V(n) asm volatile("s_waitcnt vmcnt(" #n ")" ::: "memory")
; #define PG8_WAIT_L(n) asm volatile("s_waitcnt lgkmcnt(" #n ")" ::: "memory")
; #define PG8_BAR __builtin_amdgcn_s_barrier()
; #define PG8_SCHED __builtin_amdgcn_sched_barrier(0)
; template <class Epi, class Sched, bool ALIGN_EPI = false, bool SP2 = false>
; __device__ __forceinline__ void gemm_phase(PG8_LAS unsigned char* lds, const Gemm g, const Sched& S, const Epi& E) {
;     ...
;             PG8_LDA(At, 1, 1); PG8_STAGE(PG8_SB(1, 0), b3, voffB); PG8_STAGE(PG8_SB(1, 1), b3 + hstep, voffB); PG8_STAGE(PG8_SA(1, 0), a3, voffA);
;             PG8_WAIT_V(8); PG8_WAIT_L(0); PG8_BAR; PG8_MMA(1, 0, At, B0); PG8_MMA(1, 1, At, B1); PG8_BAR; PG8_SCHED;
;     ...
;         if constexpr (ALIGN_EPI) { if (wr == 0) PG8_BAR; }
	s_setprio 0
	s_add_i32 s70, s74, s2
	v_lshl_add_u64 v[150:151], v[150:151], 0, s[8:9]
	s_mov_b32 m0, s70
	ds_read_b128 v[200:203], v157 offset:49152
	ds_read_b128 v[204:207], v157 offset:50176
	ds_read_b128 v[208:211], v157 offset:51200
	ds_read_b128 v[212:215], v157 offset:52224
	ds_read_b128 v[216:219], v157 offset:53248
	ds_read_b128 v[220:223], v157 offset:54272
	ds_read_b128 v[224:227], v157 offset:55296
	ds_read_b128 v[228:231], v157 offset:56320
	global_load_lds_dwordx4 v[150:151], off
	s_add_i32 m0, s70, 0x2000
	s_add_u32 s68, s68, 0x80080
	v_lshl_add_u64 v[150:151], v[162:163], 0, s[8:9]
	s_addc_u32 s69, s69, 0
	s_add_i32 s70, s75, s2
	global_load_lds_dwordx4 v[150:151], off
	v_lshl_add_u64 v[150:151], s[68:69], 0, v[134:135]
	s_mov_b32 m0, s70
	s_nop 0
	global_load_lds_dwordx4 v[150:151], off
	v_lshl_add_u64 v[150:151], s[68:69], 0, v[130:131]
	s_add_i32 m0, s70, 0x2000
	s_nop 0
	global_load_lds_dwordx4 v[150:151], off
	v_lshl_add_u64 v[150:151], v[192:193], 0, s[8:9]
	s_mov_b32 m0, s30
	s_nop 0
	global_load_lds_dwordx4 v[150:151], off
	v_lshl_add_u64 v[150:151], v[232:233], 0, s[8:9]
	s_mov_b32 m0, s33
	s_nop 0
	global_load_lds_dwordx4 v[150:151], off
	s_waitcnt vmcnt(8)
	s_waitcnt lgkmcnt(0)
	s_setprio 1
	s_barrier
	v_mfma_f32_16x16x32_bf16 v[62:65], v[146:149], v[200:203], v[62:65]
	v_mfma_f32_16x16x32_bf16 v[62:65], v[158:161], v[204:207], v[62:65]
	v_mfma_f32_16x16x32_bf16 v[46:49], v[158:161], v[212:215], v[46:49]
	v_mfma_f32_16x16x32_bf16 v[46:49], v[146:149], v[208:211], v[46:49]
	v_mfma_f32_16x16x32_bf16 v[30:33], v[146:149], v[216:219], v[30:33]
	v_mfma_f32_16x16x32_bf16 v[30:33], v[158:161], v[220:223], v[30:33]
	v_mfma_f32_16x16x32_bf16 v[14:17], v[158:161], v[228:231], v[14:17]
	v_mfma_f32_16x16x32_bf16 v[14:17], v[146:149], v[224:227], v[14:17]
	v_mfma_f32_16x16x32_bf16 v[10:13], v[168:171], v[224:227], v[10:13]
	v_mfma_f32_16x16x32_bf16 v[10:13], v[172:175], v[228:231], v[10:13]
	v_mfma_f32_16x16x32_bf16 v[58:61], v[172:175], v[204:207], v[58:61]
	v_mfma_f32_16x16x32_bf16 v[58:61], v[168:171], v[200:203], v[58:61]
	v_mfma_f32_16x16x32_bf16 v[42:45], v[168:171], v[208:211], v[42:45]
	v_mfma_f32_16x16x32_bf16 v[42:45], v[172:175], v[212:215], v[42:45]
	v_mfma_f32_16x16x32_bf16 v[26:29], v[172:175], v[220:223], v[26:29]
	v_mfma_f32_16x16x32_bf16 v[26:29], v[168:171], v[216:219], v[26:29]
	s_setprio 0
	s_setprio 1
	v_mfma_f32_16x16x32_bf16 v[22:25], v[176:179], v[216:219], v[22:25]
	v_mfma_f32_16x16x32_bf16 v[22:25], v[180:183], v[220:223], v[22:25]
	v_mfma_f32_16x16x32_bf16 v[54:57], v[180:183], v[204:207], v[54:57]
	v_mfma_f32_16x16x32_bf16 v[54:57], v[176:179], v[200:203], v[54:57]
	v_mfma_f32_16x16x32_bf16 v[38:41], v[176:179], v[208:211], v[38:41]
	v_mfma_f32_16x16x32_bf16 v[38:41], v[180:183], v[212:215], v[38:41]
	v_mfma_f32_16x16x32_bf16 v[6:9], v[180:183], v[228:231], v[6:9]
	v_mfma_f32_16x16x32_bf16 v[6:9], v[176:179], v[224:227], v[6:9]
	v_mfma_f32_16x16x32_bf16 v[2:5], v[184:187], v[224:227], v[2:5]
	v_mfma_f32_16x16x32_bf16 v[2:5], v[188:191], v[228:231], v[2:5]
	v_mfma_f32_16x16x32_bf16 v[50:53], v[188:191], v[204:207], v[50:53]
	v_mfma_f32_16x16x32_bf16 v[50:53], v[184:187], v[200:203], v[50:53]
	v_mfma_f32_16x16x32_bf16 v[34:37], v[184:187], v[208:211], v[34:37]
	v_mfma_f32_16x16x32_bf16 v[34:37], v[188:191], v[212:215], v[34:37]
	v_mfma_f32_16x16x32_bf16 v[18:21], v[188:191], v[220:223], v[18:21]
	v_mfma_f32_16x16x32_bf16 v[18:21], v[184:187], v[216:219], v[18:21]
	s_barrier
	s_setprio 0
	s_add_i32 s73, s73, 2
	s_add_u32 s66, s66, 0x100
	s_addc_u32 s67, s67, 0
	s_add_u32 s65, s65, 0x100
	s_addc_u32 s72, s72, 0
	s_cmp_gt_u32 s73, 29
	s_cbranch_scc0 .LBB0_1078
	s_and_b64 vcc, exec, s[10:11]
	s_cbranch_vccz .LBB0_1081
	s_barrier

; #define PG8_STAGE(bufoff, gbase, voff) do { _Pragma("unroll") for (int _i = 0; _i < 2; ++_i) \
;         __builtin_amdgcn_global_load_lds((const unsigned*)((const char*)(gbase) + (voff)[_i]), (PG8_LAS unsigned*)(lds + (bufoff) + ldsw + _i * 8192), 16, 0, 0); } while (0)
; #define PG8_LDA(dst, b, h) do { _Pragma("unroll") for (int m = 0; m < 4; ++m) _Pragma("unroll") for (int k = 0; k < 2; ++k) dst[m][k] = *(const PG8_LAS bf16x8*)(lds + PG8_SA(b, h) + aoff + m * 2048 + k * 1024); } while (0)
; #define PG8_LDB(dst, b, h) do { _Pragma("unroll") for (int n = 0; n < 2; ++n) _Pragma("unroll") for (int k = 0; k < 2; ++k) dst[n][k] = *(const PG8_LAS bf16x8*)(lds + PG8_SB(b, h) + boff + n * 2048 + k * 1024); } while (0)
; #define PG8_MMA(ai, bj, At, Bt) do { __builtin_amdgcn_s_setprio(1); _Pragma("unroll") for (int m = 0; m < 4; ++m) _Pragma("unroll") for (int n = 0; n < 2; ++n) _Pragma("unroll") for (int k = 0; k < 2; ++k) \
;         acc[ai][bj][m][n] = __builtin_amdgcn_mfma_f32_16x16x32_bf16(Bt[n][k], At[m][k], acc[ai][bj][m][n], 0, 0, 0); __builtin_amdgcn_s_setprio(0); } while (0)
; #define PG8_WAIT_V(n) asm volatile("s_waitcnt vmcnt(" #n ")" ::: "memory")
; #define PG8_WAIT_L(n) asm volatile("s_waitcnt lgkmcnt(" #n ")" ::: "memory")
; #define PG8_BAR __builtin_amdgcn_s_barrier()
; #define PG8_SCHED __builtin_amdgcn_sched_barrier(0)
; template <class Epi, class Sched, bool ALIGN_EPI = false, bool SP2 = false>
; __device__ __forceinline__ void gemm_phase(PG8_LAS unsigned char* lds, const Gemm g, const Sched& S, const Epi& E) {
;     ...
;             const bool last = (t == nt - 2);
;             const char* a1 = cA + (size_t)(t + 1) * kstep;
;             const char* a2 = last ? nA : cA + (size_t)(t + 2) * kstep; const char* b2 = last ? nB : cB + (size_t)(t + 2) * kstep;
;             const char* a3 = a2 + kstep; const char* b3 = b2 + kstep;
;             if (last && has_next) S.a_ready(nxt);
;             if constexpr (SP2) {
;             PG8_LDB(B0, 0, 0); PG8_LDB(B1, 0, 1); PG8_SCHED; PG8_LDA(At, 0, 0); PG8_STAGE(PG8_SA(1, 1), a1 + hstep, voffA);
;             PG8_WAIT_V(8); PG8_WAIT_L(0); PG8_BAR; PG8_MMA(0, 0, At, B0); PG8_MMA(0, 1, At, B1); PG8_BAR; PG8_SCHED;
;             PG8_LDA(At, 0, 1); PG8_STAGE(PG8_SB(0, 0), b2, voffB); PG8_STAGE(PG8_SB(0, 1), b2 + hstep, voffB); PG8_STAGE(PG8_SA(0, 0), a2, voffA);
.LBB0_1203:
	ds_read_b128 v[146:149], v171
	ds_read_b128 v[176:179], v171 offset:1024
	ds_read_b128 v[180:183], v171 offset:2048
	ds_read_b128 v[184:187], v171 offset:3072
	ds_read_b128 v[188:191], v172
	ds_read_b128 v[200:203], v172 offset:1024
	ds_read_b128 v[204:207], v172 offset:2048
	ds_read_b128 v[208:211], v172 offset:3072
	s_add_u32 s63, s64, 0xfff00080
	s_addc_u32 s66, s65, -1
	s_cmp_eq_u32 s61, 60
	s_cselect_b32 s69, s34, s66
	s_cselect_b32 s68, s35, s63
	s_cselect_b32 s67, s40, s55
	s_cselect_b32 s66, s41, s53
	v_lshl_add_u64 v[150:151], s[64:65], 0, v[138:139]
	s_add_i32 m0, s4, 0xc000
	ds_read_b128 v[212:215], v173
	ds_read_b128 v[216:219], v173 offset:1024
	ds_read_b128 v[220:223], v173 offset:2048
	ds_read_b128 v[224:227], v173 offset:3072
	ds_read_b128 v[228:231], v173 offset:4096
	ds_read_b128 v[240:243], v173 offset:5120
	ds_read_b128 v[244:247], v173 offset:6144
	ds_read_b128 v[248:251], v173 offset:7168
	global_load_lds_dwordx4 v[150:151], off
	v_lshl_add_u64 v[150:151], s[64:65], 0, v[140:141]
	s_add_i32 m0, s4, 0xe000
	s_nop 0
	global_load_lds_dwordx4 v[150:151], off
	s_waitcnt vmcnt(8)
	s_waitcnt lgkmcnt(0)
	s_setprio 1
	s_barrier
	v_mfma_f32_16x16x32_bf16 v[126:129], v[146:149], v[212:215], v[126:129]
	v_mfma_f32_16x16x32_bf16 v[126:129], v[176:179], v[216:219], v[126:129]
	v_mfma_f32_16x16x32_bf16 v[110:113], v[176:179], v[224:227], v[110:113]
	v_mfma_f32_16x16x32_bf16 v[110:113], v[146:149], v[220:223], v[110:113]
	v_mfma_f32_16x16x32_bf16 v[94:97], v[146:149], v[228:231], v[94:97]
	v_mfma_f32_16x16x32_bf16 v[94:97], v[176:179], v[240:243], v[94:97]
	v_mfma_f32_16x16x32_bf16 v[78:81], v[176:179], v[248:251], v[78:81]
	v_mfma_f32_16x16x32_bf16 v[78:81], v[146:149], v[244:247], v[78:81]
	v_mfma_f32_16x16x32_bf16 v[74:77], v[180:183], v[244:247], v[74:77]
	v_mfma_f32_16x16x32_bf16 v[74:77], v[184:187], v[248:251], v[74:77]
	v_mfma_f32_16x16x32_bf16 v[122:125], v[184:187], v[216:219], v[122:125]
	v_mfma_f32_16x16x32_bf16 v[122:125], v[180:183], v[212:215], v[122:125]
	v_mfma_f32_16x16x32_bf16 v[106:109], v[180:183], v[220:223], v[106:109]
	v_mfma_f32_16x16x32_bf16 v[106:109], v[184:187], v[224:227], v[106:109]
	v_mfma_f32_16x16x32_bf16 v[90:93], v[184:187], v[240:243], v[90:93]
	v_mfma_f32_16x16x32_bf16 v[90:93], v[180:183], v[228:231], v[90:93]
	s_setprio 0
	s_setprio 1
	v_mfma_f32_16x16x32_bf16 v[86:89], v[188:191], v[228:231], v[86:89]
	v_mfma_f32_16x16x32_bf16 v[86:89], v[200:203], v[240:243], v[86:89]
	v_mfma_f32_16x16x32_bf16 v[118:121], v[200:203], v[216:219], v[118:121]
	v_mfma_f32_16x16x32_bf16 v[118:121], v[188:191], v[212:215], v[118:121]
	v_mfma_f32_16x16x32_bf16 v[102:105], v[188:191], v[220:223], v[102:105]
	v_mfma_f32_16x16x32_bf16 v[102:105], v[200:203], v[224:227], v[102:105]
	v_mfma_f32_16x16x32_bf16 v[70:73], v[200:203], v[248:251], v[70:73]
	v_mfma_f32_16x16x32_bf16 v[70:73], v[188:191], v[244:247], v[70:73]
	v_mfma_f32_16x16x32_bf16 v[66:69], v[204:207], v[244:247], v[66:69]
	v_mfma_f32_16x16x32_bf16 v[66:69], v[208:211], v[248:251], v[66:69]
	v_mfma_f32_16x16x32_bf16 v[114:117], v[208:211], v[216:219], v[114:117]
	v_mfma_f32_16x16x32_bf16 v[114:117], v[204:207], v[212:215], v[114:117]
	v_mfma_f32_16x16x32_bf16 v[98:101], v[204:207], v[220:223], v[98:101]
	v_mfma_f32_16x16x32_bf16 v[98:101], v[208:211], v[224:227], v[98:101]
	v_mfma_f32_16x16x32_bf16 v[82:85], v[208:211], v[240:243], v[82:85]
	v_mfma_f32_16x16x32_bf16 v[82:85], v[204:207], v[228:231], v[82:85]
	s_barrier
	s_setprio 0
	s_add_i32 s63, s31, s2
	v_lshl_add_u64 v[150:151], s[66:67], 0, v[132:133]
	s_mov_b32 m0, s63
	ds_read_b128 v[212:215], v173 offset:16384
	ds_read_b128 v[216:219], v173 offset:17408
	ds_read_b128 v[220:223], v173 offset:18432
	ds_read_b128 v[224:227], v173 offset:19456
	ds_read_b128 v[228:231], v173 offset:20480
	ds_read_b128 v[240:243], v173 offset:21504
	ds_read_b128 v[244:247], v173 offset:22528
	ds_read_b128 v[248:251], v173 offset:23552
	global_load_lds_dwordx4 v[150:151], off
	s_add_i32 m0, s63, 0x2000
	s_add_u32 s70, s66, 0x100000
	v_lshl_add_u64 v[192:193], s[66:67], 0, v[136:137]
	s_addc_u32 s71, s67, 0
	s_add_i32 s63, s39, s2
	global_load_lds_dwordx4 v[192:193], off
	v_lshl_add_u64 v[232:233], s[70:71], 0, v[132:133]
	s_mov_b32 m0, s63
	v_lshl_add_u64 v[252:253], s[68:69], 0, v[134:135]
	global_load_lds_dwordx4 v[232:233], off
	v_lshl_add_u64 v[232:233], s[70:71], 0, v[136:137]
	s_add_i32 m0, s63, 0x2000
	s_nop 0
	global_load_lds_dwordx4 v[232:233], off
	v_lshl_add_u64 v[232:233], s[68:69], 0, v[130:131]
	s_mov_b32 m0, s4
	s_nop 0
	global_load_lds_dwordx4 v[232:233], off
	s_mov_b32 m0, s5
	s_nop 0
	global_load_lds_dwordx4 v[252:253], off
	s_waitcnt vmcnt(8)
	s_waitcnt lgkmcnt(0)
	s_setprio 1
	s_barrier
; #define PG8_STAGE(bufoff, gbase, voff) do { _Pragma("unroll") for (int _i = 0; _i < 2; ++_i) \
;         __builtin_amdgcn_global_load_lds((const unsigned*)((const char*)(gbase) + (voff)[_i]), (PG8_LAS unsigned*)(lds + (bufoff) + ldsw + _i * 8192), 16, 0, 0); } while (0)
; #define PG8_LDA(dst, b, h) do { _Pragma("unroll") for (int m = 0; m < 4; ++m) _Pragma("unroll") for (int k = 0; k < 2; ++k) dst[m][k] = *(const PG8_LAS bf16x8*)(lds + PG8_SA(b, h) + aoff + m * 2048 + k * 1024); } while (0)
; #define PG8_LDB(dst, b, h) do { _Pragma("unroll") for (int n = 0; n < 2; ++n) _Pragma("unroll") for (int k = 0; k < 2; ++k) dst[n][k] = *(const PG8_LAS bf16x8*)(lds + PG8_SB(b, h) + boff + n * 2048 + k * 1024); } while (0)
; #define PG8_MMA(ai, bj, At, Bt) do { __builtin_amdgcn_s_setprio(1); _Pragma("unroll") for (int m = 0; m < 4; ++m) _Pragma("unroll") for (int n = 0; n < 2; ++n) _Pragma("unroll") for (int k = 0; k < 2; ++k) \
;         acc[ai][bj][m][n] = __builtin_amdgcn_mfma_f32_16x16x32_bf16(Bt[n][k], At[m][k], acc[ai][bj][m][n], 0, 0, 0); __builtin_amdgcn_s_setprio(0); } while (0)
; #define PG8_WAIT_V(n) asm volatile("s_waitcnt vmcnt(" #n ")" ::: "memory")
; #define PG8_WAIT_L(n) asm volatile("s_waitcnt lgkmcnt(" #n ")" ::: "memory")
; #define PG8_BAR __builtin_amdgcn_s_barrier()
; #define PG8_SCHED __builtin_amdgcn_sched_barrier(0)
; template <class Epi, class Sched, bool ALIGN_EPI = false, bool SP2 = false>
; __device__ __forceinline__ void gemm_phase(PG8_LAS unsigned char* lds, const Gemm g, const Sched& S, const Epi& E) {
;     ...
;             PG8_WAIT_V(8); PG8_WAIT_L(0); PG8_BAR; PG8_MMA(1, 0, At, B0); PG8_MMA(1, 1, At, B1); PG8_BAR; PG8_SCHED;
;             PG8_LDB(B0, 1, 0); PG8_LDB(B1, 1, 1); PG8_SCHED; PG8_LDA(At, 1, 0); PG8_STAGE(PG8_SA(0, 1), a2 + hstep, voffA);
;             PG8_WAIT_V(8); PG8_WAIT_L(0); PG8_BAR; PG8_MMA(0, 0, At, B0); PG8_MMA(0, 1, At, B1); PG8_BAR; PG8_SCHED;
	v_mfma_f32_16x16x32_bf16 v[62:65], v[146:149], v[212:215], v[62:65]
	v_mfma_f32_16x16x32_bf16 v[62:65], v[176:179], v[216:219], v[62:65]
	v_mfma_f32_16x16x32_bf16 v[46:49], v[176:179], v[224:227], v[46:49]
	v_mfma_f32_16x16x32_bf16 v[46:49], v[146:149], v[220:223], v[46:49]
	v_mfma_f32_16x16x32_bf16 v[30:33], v[146:149], v[228:231], v[30:33]
	v_mfma_f32_16x16x32_bf16 v[30:33], v[176:179], v[240:243], v[30:33]
	v_mfma_f32_16x16x32_bf16 v[14:17], v[176:179], v[248:251], v[14:17]
	v_mfma_f32_16x16x32_bf16 v[14:17], v[146:149], v[244:247], v[14:17]
	v_mfma_f32_16x16x32_bf16 v[10:13], v[180:183], v[244:247], v[10:13]
	v_mfma_f32_16x16x32_bf16 v[10:13], v[184:187], v[248:251], v[10:13]
	v_mfma_f32_16x16x32_bf16 v[58:61], v[184:187], v[216:219], v[58:61]
	v_mfma_f32_16x16x32_bf16 v[58:61], v[180:183], v[212:215], v[58:61]
	v_mfma_f32_16x16x32_bf16 v[42:45], v[180:183], v[220:223], v[42:45]
	v_mfma_f32_16x16x32_bf16 v[42:45], v[184:187], v[224:227], v[42:45]
	v_mfma_f32_16x16x32_bf16 v[26:29], v[184:187], v[240:243], v[26:29]
	v_mfma_f32_16x16x32_bf16 v[26:29], v[180:183], v[228:231], v[26:29]
	s_setprio 0
	s_setprio 1
	v_mfma_f32_16x16x32_bf16 v[22:25], v[188:191], v[228:231], v[22:25]
	v_mfma_f32_16x16x32_bf16 v[22:25], v[200:203], v[240:243], v[22:25]
	v_mfma_f32_16x16x32_bf16 v[54:57], v[200:203], v[216:219], v[54:57]
	v_mfma_f32_16x16x32_bf16 v[54:57], v[188:191], v[212:215], v[54:57]
	v_mfma_f32_16x16x32_bf16 v[38:41], v[188:191], v[220:223], v[38:41]
	v_mfma_f32_16x16x32_bf16 v[38:41], v[200:203], v[224:227], v[38:41]
	v_mfma_f32_16x16x32_bf16 v[6:9], v[200:203], v[248:251], v[6:9]
	v_mfma_f32_16x16x32_bf16 v[6:9], v[188:191], v[244:247], v[6:9]
	v_mfma_f32_16x16x32_bf16 v[2:5], v[204:207], v[244:247], v[2:5]
	v_mfma_f32_16x16x32_bf16 v[2:5], v[208:211], v[248:251], v[2:5]
	v_mfma_f32_16x16x32_bf16 v[50:53], v[208:211], v[216:219], v[50:53]
	v_mfma_f32_16x16x32_bf16 v[50:53], v[204:207], v[212:215], v[50:53]
	v_mfma_f32_16x16x32_bf16 v[34:37], v[204:207], v[220:223], v[34:37]
	v_mfma_f32_16x16x32_bf16 v[34:37], v[208:211], v[224:227], v[34:37]
	v_mfma_f32_16x16x32_bf16 v[18:21], v[208:211], v[240:243], v[18:21]
	v_mfma_f32_16x16x32_bf16 v[18:21], v[204:207], v[228:231], v[18:21]
	s_barrier
	s_setprio 0
	s_add_i32 s63, 0, 0x18000
	v_add_u32_e32 v175, s63, v153
	s_add_i32 s70, 0, 0x1c000
	ds_read_b128 v[146:149], v175
	ds_read_b128 v[176:179], v175 offset:1024
	ds_read_b128 v[180:183], v175 offset:2048
	ds_read_b128 v[184:187], v175 offset:3072
	v_add_u32_e32 v175, s70, v153
	ds_read_b128 v[188:191], v175
	ds_read_b128 v[200:203], v175 offset:1024
	ds_read_b128 v[204:207], v175 offset:2048
	ds_read_b128 v[208:211], v175 offset:3072
	s_add_u32 s68, s68, 0x100000
	s_addc_u32 s69, s69, 0
	s_mov_b32 m0, s16
	v_lshl_add_u64 v[194:195], s[68:69], 0, v[130:131]
	ds_read_b128 v[212:215], v173 offset:32768
	ds_read_b128 v[216:219], v173 offset:33792
	ds_read_b128 v[220:223], v173 offset:34816
	ds_read_b128 v[224:227], v173 offset:35840
	ds_read_b128 v[228:231], v173 offset:36864
	ds_read_b128 v[240:243], v173 offset:37888
	ds_read_b128 v[244:247], v173 offset:38912
	ds_read_b128 v[248:251], v173 offset:39936
	global_load_lds_dwordx4 v[194:195], off
	v_lshl_add_u64 v[194:195], s[68:69], 0, v[134:135]
	s_mov_b32 m0, s17
	s_nop 0
	global_load_lds_dwordx4 v[194:195], off
	s_waitcnt vmcnt(8)
	s_waitcnt lgkmcnt(0)
	s_setprio 1
	s_barrier
	v_mfma_f32_16x16x32_bf16 v[126:129], v[146:149], v[212:215], v[126:129]
	v_mfma_f32_16x16x32_bf16 v[126:129], v[176:179], v[216:219], v[126:129]
	v_mfma_f32_16x16x32_bf16 v[110:113], v[176:179], v[224:227], v[110:113]
	v_mfma_f32_16x16x32_bf16 v[110:113], v[146:149], v[220:223], v[110:113]
	v_mfma_f32_16x16x32_bf16 v[94:97], v[146:149], v[228:231], v[94:97]
	v_mfma_f32_16x16x32_bf16 v[94:97], v[176:179], v[240:243], v[94:97]
	v_mfma_f32_16x16x32_bf16 v[78:81], v[176:179], v[248:251], v[78:81]
	v_mfma_f32_16x16x32_bf16 v[78:81], v[146:149], v[244:247], v[78:81]
	v_mfma_f32_16x16x32_bf16 v[74:77], v[180:183], v[244:247], v[74:77]
	v_mfma_f32_16x16x32_bf16 v[74:77], v[184:187], v[248:251], v[74:77]
	v_mfma_f32_16x16x32_bf16 v[122:125], v[184:187], v[216:219], v[122:125]
	v_mfma_f32_16x16x32_bf16 v[122:125], v[180:183], v[212:215], v[122:125]
	v_mfma_f32_16x16x32_bf16 v[106:109], v[180:183], v[220:223], v[106:109]
	v_mfma_f32_16x16x32_bf16 v[106:109], v[184:187], v[224:227], v[106:109]
	v_mfma_f32_16x16x32_bf16 v[90:93], v[184:187], v[240:243], v[90:93]
	v_mfma_f32_16x16x32_bf16 v[90:93], v[180:183], v[228:231], v[90:93]
	s_setprio 0
	s_setprio 1
	v_mfma_f32_16x16x32_bf16 v[86:89], v[188:191], v[228:231], v[86:89]
	v_mfma_f32_16x16x32_bf16 v[86:89], v[200:203], v[240:243], v[86:89]
	v_mfma_f32_16x16x32_bf16 v[118:121], v[200:203], v[216:219], v[118:121]
	v_mfma_f32_16x16x32_bf16 v[118:121], v[188:191], v[212:215], v[118:121]
	v_mfma_f32_16x16x32_bf16 v[102:105], v[188:191], v[220:223], v[102:105]
	v_mfma_f32_16x16x32_bf16 v[102:105], v[200:203], v[224:227], v[102:105]
	v_mfma_f32_16x16x32_bf16 v[70:73], v[200:203], v[248:251], v[70:73]
	v_mfma_f32_16x16x32_bf16 v[70:73], v[188:191], v[244:247], v[70:73]
	v_mfma_f32_16x16x32_bf16 v[66:69], v[204:207], v[244:247], v[66:69]
	v_mfma_f32_16x16x32_bf16 v[66:69], v[208:211], v[248:251], v[66:69]
	v_mfma_f32_16x16x32_bf16 v[114:117], v[208:211], v[216:219], v[114:117]
	v_mfma_f32_16x16x32_bf16 v[114:117], v[204:207], v[212:215], v[114:117]
	v_mfma_f32_16x16x32_bf16 v[98:101], v[204:207], v[220:223], v[98:101]
	v_mfma_f32_16x16x32_bf16 v[98:101], v[208:211], v[224:227], v[98:101]
	v_mfma_f32_16x16x32_bf16 v[82:85], v[208:211], v[240:243], v[82:85]
	v_mfma_f32_16x16x32_bf16 v[82:85], v[204:207], v[228:231], v[82:85]
	s_barrier
; #define PG8_STAGE(bufoff, gbase, voff) do { _Pragma("unroll") for (int _i = 0; _i < 2; ++_i) \
;         __builtin_amdgcn_global_load_lds((const unsigned*)((const char*)(gbase) + (voff)[_i]), (PG8_LAS unsigned*)(lds + (bufoff) + ldsw + _i * 8192), 16, 0, 0); } while (0)
; #define PG8_LDA(dst, b, h) do { _Pragma("unroll") for (int m = 0; m < 4; ++m) _Pragma("unroll") for (int k = 0; k < 2; ++k) dst[m][k] = *(const PG8_LAS bf16x8*)(lds + PG8_SA(b, h) + aoff + m * 2048 + k * 1024); } while (0)
; #define PG8_MMA(ai, bj, At, Bt) do { __builtin_amdgcn_s_setprio(1); _Pragma("unroll") for (int m = 0; m < 4; ++m) _Pragma("unroll") for (int n = 0; n < 2; ++n) _Pragma("unroll") for (int k = 0; k < 2; ++k) \
;         acc[ai][bj][m][n] = __builtin_amdgcn_mfma_f32_16x16x32_bf16(Bt[n][k], At[m][k], acc[ai][bj][m][n], 0, 0, 0); __builtin_amdgcn_s_setprio(0); } while (0)
; #define PG8_WAIT_V(n) asm volatile("s_waitcnt vmcnt(" #n ")" ::: "memory")
; #define PG8_WAIT_L(n) asm volatile("s_waitcnt lgkmcnt(" #n ")" ::: "memory")
; #define PG8_BAR __builtin_amdgcn_s_barrier()
; #define PG8_SCHED __builtin_amdgcn_sched_barrier(0)
; template <class Epi, class Sched, bool ALIGN_EPI = false, bool SP2 = false>
; __device__ __forceinline__ void gemm_phase(PG8_LAS unsigned char* lds, const Gemm g, const Sched& S, const Epi& E) {
;     ...
;             PG8_LDA(At, 1, 1); PG8_STAGE(PG8_SB(1, 0), b3, voffB); PG8_STAGE(PG8_SB(1, 1), b3 + hstep, voffB); PG8_STAGE(PG8_SA(1, 0), a3, voffA);
;             PG8_WAIT_V(8); PG8_WAIT_L(0); PG8_BAR; PG8_MMA(1, 0, At, B0); PG8_MMA(1, 1, At, B1); PG8_BAR; PG8_SCHED;
;     ...
;         if constexpr (ALIGN_EPI) { if (wr == 0) PG8_BAR; }
	s_setprio 0
	s_add_i32 s63, s63, s2
	v_lshl_add_u64 v[150:151], v[150:151], 0, s[44:45]
	s_mov_b32 m0, s63
	ds_read_b128 v[212:215], v173 offset:49152
	ds_read_b128 v[216:219], v173 offset:50176
	ds_read_b128 v[220:223], v173 offset:51200
	ds_read_b128 v[224:227], v173 offset:52224
	ds_read_b128 v[228:231], v173 offset:53248
	ds_read_b128 v[240:243], v173 offset:54272
	ds_read_b128 v[244:247], v173 offset:55296
	ds_read_b128 v[248:251], v173 offset:56320
	global_load_lds_dwordx4 v[150:151], off
	s_add_i32 m0, s63, 0x2000
	s_add_u32 s66, s66, 0x100080
	v_lshl_add_u64 v[150:151], v[192:193], 0, s[44:45]
	s_addc_u32 s67, s67, 0
	s_add_i32 s63, s70, s2
	global_load_lds_dwordx4 v[150:151], off
	v_lshl_add_u64 v[150:151], s[66:67], 0, v[132:133]
	s_mov_b32 m0, s63
	s_nop 0
	global_load_lds_dwordx4 v[150:151], off
	v_lshl_add_u64 v[150:151], s[66:67], 0, v[136:137]
	s_add_i32 m0, s63, 0x2000
	s_nop 0
	global_load_lds_dwordx4 v[150:151], off
	v_lshl_add_u64 v[150:151], v[232:233], 0, s[44:45]
	s_mov_b32 m0, s26
	s_nop 0
	global_load_lds_dwordx4 v[150:151], off
	v_lshl_add_u64 v[150:151], v[252:253], 0, s[44:45]
	s_mov_b32 m0, s27
	s_nop 0
	global_load_lds_dwordx4 v[150:151], off
	s_waitcnt vmcnt(8)
	s_waitcnt lgkmcnt(0)
	s_setprio 1
	s_barrier
	v_mfma_f32_16x16x32_bf16 v[62:65], v[146:149], v[212:215], v[62:65]
	v_mfma_f32_16x16x32_bf16 v[62:65], v[176:179], v[216:219], v[62:65]
	v_mfma_f32_16x16x32_bf16 v[46:49], v[176:179], v[224:227], v[46:49]
	v_mfma_f32_16x16x32_bf16 v[46:49], v[146:149], v[220:223], v[46:49]
	v_mfma_f32_16x16x32_bf16 v[30:33], v[146:149], v[228:231], v[30:33]
	v_mfma_f32_16x16x32_bf16 v[30:33], v[176:179], v[240:243], v[30:33]
	v_mfma_f32_16x16x32_bf16 v[14:17], v[176:179], v[248:251], v[14:17]
	v_mfma_f32_16x16x32_bf16 v[14:17], v[146:149], v[244:247], v[14:17]
	v_mfma_f32_16x16x32_bf16 v[10:13], v[180:183], v[244:247], v[10:13]
	v_mfma_f32_16x16x32_bf16 v[10:13], v[184:187], v[248:251], v[10:13]
	v_mfma_f32_16x16x32_bf16 v[58:61], v[184:187], v[216:219], v[58:61]
	v_mfma_f32_16x16x32_bf16 v[58:61], v[180:183], v[212:215], v[58:61]
	v_mfma_f32_16x16x32_bf16 v[42:45], v[180:183], v[220:223], v[42:45]
	v_mfma_f32_16x16x32_bf16 v[42:45], v[184:187], v[224:227], v[42:45]
	v_mfma_f32_16x16x32_bf16 v[26:29], v[184:187], v[240:243], v[26:29]
	v_mfma_f32_16x16x32_bf16 v[26:29], v[180:183], v[228:231], v[26:29]
	s_setprio 0
	s_setprio 1
	v_mfma_f32_16x16x32_bf16 v[22:25], v[188:191], v[228:231], v[22:25]
	v_mfma_f32_16x16x32_bf16 v[22:25], v[200:203], v[240:243], v[22:25]
	v_mfma_f32_16x16x32_bf16 v[54:57], v[200:203], v[216:219], v[54:57]
	v_mfma_f32_16x16x32_bf16 v[54:57], v[188:191], v[212:215], v[54:57]
	v_mfma_f32_16x16x32_bf16 v[38:41], v[188:191], v[220:223], v[38:41]
	v_mfma_f32_16x16x32_bf16 v[38:41], v[200:203], v[224:227], v[38:41]
	v_mfma_f32_16x16x32_bf16 v[6:9], v[200:203], v[248:251], v[6:9]
	v_mfma_f32_16x16x32_bf16 v[6:9], v[188:191], v[244:247], v[6:9]
	v_mfma_f32_16x16x32_bf16 v[2:5], v[204:207], v[244:247], v[2:5]
	v_mfma_f32_16x16x32_bf16 v[2:5], v[208:211], v[248:251], v[2:5]
	v_mfma_f32_16x16x32_bf16 v[50:53], v[208:211], v[216:219], v[50:53]
	v_mfma_f32_16x16x32_bf16 v[50:53], v[204:207], v[212:215], v[50:53]
	v_mfma_f32_16x16x32_bf16 v[34:37], v[204:207], v[220:223], v[34:37]
	v_mfma_f32_16x16x32_bf16 v[34:37], v[208:211], v[224:227], v[34:37]
	v_mfma_f32_16x16x32_bf16 v[18:21], v[208:211], v[240:243], v[18:21]
	v_mfma_f32_16x16x32_bf16 v[18:21], v[204:207], v[228:231], v[18:21]
	s_barrier
	s_setprio 0
	s_add_i32 s61, s61, 2
	s_add_u32 s64, s64, 0x100
	s_addc_u32 s65, s65, 0
	s_add_u32 s53, s53, 0x100
	s_addc_u32 s55, s55, 0
	s_cmp_gt_u32 s61, 61
	s_cbranch_scc0 .LBB0_1203
	s_and_b64 vcc, exec, s[46:47]
	s_cbranch_vccz .LBB0_1206
	s_barrier

; #define PG8_STAGE(bufoff, gbase, voff) do { _Pragma("unroll") for (int _i = 0; _i < 2; ++_i) \
;         __builtin_amdgcn_global_load_lds((const unsigned*)((const char*)(gbase) + (voff)[_i]), (PG8_LAS unsigned*)(lds + (bufoff) + ldsw + _i * 8192), 16, 0, 0); } while (0)
; #define PG8_LDA(dst, b, h) do { _Pragma("unroll") for (int m = 0; m < 4; ++m) _Pragma("unroll") for (int k = 0; k < 2; ++k) dst[m][k] = *(const PG8_LAS bf16x8*)(lds + PG8_SA(b, h) + aoff + m * 2048 + k * 1024); } while (0)
; #define PG8_LDB(dst, b, h) do { _Pragma("unroll") for (int n = 0; n < 2; ++n) _Pragma("unroll") for (int k = 0; k < 2; ++k) dst[n][k] = *(const PG8_LAS bf16x8*)(lds + PG8_SB(b, h) + boff + n * 2048 + k * 1024); } while (0)
; #define PG8_MMA(ai, bj, At, Bt) do { __builtin_amdgcn_s_setprio(1); _Pragma("unroll") for (int m = 0; m < 4; ++m) _Pragma("unroll") for (int n = 0; n < 2; ++n) _Pragma("unroll") for (int k = 0; k < 2; ++k) \
;         acc[ai][bj][m][n] = __builtin_amdgcn_mfma_f32_16x16x32_bf16(Bt[n][k], At[m][k], acc[ai][bj][m][n], 0, 0, 0); __builtin_amdgcn_s_setprio(0); } while (0)
; #define PG8_WAIT_V(n) asm volatile("s_waitcnt vmcnt(" #n ")" ::: "memory")
; #define PG8_WAIT_L(n) asm volatile("s_waitcnt lgkmcnt(" #n ")" ::: "memory")
; #define PG8_BAR __builtin_amdgcn_s_barrier()
; #define PG8_SCHED __builtin_amdgcn_sched_barrier(0)
; template <class Epi, class Sched, bool ALIGN_EPI = false, bool SP2 = false>
; __device__ __forceinline__ void gemm_phase(PG8_LAS unsigned char* lds, const Gemm g, const Sched& S, const Epi& E) {
;     ...
;             const bool last = (t == nt - 2);
;             const char* a1 = cA + (size_t)(t + 1) * kstep;
;             const char* a2 = last ? nA : cA + (size_t)(t + 2) * kstep; const char* b2 = last ? nB : cB + (size_t)(t + 2) * kstep;
;             const char* a3 = a2 + kstep; const char* b3 = b2 + kstep;
;             if (last && has_next) S.a_ready(nxt);
;             if constexpr (SP2) {
;             PG8_LDB(B0, 0, 0); PG8_LDB(B1, 0, 1); PG8_SCHED; PG8_LDA(At, 0, 0); PG8_STAGE(PG8_SA(1, 1), a1 + hstep, voffA);
;             PG8_WAIT_V(8); PG8_WAIT_L(0); PG8_BAR; PG8_MMA(0, 0, At, B0); PG8_MMA(0, 1, At, B1); PG8_BAR; PG8_SCHED;
;             PG8_LDA(At, 0, 1); PG8_STAGE(PG8_SB(0, 0), b2, voffB); PG8_STAGE(PG8_SB(0, 1), b2 + hstep, voffB); PG8_STAGE(PG8_SA(0, 0), a2, voffA);
.LBB0_1230:
	ds_read_b128 v[146:149], v140
	ds_read_b128 v[150:153], v140 offset:1024
	ds_read_b128 v[154:157], v140 offset:2048
	ds_read_b128 v[158:161], v140 offset:3072
	ds_read_b128 v[168:171], v141
	ds_read_b128 v[172:175], v141 offset:1024
	ds_read_b128 v[176:179], v141 offset:2048
	ds_read_b128 v[180:183], v141 offset:3072
	s_add_u32 s50, s46, 0x100
	s_addc_u32 s51, s47, 0
	s_cmp_lg_u32 s30, 12
	s_cselect_b32 s52, s50, 0
	s_cselect_b32 s53, s51, 0
	s_add_u32 s54, s10, s52
	s_addc_u32 s55, s11, s53
	s_add_u32 s52, s8, s52
	s_addc_u32 s53, s9, s53
	s_mov_b32 m0, s33
	v_lshl_add_u64 v[162:163], v[134:135], 0, s[46:47]
	ds_read_b128 v[184:187], v142
	ds_read_b128 v[188:191], v142 offset:1024
	ds_read_b128 v[200:203], v142 offset:2048
	ds_read_b128 v[204:207], v142 offset:3072
	ds_read_b128 v[208:211], v142 offset:4096
	ds_read_b128 v[212:215], v142 offset:5120
	ds_read_b128 v[216:219], v142 offset:6144
	ds_read_b128 v[220:223], v142 offset:7168
	global_load_lds_dwordx4 v[162:163], off
	v_lshl_add_u64 v[162:163], v[136:137], 0, s[46:47]
	s_mov_b32 m0, s34
	s_nop 0
	global_load_lds_dwordx4 v[162:163], off
	s_waitcnt vmcnt(8)
	s_waitcnt lgkmcnt(0)
	s_setprio 1
	s_barrier
	v_mfma_f32_16x16x32_bf16 v[126:129], v[146:149], v[184:187], v[126:129]
	v_mfma_f32_16x16x32_bf16 v[126:129], v[150:153], v[188:191], v[126:129]
	v_mfma_f32_16x16x32_bf16 v[118:121], v[150:153], v[204:207], v[118:121]
	v_mfma_f32_16x16x32_bf16 v[118:121], v[146:149], v[200:203], v[118:121]
	v_mfma_f32_16x16x32_bf16 v[106:109], v[146:149], v[208:211], v[106:109]
	v_mfma_f32_16x16x32_bf16 v[106:109], v[150:153], v[212:215], v[106:109]
	v_mfma_f32_16x16x32_bf16 v[90:93], v[150:153], v[220:223], v[90:93]
	v_mfma_f32_16x16x32_bf16 v[90:93], v[146:149], v[216:219], v[90:93]
	v_mfma_f32_16x16x32_bf16 v[82:85], v[154:157], v[216:219], v[82:85]
	v_mfma_f32_16x16x32_bf16 v[82:85], v[158:161], v[220:223], v[82:85]
	v_mfma_f32_16x16x32_bf16 v[122:125], v[158:161], v[188:191], v[122:125]
	v_mfma_f32_16x16x32_bf16 v[122:125], v[154:157], v[184:187], v[122:125]
	v_mfma_f32_16x16x32_bf16 v[114:117], v[154:157], v[200:203], v[114:117]
	v_mfma_f32_16x16x32_bf16 v[114:117], v[158:161], v[204:207], v[114:117]
	v_mfma_f32_16x16x32_bf16 v[98:101], v[158:161], v[212:215], v[98:101]
	v_mfma_f32_16x16x32_bf16 v[98:101], v[154:157], v[208:211], v[98:101]
	s_setprio 0
	s_setprio 1
	v_mfma_f32_16x16x32_bf16 v[78:81], v[168:171], v[208:211], v[78:81]
	v_mfma_f32_16x16x32_bf16 v[78:81], v[172:175], v[212:215], v[78:81]
	v_mfma_f32_16x16x32_bf16 v[110:113], v[172:175], v[188:191], v[110:113]
	v_mfma_f32_16x16x32_bf16 v[110:113], v[168:171], v[184:187], v[110:113]
	v_mfma_f32_16x16x32_bf16 v[94:97], v[168:171], v[200:203], v[94:97]
	v_mfma_f32_16x16x32_bf16 v[94:97], v[172:175], v[204:207], v[94:97]
	v_mfma_f32_16x16x32_bf16 v[70:73], v[172:175], v[220:223], v[70:73]
	v_mfma_f32_16x16x32_bf16 v[70:73], v[168:171], v[216:219], v[70:73]
	v_mfma_f32_16x16x32_bf16 v[66:69], v[176:179], v[216:219], v[66:69]
	v_mfma_f32_16x16x32_bf16 v[66:69], v[180:183], v[220:223], v[66:69]
	v_mfma_f32_16x16x32_bf16 v[102:105], v[180:183], v[188:191], v[102:105]
	v_mfma_f32_16x16x32_bf16 v[102:105], v[176:179], v[184:187], v[102:105]
	v_mfma_f32_16x16x32_bf16 v[86:89], v[176:179], v[200:203], v[86:89]
	v_mfma_f32_16x16x32_bf16 v[86:89], v[180:183], v[204:207], v[86:89]
	v_mfma_f32_16x16x32_bf16 v[74:77], v[180:183], v[212:215], v[74:77]
	v_mfma_f32_16x16x32_bf16 v[74:77], v[176:179], v[208:211], v[74:77]
	s_barrier
	s_setprio 0
	s_mov_b32 m0, s35
	v_lshl_add_u64 v[162:163], s[52:53], 0, v[130:131]
	s_add_u32 s46, s52, 0x100000
	ds_read_b128 v[184:187], v142 offset:16384
	ds_read_b128 v[188:191], v142 offset:17408
	ds_read_b128 v[200:203], v142 offset:18432
	ds_read_b128 v[204:207], v142 offset:19456
	ds_read_b128 v[208:211], v142 offset:20480
	ds_read_b128 v[212:215], v142 offset:21504
	ds_read_b128 v[216:219], v142 offset:22528
	ds_read_b128 v[220:223], v142 offset:23552
	global_load_lds_dwordx4 v[162:163], off
	v_lshl_add_u64 v[192:193], s[52:53], 0, v[132:133]
	s_mov_b32 m0, s39
	s_addc_u32 s47, s53, 0
	global_load_lds_dwordx4 v[192:193], off
	v_lshl_add_u64 v[194:195], s[46:47], 0, v[130:131]
	s_mov_b32 m0, s40
	v_lshl_add_u64 v[224:225], s[54:55], 0, v[132:133]
	global_load_lds_dwordx4 v[194:195], off
	v_lshl_add_u64 v[194:195], s[46:47], 0, v[132:133]
	s_mov_b32 m0, s41
	s_nop 0
	global_load_lds_dwordx4 v[194:195], off
	v_lshl_add_u64 v[194:195], s[54:55], 0, v[130:131]
	s_mov_b32 m0, s7
	s_nop 0
	global_load_lds_dwordx4 v[194:195], off
	s_mov_b32 m0, s16
	s_nop 0
	global_load_lds_dwordx4 v[224:225], off
	s_waitcnt vmcnt(8)
	s_waitcnt lgkmcnt(0)
	s_setprio 1
	s_barrier
; #define PG8_STAGE(bufoff, gbase, voff) do { _Pragma("unroll") for (int _i = 0; _i < 2; ++_i) \
;         __builtin_amdgcn_global_load_lds((const unsigned*)((const char*)(gbase) + (voff)[_i]), (PG8_LAS unsigned*)(lds + (bufoff) + ldsw + _i * 8192), 16, 0, 0); } while (0)
; #define PG8_LDA(dst, b, h) do { _Pragma("unroll") for (int m = 0; m < 4; ++m) _Pragma("unroll") for (int k = 0; k < 2; ++k) dst[m][k] = *(const PG8_LAS bf16x8*)(lds + PG8_SA(b, h) + aoff + m * 2048 + k * 1024); } while (0)
; #define PG8_LDB(dst, b, h) do { _Pragma("unroll") for (int n = 0; n < 2; ++n) _Pragma("unroll") for (int k = 0; k < 2; ++k) dst[n][k] = *(const PG8_LAS bf16x8*)(lds + PG8_SB(b, h) + boff + n * 2048 + k * 1024); } while (0)
; #define PG8_MMA(ai, bj, At, Bt) do { __builtin_amdgcn_s_setprio(1); _Pragma("unroll") for (int m = 0; m < 4; ++m) _Pragma("unroll") for (int n = 0; n < 2; ++n) _Pragma("unroll") for (int k = 0; k < 2; ++k) \
;         acc[ai][bj][m][n] = __builtin_amdgcn_mfma_f32_16x16x32_bf16(Bt[n][k], At[m][k], acc[ai][bj][m][n], 0, 0, 0); __builtin_amdgcn_s_setprio(0); } while (0)
; #define PG8_WAIT_V(n) asm volatile("s_waitcnt vmcnt(" #n ")" ::: "memory")
; #define PG8_WAIT_L(n) asm volatile("s_waitcnt lgkmcnt(" #n ")" ::: "memory")
; #define PG8_BAR __builtin_amdgcn_s_barrier()
; #define PG8_SCHED __builtin_amdgcn_sched_barrier(0)
; template <class Epi, class Sched, bool ALIGN_EPI = false, bool SP2 = false>
; __device__ __forceinline__ void gemm_phase(PG8_LAS unsigned char* lds, const Gemm g, const Sched& S, const Epi& E) {
;     ...
;             PG8_WAIT_V(8); PG8_WAIT_L(0); PG8_BAR; PG8_MMA(1, 0, At, B0); PG8_MMA(1, 1, At, B1); PG8_BAR; PG8_SCHED;
;             PG8_LDB(B0, 1, 0); PG8_LDB(B1, 1, 1); PG8_SCHED; PG8_LDA(At, 1, 0); PG8_STAGE(PG8_SA(0, 1), a2 + hstep, voffA);
;             PG8_WAIT_V(8); PG8_WAIT_L(0); PG8_BAR; PG8_MMA(0, 0, At, B0); PG8_MMA(0, 1, At, B1); PG8_BAR; PG8_SCHED;
	v_mfma_f32_16x16x32_bf16 v[62:65], v[146:149], v[184:187], v[62:65]
	v_mfma_f32_16x16x32_bf16 v[62:65], v[150:153], v[188:191], v[62:65]
	v_mfma_f32_16x16x32_bf16 v[54:57], v[150:153], v[204:207], v[54:57]
	v_mfma_f32_16x16x32_bf16 v[54:57], v[146:149], v[200:203], v[54:57]
	v_mfma_f32_16x16x32_bf16 v[42:45], v[146:149], v[208:211], v[42:45]
	v_mfma_f32_16x16x32_bf16 v[42:45], v[150:153], v[212:215], v[42:45]
	v_mfma_f32_16x16x32_bf16 v[26:29], v[150:153], v[220:223], v[26:29]
	v_mfma_f32_16x16x32_bf16 v[26:29], v[146:149], v[216:219], v[26:29]
	v_mfma_f32_16x16x32_bf16 v[18:21], v[154:157], v[216:219], v[18:21]
	v_mfma_f32_16x16x32_bf16 v[18:21], v[158:161], v[220:223], v[18:21]
	v_mfma_f32_16x16x32_bf16 v[58:61], v[158:161], v[188:191], v[58:61]
	v_mfma_f32_16x16x32_bf16 v[58:61], v[154:157], v[184:187], v[58:61]
	v_mfma_f32_16x16x32_bf16 v[50:53], v[154:157], v[200:203], v[50:53]
	v_mfma_f32_16x16x32_bf16 v[50:53], v[158:161], v[204:207], v[50:53]
	v_mfma_f32_16x16x32_bf16 v[34:37], v[158:161], v[212:215], v[34:37]
	v_mfma_f32_16x16x32_bf16 v[34:37], v[154:157], v[208:211], v[34:37]
	s_setprio 0
	s_setprio 1
	v_mfma_f32_16x16x32_bf16 v[14:17], v[168:171], v[208:211], v[14:17]
	v_mfma_f32_16x16x32_bf16 v[14:17], v[172:175], v[212:215], v[14:17]
	v_mfma_f32_16x16x32_bf16 v[46:49], v[172:175], v[188:191], v[46:49]
	v_mfma_f32_16x16x32_bf16 v[46:49], v[168:171], v[184:187], v[46:49]
	v_mfma_f32_16x16x32_bf16 v[30:33], v[168:171], v[200:203], v[30:33]
	v_mfma_f32_16x16x32_bf16 v[30:33], v[172:175], v[204:207], v[30:33]
	v_mfma_f32_16x16x32_bf16 v[6:9], v[172:175], v[220:223], v[6:9]
	v_mfma_f32_16x16x32_bf16 v[6:9], v[168:171], v[216:219], v[6:9]
	v_mfma_f32_16x16x32_bf16 v[2:5], v[176:179], v[216:219], v[2:5]
	v_mfma_f32_16x16x32_bf16 v[2:5], v[180:183], v[220:223], v[2:5]
	v_mfma_f32_16x16x32_bf16 v[38:41], v[180:183], v[188:191], v[38:41]
	v_mfma_f32_16x16x32_bf16 v[38:41], v[176:179], v[184:187], v[38:41]
	v_mfma_f32_16x16x32_bf16 v[22:25], v[176:179], v[200:203], v[22:25]
	v_mfma_f32_16x16x32_bf16 v[22:25], v[180:183], v[204:207], v[22:25]
	v_mfma_f32_16x16x32_bf16 v[10:13], v[180:183], v[212:215], v[10:13]
	v_mfma_f32_16x16x32_bf16 v[10:13], v[176:179], v[208:211], v[10:13]
	s_barrier
	s_setprio 0
	ds_read_b128 v[146:149], v143
	ds_read_b128 v[150:153], v143 offset:1024
	ds_read_b128 v[154:157], v143 offset:2048
	ds_read_b128 v[158:161], v143 offset:3072
	ds_read_b128 v[168:171], v144
	ds_read_b128 v[172:175], v144 offset:1024
	ds_read_b128 v[176:179], v144 offset:2048
	ds_read_b128 v[180:183], v144 offset:3072
	s_add_u32 s46, s54, 0x100000
	s_addc_u32 s47, s55, 0
	s_mov_b32 m0, s17
	v_lshl_add_u64 v[226:227], s[46:47], 0, v[130:131]
	ds_read_b128 v[184:187], v142 offset:32768
	ds_read_b128 v[188:191], v142 offset:33792
	ds_read_b128 v[200:203], v142 offset:34816
	ds_read_b128 v[204:207], v142 offset:35840
	ds_read_b128 v[208:211], v142 offset:36864
	ds_read_b128 v[212:215], v142 offset:37888
	ds_read_b128 v[216:219], v142 offset:38912
	ds_read_b128 v[220:223], v142 offset:39936
	global_load_lds_dwordx4 v[226:227], off
	v_lshl_add_u64 v[226:227], s[46:47], 0, v[132:133]
	s_mov_b32 m0, s26
	s_nop 0
	global_load_lds_dwordx4 v[226:227], off
	s_waitcnt vmcnt(8)
	s_waitcnt lgkmcnt(0)
	s_setprio 1
	s_barrier
	v_mfma_f32_16x16x32_bf16 v[126:129], v[146:149], v[184:187], v[126:129]
	v_mfma_f32_16x16x32_bf16 v[126:129], v[150:153], v[188:191], v[126:129]
	v_mfma_f32_16x16x32_bf16 v[118:121], v[150:153], v[204:207], v[118:121]
	v_mfma_f32_16x16x32_bf16 v[118:121], v[146:149], v[200:203], v[118:121]
	v_mfma_f32_16x16x32_bf16 v[106:109], v[146:149], v[208:211], v[106:109]
	v_mfma_f32_16x16x32_bf16 v[106:109], v[150:153], v[212:215], v[106:109]
	v_mfma_f32_16x16x32_bf16 v[90:93], v[150:153], v[220:223], v[90:93]
	v_mfma_f32_16x16x32_bf16 v[90:93], v[146:149], v[216:219], v[90:93]
	v_mfma_f32_16x16x32_bf16 v[82:85], v[154:157], v[216:219], v[82:85]
	v_mfma_f32_16x16x32_bf16 v[82:85], v[158:161], v[220:223], v[82:85]
	v_mfma_f32_16x16x32_bf16 v[122:125], v[158:161], v[188:191], v[122:125]
	v_mfma_f32_16x16x32_bf16 v[122:125], v[154:157], v[184:187], v[122:125]
	v_mfma_f32_16x16x32_bf16 v[114:117], v[154:157], v[200:203], v[114:117]
	v_mfma_f32_16x16x32_bf16 v[114:117], v[158:161], v[204:207], v[114:117]
	v_mfma_f32_16x16x32_bf16 v[98:101], v[158:161], v[212:215], v[98:101]
	v_mfma_f32_16x16x32_bf16 v[98:101], v[154:157], v[208:211], v[98:101]
	s_setprio 0
	s_setprio 1
	v_mfma_f32_16x16x32_bf16 v[78:81], v[168:171], v[208:211], v[78:81]
	v_mfma_f32_16x16x32_bf16 v[78:81], v[172:175], v[212:215], v[78:81]
	v_mfma_f32_16x16x32_bf16 v[110:113], v[172:175], v[188:191], v[110:113]
	v_mfma_f32_16x16x32_bf16 v[110:113], v[168:171], v[184:187], v[110:113]
	v_mfma_f32_16x16x32_bf16 v[94:97], v[168:171], v[200:203], v[94:97]
	v_mfma_f32_16x16x32_bf16 v[94:97], v[172:175], v[204:207], v[94:97]
	v_mfma_f32_16x16x32_bf16 v[70:73], v[172:175], v[220:223], v[70:73]
	v_mfma_f32_16x16x32_bf16 v[70:73], v[168:171], v[216:219], v[70:73]
	v_mfma_f32_16x16x32_bf16 v[66:69], v[176:179], v[216:219], v[66:69]
	v_mfma_f32_16x16x32_bf16 v[66:69], v[180:183], v[220:223], v[66:69]
	v_mfma_f32_16x16x32_bf16 v[102:105], v[180:183], v[188:191], v[102:105]
	v_mfma_f32_16x16x32_bf16 v[102:105], v[176:179], v[184:187], v[102:105]
	v_mfma_f32_16x16x32_bf16 v[86:89], v[176:179], v[200:203], v[86:89]
	v_mfma_f32_16x16x32_bf16 v[86:89], v[180:183], v[204:207], v[86:89]
	v_mfma_f32_16x16x32_bf16 v[74:77], v[180:183], v[212:215], v[74:77]
	v_mfma_f32_16x16x32_bf16 v[74:77], v[176:179], v[208:211], v[74:77]
	s_barrier
; #define PG8_STAGE(bufoff, gbase, voff) do { _Pragma("unroll") for (int _i = 0; _i < 2; ++_i) \
;         __builtin_amdgcn_global_load_lds((const unsigned*)((const char*)(gbase) + (voff)[_i]), (PG8_LAS unsigned*)(lds + (bufoff) + ldsw + _i * 8192), 16, 0, 0); } while (0)
; #define PG8_LDA(dst, b, h) do { _Pragma("unroll") for (int m = 0; m < 4; ++m) _Pragma("unroll") for (int k = 0; k < 2; ++k) dst[m][k] = *(const PG8_LAS bf16x8*)(lds + PG8_SA(b, h) + aoff + m * 2048 + k * 1024); } while (0)
; #define PG8_MMA(ai, bj, At, Bt) do { __builtin_amdgcn_s_setprio(1); _Pragma("unroll") for (int m = 0; m < 4; ++m) _Pragma("unroll") for (int n = 0; n < 2; ++n) _Pragma("unroll") for (int k = 0; k < 2; ++k) \
;         acc[ai][bj][m][n] = __builtin_amdgcn_mfma_f32_16x16x32_bf16(Bt[n][k], At[m][k], acc[ai][bj][m][n], 0, 0, 0); __builtin_amdgcn_s_setprio(0); } while (0)
; #define PG8_WAIT_V(n) asm volatile("s_waitcnt vmcnt(" #n ")" ::: "memory")
; #define PG8_WAIT_L(n) asm volatile("s_waitcnt lgkmcnt(" #n ")" ::: "memory")
; #define PG8_BAR __builtin_amdgcn_s_barrier()
; #define PG8_SCHED __builtin_amdgcn_sched_barrier(0)
; template <class Epi, class Sched, bool ALIGN_EPI = false, bool SP2 = false>
; __device__ __forceinline__ void gemm_phase(PG8_LAS unsigned char* lds, const Gemm g, const Sched& S, const Epi& E) {
;     ...
;             PG8_LDA(At, 1, 1); PG8_STAGE(PG8_SB(1, 0), b3, voffB); PG8_STAGE(PG8_SB(1, 1), b3 + hstep, voffB); PG8_STAGE(PG8_SA(1, 0), a3, voffA);
;             PG8_WAIT_V(8); PG8_WAIT_L(0); PG8_BAR; PG8_MMA(1, 0, At, B0); PG8_MMA(1, 1, At, B1); PG8_BAR; PG8_SCHED;
;     ...
;         if constexpr (ALIGN_EPI) { if (wr == 0) PG8_BAR; }
	s_setprio 0
	s_mov_b32 m0, s44
	v_lshl_add_u64 v[162:163], v[162:163], 0, s[12:13]
	s_add_u32 s46, s52, 0x100080
	ds_read_b128 v[184:187], v142 offset:49152
	ds_read_b128 v[188:191], v142 offset:50176
	ds_read_b128 v[200:203], v142 offset:51200
	ds_read_b128 v[204:207], v142 offset:52224
	ds_read_b128 v[208:211], v142 offset:53248
	ds_read_b128 v[212:215], v142 offset:54272
	ds_read_b128 v[216:219], v142 offset:55296
	ds_read_b128 v[220:223], v142 offset:56320
	global_load_lds_dwordx4 v[162:163], off
	v_lshl_add_u64 v[162:163], v[192:193], 0, s[12:13]
	s_mov_b32 m0, s45
	s_addc_u32 s47, s53, 0
	global_load_lds_dwordx4 v[162:163], off
	v_lshl_add_u64 v[162:163], s[46:47], 0, v[130:131]
	s_mov_b32 m0, s56
	s_nop 0
	global_load_lds_dwordx4 v[162:163], off
	v_lshl_add_u64 v[162:163], s[46:47], 0, v[132:133]
	s_mov_b32 m0, s57
	s_nop 0
	global_load_lds_dwordx4 v[162:163], off
	v_lshl_add_u64 v[162:163], v[194:195], 0, s[12:13]
	s_mov_b32 m0, s28
	s_nop 0
	global_load_lds_dwordx4 v[162:163], off
	v_lshl_add_u64 v[162:163], v[224:225], 0, s[12:13]
	s_mov_b32 m0, s29
	s_nop 0
	global_load_lds_dwordx4 v[162:163], off
	s_waitcnt vmcnt(8)
	s_waitcnt lgkmcnt(0)
	s_setprio 1
	s_barrier
	v_mfma_f32_16x16x32_bf16 v[62:65], v[146:149], v[184:187], v[62:65]
	v_mfma_f32_16x16x32_bf16 v[62:65], v[150:153], v[188:191], v[62:65]
	v_mfma_f32_16x16x32_bf16 v[54:57], v[150:153], v[204:207], v[54:57]
	v_mfma_f32_16x16x32_bf16 v[54:57], v[146:149], v[200:203], v[54:57]
	v_mfma_f32_16x16x32_bf16 v[42:45], v[146:149], v[208:211], v[42:45]
	v_mfma_f32_16x16x32_bf16 v[42:45], v[150:153], v[212:215], v[42:45]
	v_mfma_f32_16x16x32_bf16 v[26:29], v[150:153], v[220:223], v[26:29]
	v_mfma_f32_16x16x32_bf16 v[26:29], v[146:149], v[216:219], v[26:29]
	v_mfma_f32_16x16x32_bf16 v[18:21], v[154:157], v[216:219], v[18:21]
	v_mfma_f32_16x16x32_bf16 v[18:21], v[158:161], v[220:223], v[18:21]
	v_mfma_f32_16x16x32_bf16 v[58:61], v[158:161], v[188:191], v[58:61]
	v_mfma_f32_16x16x32_bf16 v[58:61], v[154:157], v[184:187], v[58:61]
	v_mfma_f32_16x16x32_bf16 v[50:53], v[154:157], v[200:203], v[50:53]
	v_mfma_f32_16x16x32_bf16 v[50:53], v[158:161], v[204:207], v[50:53]
	v_mfma_f32_16x16x32_bf16 v[34:37], v[158:161], v[212:215], v[34:37]
	v_mfma_f32_16x16x32_bf16 v[34:37], v[154:157], v[208:211], v[34:37]
	s_setprio 0
	s_setprio 1
	v_mfma_f32_16x16x32_bf16 v[14:17], v[168:171], v[208:211], v[14:17]
	v_mfma_f32_16x16x32_bf16 v[14:17], v[172:175], v[212:215], v[14:17]
	v_mfma_f32_16x16x32_bf16 v[46:49], v[172:175], v[188:191], v[46:49]
	v_mfma_f32_16x16x32_bf16 v[46:49], v[168:171], v[184:187], v[46:49]
	v_mfma_f32_16x16x32_bf16 v[30:33], v[168:171], v[200:203], v[30:33]
	v_mfma_f32_16x16x32_bf16 v[30:33], v[172:175], v[204:207], v[30:33]
	v_mfma_f32_16x16x32_bf16 v[6:9], v[172:175], v[220:223], v[6:9]
	v_mfma_f32_16x16x32_bf16 v[6:9], v[168:171], v[216:219], v[6:9]
	v_mfma_f32_16x16x32_bf16 v[2:5], v[176:179], v[216:219], v[2:5]
	v_mfma_f32_16x16x32_bf16 v[2:5], v[180:183], v[220:223], v[2:5]
	v_mfma_f32_16x16x32_bf16 v[38:41], v[180:183], v[188:191], v[38:41]
	v_mfma_f32_16x16x32_bf16 v[38:41], v[176:179], v[184:187], v[38:41]
	v_mfma_f32_16x16x32_bf16 v[22:25], v[176:179], v[200:203], v[22:25]
	v_mfma_f32_16x16x32_bf16 v[22:25], v[180:183], v[204:207], v[22:25]
	v_mfma_f32_16x16x32_bf16 v[10:13], v[180:183], v[212:215], v[10:13]
	v_mfma_f32_16x16x32_bf16 v[10:13], v[176:179], v[208:211], v[10:13]
	s_barrier
	s_setprio 0
	s_add_i32 s30, s30, 2
	s_cmp_gt_u32 s30, 13
	s_mov_b64 s[46:47], s[50:51]
	s_cbranch_scc0 .LBB0_1230
	s_cmpk_lt_u32 s2, 0x100
	s_cbranch_scc0 .LBB0_1233
	s_barrier

; #define PG8_STAGE(bufoff, gbase, voff) do { _Pragma("unroll") for (int _i = 0; _i < 2; ++_i) \
;         __builtin_amdgcn_global_load_lds((const unsigned*)((const char*)(gbase) + (voff)[_i]), (PG8_LAS unsigned*)(lds + (bufoff) + ldsw + _i * 8192), 16, 0, 0); } while (0)
; #define PG8_LDA(dst, b, h) do { _Pragma("unroll") for (int m = 0; m < 4; ++m) _Pragma("unroll") for (int k = 0; k < 2; ++k) dst[m][k] = *(const PG8_LAS bf16x8*)(lds + PG8_SA(b, h) + aoff + m * 2048 + k * 1024); } while (0)
; #define PG8_LDB(dst, b, h) do { _Pragma("unroll") for (int n = 0; n < 2; ++n) _Pragma("unroll") for (int k = 0; k < 2; ++k) dst[n][k] = *(const PG8_LAS bf16x8*)(lds + PG8_SB(b, h) + boff + n * 2048 + k * 1024); } while (0)
; #define PG8_MMA(ai, bj, At, Bt) do { __builtin_amdgcn_s_setprio(1); _Pragma("unroll") for (int m = 0; m < 4; ++m) _Pragma("unroll") for (int n = 0; n < 2; ++n) _Pragma("unroll") for (int k = 0; k < 2; ++k) \
;         acc[ai][bj][m][n] = __builtin_amdgcn_mfma_f32_16x16x32_bf16(Bt[n][k], At[m][k], acc[ai][bj][m][n], 0, 0, 0); __builtin_amdgcn_s_setprio(0); } while (0)
; #define PG8_WAIT_V(n) asm volatile("s_waitcnt vmcnt(" #n ")" ::: "memory")
; #define PG8_WAIT_L(n) asm volatile("s_waitcnt lgkmcnt(" #n ")" ::: "memory")
; template <class Epi, class Sched, bool ALIGN_EPI = false, bool SP2 = false>
; __device__ __forceinline__ void gemm_phase(PG8_LAS unsigned char* lds, const Gemm g, const Sched& S, const Epi& E) {
;     ...
;             const bool last = (t == nt - 2);
;             const char* a1 = cA + (size_t)(t + 1) * kstep;
;             const char* a2 = last ? nA : cA + (size_t)(t + 2) * kstep; const char* b2 = last ? nB : cB + (size_t)(t + 2) * kstep;
;             const char* a3 = a2 + kstep; const char* b3 = b2 + kstep;
;             if (last && has_next) S.a_ready(nxt);
;             if constexpr (SP2) {
;             PG8_LDB(B0, 0, 0); PG8_LDB(B1, 0, 1); PG8_SCHED; PG8_LDA(At, 0, 0); PG8_STAGE(PG8_SA(1, 1), a1 + hstep, voffA);
;             PG8_WAIT_V(8); PG8_WAIT_L(0); PG8_BAR; PG8_MMA(0, 0, At, B0); PG8_MMA(0, 1, At, B1); PG8_BAR; PG8_SCHED;
;             PG8_LDA(At, 0, 1); PG8_STAGE(PG8_SB(0, 0), b2, voffB); PG8_STAGE(PG8_SB(0, 1), b2 + hstep, voffB); PG8_STAGE(PG8_SA(0, 0), a2, voffA);
;             PG8_WAIT_V(8); PG8_WAIT_L(0); PG8_BAR; PG8_MMA(1, 0, At, B0); PG8_MMA(1, 1, At, B1); PG8_BAR; PG8_SCHED;
.LBB0_1478:
	v_add_u32_e32 v144, s31, v201
	v_add_u32_e32 v160, s52, v201
	ds_read_b128 v[132:135], v144
	ds_read_b128 v[136:139], v144 offset:1024
	ds_read_b128 v[140:143], v144 offset:2048
	ds_read_b128 v[144:147], v144 offset:3072
	ds_read_b128 v[148:151], v160
	ds_read_b128 v[152:155], v160 offset:1024
	ds_read_b128 v[156:159], v160 offset:2048
	ds_read_b128 v[160:163], v160 offset:3072
	s_add_u32 s50, s82, 0xfff00080
	s_addc_u32 s56, s83, -1
	s_and_b64 s[34:35], s[84:85], exec
	s_cselect_b32 s87, s65, s56
	s_cselect_b32 s86, s69, s50
	s_cselect_b32 s85, s67, s88
	s_cselect_b32 s84, s77, s79
	v_lshl_add_u64 v[192:193], s[82:83], 0, v[220:221]
	s_add_i32 m0, s28, 0xc000
	ds_read_b128 v[164:167], v242
	ds_read_b128 v[168:171], v242 offset:1024
	ds_read_b128 v[172:175], v242 offset:2048
	ds_read_b128 v[176:179], v242 offset:3072
	ds_read_b128 v[180:183], v242 offset:4096
	ds_read_b128 v[184:187], v242 offset:5120
	ds_read_b128 v[188:191], v242 offset:6144
	ds_read_b128 v[226:229], v242 offset:7168
	global_load_lds_dwordx4 v[192:193], off
	v_lshl_add_u64 v[192:193], s[82:83], 0, v[222:223]
	s_add_i32 m0, s28, 0xe000
	s_nop 0
	global_load_lds_dwordx4 v[192:193], off
	s_waitcnt vmcnt(8)
	s_waitcnt lgkmcnt(0)
	s_setprio 1
	s_barrier
	v_mfma_f32_16x16x32_bf16 v[126:129], v[132:135], v[164:167], v[126:129]
	v_mfma_f32_16x16x32_bf16 v[126:129], v[136:139], v[168:171], v[126:129]
	v_mfma_f32_16x16x32_bf16 v[118:121], v[136:139], v[176:179], v[118:121]
	v_mfma_f32_16x16x32_bf16 v[118:121], v[132:135], v[172:175], v[118:121]
	v_mfma_f32_16x16x32_bf16 v[110:113], v[132:135], v[180:183], v[110:113]
	v_mfma_f32_16x16x32_bf16 v[110:113], v[136:139], v[184:187], v[110:113]
	v_mfma_f32_16x16x32_bf16 v[102:105], v[136:139], v[226:229], v[102:105]
	v_mfma_f32_16x16x32_bf16 v[102:105], v[132:135], v[188:191], v[102:105]
	v_mfma_f32_16x16x32_bf16 v[106:109], v[140:143], v[188:191], v[106:109]
	v_mfma_f32_16x16x32_bf16 v[106:109], v[144:147], v[226:229], v[106:109]
	v_mfma_f32_16x16x32_bf16 v[46:49], v[144:147], v[168:171], v[46:49]
	v_mfma_f32_16x16x32_bf16 v[46:49], v[140:143], v[164:167], v[46:49]
	v_mfma_f32_16x16x32_bf16 v[122:125], v[140:143], v[172:175], v[122:125]
	v_mfma_f32_16x16x32_bf16 v[122:125], v[144:147], v[176:179], v[122:125]
	v_mfma_f32_16x16x32_bf16 v[114:117], v[144:147], v[184:187], v[114:117]
	v_mfma_f32_16x16x32_bf16 v[114:117], v[140:143], v[180:183], v[114:117]
	s_setprio 0
	s_setprio 1
	v_mfma_f32_16x16x32_bf16 v[62:65], v[148:151], v[180:183], v[62:65]
	v_mfma_f32_16x16x32_bf16 v[62:65], v[152:155], v[184:187], v[62:65]
	v_mfma_f32_16x16x32_bf16 v[54:57], v[152:155], v[168:171], v[54:57]
	v_mfma_f32_16x16x32_bf16 v[54:57], v[148:151], v[164:167], v[54:57]
	v_mfma_f32_16x16x32_bf16 v[58:61], v[148:151], v[172:175], v[58:61]
	v_mfma_f32_16x16x32_bf16 v[58:61], v[152:155], v[176:179], v[58:61]
	v_mfma_f32_16x16x32_bf16 v[98:101], v[152:155], v[226:229], v[98:101]
	v_mfma_f32_16x16x32_bf16 v[98:101], v[148:151], v[188:191], v[98:101]
	v_mfma_f32_16x16x32_bf16 v[50:53], v[156:159], v[188:191], v[50:53]
	v_mfma_f32_16x16x32_bf16 v[50:53], v[160:163], v[226:229], v[50:53]
	v_mfma_f32_16x16x32_bf16 v[38:41], v[160:163], v[168:171], v[38:41]
	v_mfma_f32_16x16x32_bf16 v[38:41], v[156:159], v[164:167], v[38:41]
	v_mfma_f32_16x16x32_bf16 v[30:33], v[156:159], v[172:175], v[30:33]
	v_mfma_f32_16x16x32_bf16 v[30:33], v[160:163], v[176:179], v[30:33]
	v_mfma_f32_16x16x32_bf16 v[22:25], v[160:163], v[184:187], v[22:25]
	v_mfma_f32_16x16x32_bf16 v[22:25], v[156:159], v[180:183], v[22:25]
	s_barrier
	s_setprio 0
	s_add_i32 s34, s31, s45
	v_lshl_add_u64 v[192:193], s[84:85], 0, v[208:209]
	s_mov_b32 m0, s34
	ds_read_b128 v[164:167], v242 offset:16384
	ds_read_b128 v[168:171], v242 offset:17408
	ds_read_b128 v[172:175], v242 offset:18432
	ds_read_b128 v[176:179], v242 offset:19456
	ds_read_b128 v[180:183], v242 offset:20480
	ds_read_b128 v[184:187], v242 offset:21504
	ds_read_b128 v[188:191], v242 offset:22528
	ds_read_b128 v[226:229], v242 offset:23552
	global_load_lds_dwordx4 v[192:193], off
	s_add_i32 m0, s34, 0x2000
	s_add_u32 s34, s84, 0x100000
	v_lshl_add_u64 v[194:195], s[84:85], 0, v[212:213]
	s_addc_u32 s35, s85, 0
	s_add_i32 s50, s52, s45
	global_load_lds_dwordx4 v[194:195], off
	v_lshl_add_u64 v[230:231], s[34:35], 0, v[208:209]
	s_mov_b32 m0, s50
	v_lshl_add_u64 v[232:233], s[86:87], 0, v[210:211]
	global_load_lds_dwordx4 v[230:231], off
	v_lshl_add_u64 v[230:231], s[34:35], 0, v[212:213]
	s_add_i32 m0, s50, 0x2000
	s_nop 0
	global_load_lds_dwordx4 v[230:231], off
	v_lshl_add_u64 v[230:231], s[86:87], 0, v[206:207]
	s_mov_b32 m0, s28
	s_nop 0
	global_load_lds_dwordx4 v[230:231], off
	s_mov_b32 m0, s29
	s_nop 0
	global_load_lds_dwordx4 v[232:233], off
	s_waitcnt vmcnt(8)
	s_waitcnt lgkmcnt(0)
	s_setprio 1
	s_barrier
; #define PG8_STAGE(bufoff, gbase, voff) do { _Pragma("unroll") for (int _i = 0; _i < 2; ++_i) \
;         __builtin_amdgcn_global_load_lds((const unsigned*)((const char*)(gbase) + (voff)[_i]), (PG8_LAS unsigned*)(lds + (bufoff) + ldsw + _i * 8192), 16, 0, 0); } while (0)
; #define PG8_LDA(dst, b, h) do { _Pragma("unroll") for (int m = 0; m < 4; ++m) _Pragma("unroll") for (int k = 0; k < 2; ++k) dst[m][k] = *(const PG8_LAS bf16x8*)(lds + PG8_SA(b, h) + aoff + m * 2048 + k * 1024); } while (0)
; #define PG8_LDB(dst, b, h) do { _Pragma("unroll") for (int n = 0; n < 2; ++n) _Pragma("unroll") for (int k = 0; k < 2; ++k) dst[n][k] = *(const PG8_LAS bf16x8*)(lds + PG8_SB(b, h) + boff + n * 2048 + k * 1024); } while (0)
; #define PG8_MMA(ai, bj, At, Bt) do { __builtin_amdgcn_s_setprio(1); _Pragma("unroll") for (int m = 0; m < 4; ++m) _Pragma("unroll") for (int n = 0; n < 2; ++n) _Pragma("unroll") for (int k = 0; k < 2; ++k) \
;         acc[ai][bj][m][n] = __builtin_amdgcn_mfma_f32_16x16x32_bf16(Bt[n][k], At[m][k], acc[ai][bj][m][n], 0, 0, 0); __builtin_amdgcn_s_setprio(0); } while (0)
; #define PG8_WAIT_V(n) asm volatile("s_waitcnt vmcnt(" #n ")" ::: "memory")
; #define PG8_WAIT_L(n) asm volatile("s_waitcnt lgkmcnt(" #n ")" ::: "memory")
; #define PG8_BAR __builtin_amdgcn_s_barrier()
; #define PG8_SCHED __builtin_amdgcn_sched_barrier(0)
; template <class Epi, class Sched, bool ALIGN_EPI = false, bool SP2 = false>
; __device__ __forceinline__ void gemm_phase(PG8_LAS unsigned char* lds, const Gemm g, const Sched& S, const Epi& E) {
;     ...
;             PG8_WAIT_V(8); PG8_WAIT_L(0); PG8_BAR; PG8_MMA(1, 0, At, B0); PG8_MMA(1, 1, At, B1); PG8_BAR; PG8_SCHED;
;             PG8_LDB(B0, 1, 0); PG8_LDB(B1, 1, 1); PG8_SCHED; PG8_LDA(At, 1, 0); PG8_STAGE(PG8_SA(0, 1), a2 + hstep, voffA);
;             PG8_WAIT_V(8); PG8_WAIT_L(0); PG8_BAR; PG8_MMA(0, 0, At, B0); PG8_MMA(0, 1, At, B1); PG8_BAR; PG8_SCHED;
	v_mfma_f32_16x16x32_bf16 v[78:81], v[132:135], v[164:167], v[78:81]
	v_mfma_f32_16x16x32_bf16 v[78:81], v[136:139], v[168:171], v[78:81]
	v_mfma_f32_16x16x32_bf16 v[66:69], v[136:139], v[176:179], v[66:69]
	v_mfma_f32_16x16x32_bf16 v[66:69], v[132:135], v[172:175], v[66:69]
	v_mfma_f32_16x16x32_bf16 v[70:73], v[132:135], v[180:183], v[70:73]
	v_mfma_f32_16x16x32_bf16 v[70:73], v[136:139], v[184:187], v[70:73]
	v_mfma_f32_16x16x32_bf16 v[74:77], v[136:139], v[226:229], v[74:77]
	v_mfma_f32_16x16x32_bf16 v[74:77], v[132:135], v[188:191], v[74:77]
	v_mfma_f32_16x16x32_bf16 v[10:13], v[140:143], v[188:191], v[10:13]
	v_mfma_f32_16x16x32_bf16 v[10:13], v[144:147], v[226:229], v[10:13]
	v_mfma_f32_16x16x32_bf16 v[14:17], v[144:147], v[168:171], v[14:17]
	v_mfma_f32_16x16x32_bf16 v[14:17], v[140:143], v[164:167], v[14:17]
	v_mfma_f32_16x16x32_bf16 v[94:97], v[140:143], v[172:175], v[94:97]
	v_mfma_f32_16x16x32_bf16 v[94:97], v[144:147], v[176:179], v[94:97]
	v_mfma_f32_16x16x32_bf16 v[90:93], v[144:147], v[184:187], v[90:93]
	v_mfma_f32_16x16x32_bf16 v[90:93], v[140:143], v[180:183], v[90:93]
	s_setprio 0
	s_setprio 1
	v_mfma_f32_16x16x32_bf16 v[86:89], v[148:151], v[180:183], v[86:89]
	v_mfma_f32_16x16x32_bf16 v[86:89], v[152:155], v[184:187], v[86:89]
	v_mfma_f32_16x16x32_bf16 v[42:45], v[152:155], v[168:171], v[42:45]
	v_mfma_f32_16x16x32_bf16 v[42:45], v[148:151], v[164:167], v[42:45]
	v_mfma_f32_16x16x32_bf16 v[34:37], v[148:151], v[172:175], v[34:37]
	v_mfma_f32_16x16x32_bf16 v[34:37], v[152:155], v[176:179], v[34:37]
	v_mfma_f32_16x16x32_bf16 v[82:85], v[152:155], v[226:229], v[82:85]
	v_mfma_f32_16x16x32_bf16 v[82:85], v[148:151], v[188:191], v[82:85]
	v_mfma_f32_16x16x32_bf16 v[18:21], v[156:159], v[188:191], v[18:21]
	v_mfma_f32_16x16x32_bf16 v[18:21], v[160:163], v[226:229], v[18:21]
	v_mfma_f32_16x16x32_bf16 v[2:5], v[160:163], v[168:171], v[2:5]
	v_mfma_f32_16x16x32_bf16 v[2:5], v[156:159], v[164:167], v[2:5]
	v_mfma_f32_16x16x32_bf16 v[6:9], v[156:159], v[172:175], v[6:9]
	v_mfma_f32_16x16x32_bf16 v[6:9], v[160:163], v[176:179], v[6:9]
	v_mfma_f32_16x16x32_bf16 v[26:29], v[160:163], v[184:187], v[26:29]
	v_mfma_f32_16x16x32_bf16 v[26:29], v[156:159], v[180:183], v[26:29]
	s_barrier
	s_setprio 0
	s_add_i32 s50, 0, 0x18000
	s_add_i32 s56, 0, 0x1c000
	v_add_u32_e32 v144, s50, v201
	v_add_u32_e32 v160, s56, v201
	ds_read_b128 v[132:135], v144
	ds_read_b128 v[136:139], v144 offset:1024
	ds_read_b128 v[140:143], v144 offset:2048
	ds_read_b128 v[144:147], v144 offset:3072
	ds_read_b128 v[148:151], v160
	ds_read_b128 v[152:155], v160 offset:1024
	ds_read_b128 v[156:159], v160 offset:2048
	ds_read_b128 v[160:163], v160 offset:3072
	s_add_u32 s34, s86, 0x100000
	s_addc_u32 s35, s87, 0
	s_mov_b32 m0, s16
	v_lshl_add_u64 v[246:247], s[34:35], 0, v[206:207]
	ds_read_b128 v[164:167], v242 offset:32768
	ds_read_b128 v[168:171], v242 offset:33792
	ds_read_b128 v[172:175], v242 offset:34816
	ds_read_b128 v[176:179], v242 offset:35840
	ds_read_b128 v[180:183], v242 offset:36864
	ds_read_b128 v[184:187], v242 offset:37888
	ds_read_b128 v[188:191], v242 offset:38912
	ds_read_b128 v[226:229], v242 offset:39936
	global_load_lds_dwordx4 v[246:247], off
	v_lshl_add_u64 v[246:247], s[34:35], 0, v[210:211]
	s_mov_b32 m0, s17
	s_nop 0
	global_load_lds_dwordx4 v[246:247], off
	s_waitcnt vmcnt(8)
	s_waitcnt lgkmcnt(0)
	s_setprio 1
	s_barrier
	v_mfma_f32_16x16x32_bf16 v[126:129], v[132:135], v[164:167], v[126:129]
	v_mfma_f32_16x16x32_bf16 v[126:129], v[136:139], v[168:171], v[126:129]
	v_mfma_f32_16x16x32_bf16 v[118:121], v[136:139], v[176:179], v[118:121]
	v_mfma_f32_16x16x32_bf16 v[118:121], v[132:135], v[172:175], v[118:121]
	v_mfma_f32_16x16x32_bf16 v[110:113], v[132:135], v[180:183], v[110:113]
	v_mfma_f32_16x16x32_bf16 v[110:113], v[136:139], v[184:187], v[110:113]
	v_mfma_f32_16x16x32_bf16 v[102:105], v[136:139], v[226:229], v[102:105]
	v_mfma_f32_16x16x32_bf16 v[102:105], v[132:135], v[188:191], v[102:105]
	v_mfma_f32_16x16x32_bf16 v[106:109], v[140:143], v[188:191], v[106:109]
	v_mfma_f32_16x16x32_bf16 v[106:109], v[144:147], v[226:229], v[106:109]
	v_mfma_f32_16x16x32_bf16 v[46:49], v[144:147], v[168:171], v[46:49]
	v_mfma_f32_16x16x32_bf16 v[46:49], v[140:143], v[164:167], v[46:49]
	v_mfma_f32_16x16x32_bf16 v[122:125], v[140:143], v[172:175], v[122:125]
	v_mfma_f32_16x16x32_bf16 v[122:125], v[144:147], v[176:179], v[122:125]
	v_mfma_f32_16x16x32_bf16 v[114:117], v[144:147], v[184:187], v[114:117]
	v_mfma_f32_16x16x32_bf16 v[114:117], v[140:143], v[180:183], v[114:117]
	s_setprio 0
	s_setprio 1
	v_mfma_f32_16x16x32_bf16 v[62:65], v[148:151], v[180:183], v[62:65]
	v_mfma_f32_16x16x32_bf16 v[62:65], v[152:155], v[184:187], v[62:65]
	v_mfma_f32_16x16x32_bf16 v[54:57], v[152:155], v[168:171], v[54:57]
	v_mfma_f32_16x16x32_bf16 v[54:57], v[148:151], v[164:167], v[54:57]
	v_mfma_f32_16x16x32_bf16 v[58:61], v[148:151], v[172:175], v[58:61]
	v_mfma_f32_16x16x32_bf16 v[58:61], v[152:155], v[176:179], v[58:61]
	v_mfma_f32_16x16x32_bf16 v[98:101], v[152:155], v[226:229], v[98:101]
	v_mfma_f32_16x16x32_bf16 v[98:101], v[148:151], v[188:191], v[98:101]
	v_mfma_f32_16x16x32_bf16 v[50:53], v[156:159], v[188:191], v[50:53]
	v_mfma_f32_16x16x32_bf16 v[50:53], v[160:163], v[226:229], v[50:53]
	v_mfma_f32_16x16x32_bf16 v[38:41], v[160:163], v[168:171], v[38:41]
	v_mfma_f32_16x16x32_bf16 v[38:41], v[156:159], v[164:167], v[38:41]
	v_mfma_f32_16x16x32_bf16 v[30:33], v[156:159], v[172:175], v[30:33]
	v_mfma_f32_16x16x32_bf16 v[30:33], v[160:163], v[176:179], v[30:33]
	v_mfma_f32_16x16x32_bf16 v[22:25], v[160:163], v[184:187], v[22:25]
	v_mfma_f32_16x16x32_bf16 v[22:25], v[156:159], v[180:183], v[22:25]
	s_barrier
; #define PG8_STAGE(bufoff, gbase, voff) do { _Pragma("unroll") for (int _i = 0; _i < 2; ++_i) \
;         __builtin_amdgcn_global_load_lds((const unsigned*)((const char*)(gbase) + (voff)[_i]), (PG8_LAS unsigned*)(lds + (bufoff) + ldsw + _i * 8192), 16, 0, 0); } while (0)
; #define PG8_LDA(dst, b, h) do { _Pragma("unroll") for (int m = 0; m < 4; ++m) _Pragma("unroll") for (int k = 0; k < 2; ++k) dst[m][k] = *(const PG8_LAS bf16x8*)(lds + PG8_SA(b, h) + aoff + m * 2048 + k * 1024); } while (0)
; #define PG8_MMA(ai, bj, At, Bt) do { __builtin_amdgcn_s_setprio(1); _Pragma("unroll") for (int m = 0; m < 4; ++m) _Pragma("unroll") for (int n = 0; n < 2; ++n) _Pragma("unroll") for (int k = 0; k < 2; ++k) \
;         acc[ai][bj][m][n] = __builtin_amdgcn_mfma_f32_16x16x32_bf16(Bt[n][k], At[m][k], acc[ai][bj][m][n], 0, 0, 0); __builtin_amdgcn_s_setprio(0); } while (0)
; #define PG8_WAIT_V(n) asm volatile("s_waitcnt vmcnt(" #n ")" ::: "memory")
; #define PG8_WAIT_L(n) asm volatile("s_waitcnt lgkmcnt(" #n ")" ::: "memory")
; #define PG8_BAR __builtin_amdgcn_s_barrier()
; #define PG8_SCHED __builtin_amdgcn_sched_barrier(0)
; template <class Epi, class Sched, bool ALIGN_EPI = false, bool SP2 = false>
; __device__ __forceinline__ void gemm_phase(PG8_LAS unsigned char* lds, const Gemm g, const Sched& S, const Epi& E) {
;     ...
;         for (int t = 0; t < nt; t += 2) {
;     ...
;             PG8_LDA(At, 1, 1); PG8_STAGE(PG8_SB(1, 0), b3, voffB); PG8_STAGE(PG8_SB(1, 1), b3 + hstep, voffB); PG8_STAGE(PG8_SA(1, 0), a3, voffA);
;             PG8_WAIT_V(8); PG8_WAIT_L(0); PG8_BAR; PG8_MMA(1, 0, At, B0); PG8_MMA(1, 1, At, B1); PG8_BAR; PG8_SCHED;
	s_setprio 0
	s_add_i32 s34, s50, s45
	v_lshl_add_u64 v[192:193], v[192:193], 0, s[54:55]
	s_mov_b32 m0, s34
	ds_read_b128 v[164:167], v242 offset:49152
	ds_read_b128 v[168:171], v242 offset:50176
	ds_read_b128 v[172:175], v242 offset:51200
	ds_read_b128 v[176:179], v242 offset:52224
	ds_read_b128 v[180:183], v242 offset:53248
	ds_read_b128 v[184:187], v242 offset:54272
	ds_read_b128 v[188:191], v242 offset:55296
	ds_read_b128 v[226:229], v242 offset:56320
	global_load_lds_dwordx4 v[192:193], off
	s_add_i32 m0, s34, 0x2000
	s_add_u32 s34, s84, 0x100080
	v_lshl_add_u64 v[192:193], v[194:195], 0, s[54:55]
	s_addc_u32 s35, s85, 0
	s_add_i32 s50, s56, s45
	global_load_lds_dwordx4 v[192:193], off
	v_lshl_add_u64 v[192:193], s[34:35], 0, v[208:209]
	s_mov_b32 m0, s50
	s_nop 0
	global_load_lds_dwordx4 v[192:193], off
	v_lshl_add_u64 v[192:193], s[34:35], 0, v[212:213]
	s_add_i32 m0, s50, 0x2000
	s_nop 0
	global_load_lds_dwordx4 v[192:193], off
	v_lshl_add_u64 v[192:193], v[230:231], 0, s[54:55]
	s_mov_b32 m0, s39
	s_nop 0
	global_load_lds_dwordx4 v[192:193], off
	v_lshl_add_u64 v[192:193], v[232:233], 0, s[54:55]
	s_mov_b32 m0, s46
	s_nop 0
	global_load_lds_dwordx4 v[192:193], off
	s_waitcnt vmcnt(8)
	s_waitcnt lgkmcnt(0)
	s_setprio 1
	s_barrier
	v_mfma_f32_16x16x32_bf16 v[78:81], v[132:135], v[164:167], v[78:81]
	v_mfma_f32_16x16x32_bf16 v[78:81], v[136:139], v[168:171], v[78:81]
	v_mfma_f32_16x16x32_bf16 v[66:69], v[136:139], v[176:179], v[66:69]
	v_mfma_f32_16x16x32_bf16 v[66:69], v[132:135], v[172:175], v[66:69]
	v_mfma_f32_16x16x32_bf16 v[70:73], v[132:135], v[180:183], v[70:73]
	v_mfma_f32_16x16x32_bf16 v[70:73], v[136:139], v[184:187], v[70:73]
	v_mfma_f32_16x16x32_bf16 v[74:77], v[136:139], v[226:229], v[74:77]
	v_mfma_f32_16x16x32_bf16 v[74:77], v[132:135], v[188:191], v[74:77]
	v_mfma_f32_16x16x32_bf16 v[10:13], v[140:143], v[188:191], v[10:13]
	v_mfma_f32_16x16x32_bf16 v[10:13], v[144:147], v[226:229], v[10:13]
	v_mfma_f32_16x16x32_bf16 v[14:17], v[144:147], v[168:171], v[14:17]
	v_mfma_f32_16x16x32_bf16 v[14:17], v[140:143], v[164:167], v[14:17]
	v_mfma_f32_16x16x32_bf16 v[94:97], v[140:143], v[172:175], v[94:97]
	v_mfma_f32_16x16x32_bf16 v[94:97], v[144:147], v[176:179], v[94:97]
	v_mfma_f32_16x16x32_bf16 v[90:93], v[144:147], v[184:187], v[90:93]
	v_mfma_f32_16x16x32_bf16 v[90:93], v[140:143], v[180:183], v[90:93]
	s_setprio 0
	s_setprio 1
	v_mfma_f32_16x16x32_bf16 v[86:89], v[148:151], v[180:183], v[86:89]
	v_mfma_f32_16x16x32_bf16 v[86:89], v[152:155], v[184:187], v[86:89]
	v_mfma_f32_16x16x32_bf16 v[42:45], v[152:155], v[168:171], v[42:45]
	v_mfma_f32_16x16x32_bf16 v[42:45], v[148:151], v[164:167], v[42:45]
	v_mfma_f32_16x16x32_bf16 v[34:37], v[148:151], v[172:175], v[34:37]
	v_mfma_f32_16x16x32_bf16 v[34:37], v[152:155], v[176:179], v[34:37]
	v_mfma_f32_16x16x32_bf16 v[82:85], v[152:155], v[226:229], v[82:85]
	v_mfma_f32_16x16x32_bf16 v[82:85], v[148:151], v[188:191], v[82:85]
	v_mfma_f32_16x16x32_bf16 v[18:21], v[156:159], v[188:191], v[18:21]
	v_mfma_f32_16x16x32_bf16 v[18:21], v[160:163], v[226:229], v[18:21]
	v_mfma_f32_16x16x32_bf16 v[2:5], v[160:163], v[168:171], v[2:5]
	v_mfma_f32_16x16x32_bf16 v[2:5], v[156:159], v[164:167], v[2:5]
	v_mfma_f32_16x16x32_bf16 v[6:9], v[156:159], v[172:175], v[6:9]
	v_mfma_f32_16x16x32_bf16 v[6:9], v[160:163], v[176:179], v[6:9]
	v_mfma_f32_16x16x32_bf16 v[26:29], v[160:163], v[184:187], v[26:29]
	v_mfma_f32_16x16x32_bf16 v[26:29], v[156:159], v[180:183], v[26:29]
	s_barrier
	s_setprio 0
	s_add_i32 s89, s89, 2
	s_add_u32 s82, s82, 0x100
	s_addc_u32 s83, s83, 0
	s_add_u32 s79, s79, 0x100
	s_addc_u32 s88, s88, 0
	s_cmp_gt_u32 s89, 61
	s_cbranch_scc1 .LBB0_1490

; #define PG8_STAGE(bufoff, gbase, voff) do { _Pragma("unroll") for (int _i = 0; _i < 2; ++_i) \
;         __builtin_amdgcn_global_load_lds((const unsigned*)((const char*)(gbase) + (voff)[_i]), (PG8_LAS unsigned*)(lds + (bufoff) + ldsw + _i * 8192), 16, 0, 0); } while (0)
; #define PG8_LDA(dst, b, h) do { _Pragma("unroll") for (int m = 0; m < 4; ++m) _Pragma("unroll") for (int k = 0; k < 2; ++k) dst[m][k] = *(const PG8_LAS bf16x8*)(lds + PG8_SA(b, h) + aoff + m * 2048 + k * 1024); } while (0)
; #define PG8_LDB(dst, b, h) do { _Pragma("unroll") for (int n = 0; n < 2; ++n) _Pragma("unroll") for (int k = 0; k < 2; ++k) dst[n][k] = *(const PG8_LAS bf16x8*)(lds + PG8_SB(b, h) + boff + n * 2048 + k * 1024); } while (0)
; #define PG8_MMA(ai, bj, At, Bt) do { __builtin_amdgcn_s_setprio(1); _Pragma("unroll") for (int m = 0; m < 4; ++m) _Pragma("unroll") for (int n = 0; n < 2; ++n) _Pragma("unroll") for (int k = 0; k < 2; ++k) \
;         acc[ai][bj][m][n] = __builtin_amdgcn_mfma_f32_16x16x32_bf16(Bt[n][k], At[m][k], acc[ai][bj][m][n], 0, 0, 0); __builtin_amdgcn_s_setprio(0); } while (0)
; #define PG8_WAIT_V(n) asm volatile("s_waitcnt vmcnt(" #n ")" ::: "memory")
; #define PG8_WAIT_L(n) asm volatile("s_waitcnt lgkmcnt(" #n ")" ::: "memory")
; template <class Epi, class Sched, bool ALIGN_EPI = false, bool SP2 = false>
; __device__ __forceinline__ void gemm_phase(PG8_LAS unsigned char* lds, const Gemm g, const Sched& S, const Epi& E) {
;     ...
;             const bool last = (t == nt - 2);
;             const char* a1 = cA + (size_t)(t + 1) * kstep;
;             const char* a2 = last ? nA : cA + (size_t)(t + 2) * kstep; const char* b2 = last ? nB : cB + (size_t)(t + 2) * kstep;
;             const char* a3 = a2 + kstep; const char* b3 = b2 + kstep;
;             if (last && has_next) S.a_ready(nxt);
;             if constexpr (SP2) {
;             PG8_LDB(B0, 0, 0); PG8_LDB(B1, 0, 1); PG8_SCHED; PG8_LDA(At, 0, 0); PG8_STAGE(PG8_SA(1, 1), a1 + hstep, voffA);
;             PG8_WAIT_V(8); PG8_WAIT_L(0); PG8_BAR; PG8_MMA(0, 0, At, B0); PG8_MMA(0, 1, At, B1); PG8_BAR; PG8_SCHED;
;             PG8_LDA(At, 0, 1); PG8_STAGE(PG8_SB(0, 0), b2, voffB); PG8_STAGE(PG8_SB(0, 1), b2 + hstep, voffB); PG8_STAGE(PG8_SA(0, 0), a2, voffA);
;             PG8_WAIT_V(8); PG8_WAIT_L(0); PG8_BAR; PG8_MMA(1, 0, At, B0); PG8_MMA(1, 1, At, B1); PG8_BAR; PG8_SCHED;
.LBB0_1731:
	ds_read_b128 v[170:173], v166
	ds_read_b128 v[174:177], v166 offset:1024
	ds_read_b128 v[178:181], v166 offset:2048
	ds_read_b128 v[182:185], v166 offset:3072
	ds_read_b128 v[186:189], v167
	ds_read_b128 v[190:193], v167 offset:1024
	ds_read_b128 v[196:199], v167 offset:2048
	ds_read_b128 v[202:205], v167 offset:3072
	s_add_u32 s48, s40, 0x100
	s_addc_u32 s49, s41, 0
	s_cmpk_eq_i32 s56, 0xa8
	s_cselect_b32 s53, s7, s49
	s_cselect_b32 s52, s6, s48
	s_cselect_b32 s51, s39, s55
	s_cselect_b32 s50, s38, s54
	v_lshl_add_u64 v[146:147], s[40:41], 0, v[138:139]
	s_add_i32 m0, s16, 0xc000
	ds_read_b128 v[206:209], v168
	ds_read_b128 v[210:213], v168 offset:1024
	ds_read_b128 v[214:217], v168 offset:2048
	ds_read_b128 v[218:221], v168 offset:3072
	ds_read_b128 v[222:225], v168 offset:4096
	ds_read_b128 v[226:229], v168 offset:5120
	ds_read_b128 v[230:233], v168 offset:6144
	ds_read_b128 v[234:237], v168 offset:7168
	global_load_lds_dwordx4 v[146:147], off
	v_lshl_add_u64 v[146:147], s[40:41], 0, v[140:141]
	s_add_i32 m0, s16, 0xe000
	s_nop 0
	global_load_lds_dwordx4 v[146:147], off
	s_waitcnt vmcnt(8)
	s_waitcnt lgkmcnt(0)
	s_setprio 1
	s_barrier
	v_mfma_f32_16x16x32_bf16 v[126:129], v[170:173], v[206:209], v[126:129]
	v_mfma_f32_16x16x32_bf16 v[126:129], v[174:177], v[210:213], v[126:129]
	v_mfma_f32_16x16x32_bf16 v[110:113], v[174:177], v[218:221], v[110:113]
	v_mfma_f32_16x16x32_bf16 v[110:113], v[170:173], v[214:217], v[110:113]
	v_mfma_f32_16x16x32_bf16 v[94:97], v[170:173], v[222:225], v[94:97]
	v_mfma_f32_16x16x32_bf16 v[94:97], v[174:177], v[226:229], v[94:97]
	v_mfma_f32_16x16x32_bf16 v[78:81], v[174:177], v[234:237], v[78:81]
	v_mfma_f32_16x16x32_bf16 v[78:81], v[170:173], v[230:233], v[78:81]
	v_mfma_f32_16x16x32_bf16 v[74:77], v[178:181], v[230:233], v[74:77]
	v_mfma_f32_16x16x32_bf16 v[74:77], v[182:185], v[234:237], v[74:77]
	v_mfma_f32_16x16x32_bf16 v[122:125], v[182:185], v[210:213], v[122:125]
	v_mfma_f32_16x16x32_bf16 v[122:125], v[178:181], v[206:209], v[122:125]
	v_mfma_f32_16x16x32_bf16 v[106:109], v[178:181], v[214:217], v[106:109]
	v_mfma_f32_16x16x32_bf16 v[106:109], v[182:185], v[218:221], v[106:109]
	v_mfma_f32_16x16x32_bf16 v[90:93], v[182:185], v[226:229], v[90:93]
	v_mfma_f32_16x16x32_bf16 v[90:93], v[178:181], v[222:225], v[90:93]
	s_setprio 0
	s_setprio 1
	v_mfma_f32_16x16x32_bf16 v[86:89], v[186:189], v[222:225], v[86:89]
	v_mfma_f32_16x16x32_bf16 v[86:89], v[190:193], v[226:229], v[86:89]
	v_mfma_f32_16x16x32_bf16 v[118:121], v[190:193], v[210:213], v[118:121]
	v_mfma_f32_16x16x32_bf16 v[118:121], v[186:189], v[206:209], v[118:121]
	v_mfma_f32_16x16x32_bf16 v[102:105], v[186:189], v[214:217], v[102:105]
	v_mfma_f32_16x16x32_bf16 v[102:105], v[190:193], v[218:221], v[102:105]
	v_mfma_f32_16x16x32_bf16 v[70:73], v[190:193], v[234:237], v[70:73]
	v_mfma_f32_16x16x32_bf16 v[70:73], v[186:189], v[230:233], v[70:73]
	v_mfma_f32_16x16x32_bf16 v[66:69], v[196:199], v[230:233], v[66:69]
	v_mfma_f32_16x16x32_bf16 v[66:69], v[202:205], v[234:237], v[66:69]
	v_mfma_f32_16x16x32_bf16 v[114:117], v[202:205], v[210:213], v[114:117]
	v_mfma_f32_16x16x32_bf16 v[114:117], v[196:199], v[206:209], v[114:117]
	v_mfma_f32_16x16x32_bf16 v[98:101], v[196:199], v[214:217], v[98:101]
	v_mfma_f32_16x16x32_bf16 v[98:101], v[202:205], v[218:221], v[98:101]
	v_mfma_f32_16x16x32_bf16 v[82:85], v[202:205], v[226:229], v[82:85]
	v_mfma_f32_16x16x32_bf16 v[82:85], v[196:199], v[222:225], v[82:85]
	s_barrier
	s_setprio 0
	s_add_i32 s40, s31, s3
	v_lshl_add_u64 v[146:147], s[50:51], 0, v[132:133]
	s_mov_b32 m0, s40
	ds_read_b128 v[206:209], v168 offset:16384
	ds_read_b128 v[210:213], v168 offset:17408
	ds_read_b128 v[214:217], v168 offset:18432
	ds_read_b128 v[218:221], v168 offset:19456
	ds_read_b128 v[222:225], v168 offset:20480
	ds_read_b128 v[226:229], v168 offset:21504
	ds_read_b128 v[230:233], v168 offset:22528
	ds_read_b128 v[234:237], v168 offset:23552
	global_load_lds_dwordx4 v[146:147], off
	s_add_i32 m0, s40, 0x2000
	s_add_u32 s40, s50, 0x2b0000
	v_lshl_add_u64 v[194:195], s[50:51], 0, v[136:137]
	s_addc_u32 s41, s51, 0
	s_add_i32 s57, s35, s3
	global_load_lds_dwordx4 v[194:195], off
	v_lshl_add_u64 v[238:239], s[40:41], 0, v[132:133]
	s_mov_b32 m0, s57
	v_lshl_add_u64 v[240:241], s[52:53], 0, v[134:135]
	global_load_lds_dwordx4 v[238:239], off
	v_lshl_add_u64 v[238:239], s[40:41], 0, v[136:137]
	s_add_i32 m0, s57, 0x2000
	s_nop 0
	global_load_lds_dwordx4 v[238:239], off
	v_lshl_add_u64 v[238:239], s[52:53], 0, v[130:131]
	s_mov_b32 m0, s16
	s_nop 0
	global_load_lds_dwordx4 v[238:239], off
	s_mov_b32 m0, s17
	s_nop 0
	global_load_lds_dwordx4 v[240:241], off
	s_waitcnt vmcnt(8)
	s_waitcnt lgkmcnt(0)
	s_setprio 1
	s_barrier
; #define PG8_STAGE(bufoff, gbase, voff) do { _Pragma("unroll") for (int _i = 0; _i < 2; ++_i) \
;         __builtin_amdgcn_global_load_lds((const unsigned*)((const char*)(gbase) + (voff)[_i]), (PG8_LAS unsigned*)(lds + (bufoff) + ldsw + _i * 8192), 16, 0, 0); } while (0)
; #define PG8_LDA(dst, b, h) do { _Pragma("unroll") for (int m = 0; m < 4; ++m) _Pragma("unroll") for (int k = 0; k < 2; ++k) dst[m][k] = *(const PG8_LAS bf16x8*)(lds + PG8_SA(b, h) + aoff + m * 2048 + k * 1024); } while (0)
; #define PG8_LDB(dst, b, h) do { _Pragma("unroll") for (int n = 0; n < 2; ++n) _Pragma("unroll") for (int k = 0; k < 2; ++k) dst[n][k] = *(const PG8_LAS bf16x8*)(lds + PG8_SB(b, h) + boff + n * 2048 + k * 1024); } while (0)
; #define PG8_MMA(ai, bj, At, Bt) do { __builtin_amdgcn_s_setprio(1); _Pragma("unroll") for (int m = 0; m < 4; ++m) _Pragma("unroll") for (int n = 0; n < 2; ++n) _Pragma("unroll") for (int k = 0; k < 2; ++k) \
;         acc[ai][bj][m][n] = __builtin_amdgcn_mfma_f32_16x16x32_bf16(Bt[n][k], At[m][k], acc[ai][bj][m][n], 0, 0, 0); __builtin_amdgcn_s_setprio(0); } while (0)
; #define PG8_WAIT_V(n) asm volatile("s_waitcnt vmcnt(" #n ")" ::: "memory")
; #define PG8_WAIT_L(n) asm volatile("s_waitcnt lgkmcnt(" #n ")" ::: "memory")
; #define PG8_BAR __builtin_amdgcn_s_barrier()
; #define PG8_SCHED __builtin_amdgcn_sched_barrier(0)
; template <class Epi, class Sched, bool ALIGN_EPI = false, bool SP2 = false>
; __device__ __forceinline__ void gemm_phase(PG8_LAS unsigned char* lds, const Gemm g, const Sched& S, const Epi& E) {
;     ...
;             PG8_WAIT_V(8); PG8_WAIT_L(0); PG8_BAR; PG8_MMA(1, 0, At, B0); PG8_MMA(1, 1, At, B1); PG8_BAR; PG8_SCHED;
;             PG8_LDB(B0, 1, 0); PG8_LDB(B1, 1, 1); PG8_SCHED; PG8_LDA(At, 1, 0); PG8_STAGE(PG8_SA(0, 1), a2 + hstep, voffA);
;             PG8_WAIT_V(8); PG8_WAIT_L(0); PG8_BAR; PG8_MMA(0, 0, At, B0); PG8_MMA(0, 1, At, B1); PG8_BAR; PG8_SCHED;
	v_mfma_f32_16x16x32_bf16 v[62:65], v[170:173], v[206:209], v[62:65]
	v_mfma_f32_16x16x32_bf16 v[62:65], v[174:177], v[210:213], v[62:65]
	v_mfma_f32_16x16x32_bf16 v[46:49], v[174:177], v[218:221], v[46:49]
	v_mfma_f32_16x16x32_bf16 v[46:49], v[170:173], v[214:217], v[46:49]
	v_mfma_f32_16x16x32_bf16 v[30:33], v[170:173], v[222:225], v[30:33]
	v_mfma_f32_16x16x32_bf16 v[30:33], v[174:177], v[226:229], v[30:33]
	v_mfma_f32_16x16x32_bf16 v[14:17], v[174:177], v[234:237], v[14:17]
	v_mfma_f32_16x16x32_bf16 v[14:17], v[170:173], v[230:233], v[14:17]
	v_mfma_f32_16x16x32_bf16 v[10:13], v[178:181], v[230:233], v[10:13]
	v_mfma_f32_16x16x32_bf16 v[10:13], v[182:185], v[234:237], v[10:13]
	v_mfma_f32_16x16x32_bf16 v[58:61], v[182:185], v[210:213], v[58:61]
	v_mfma_f32_16x16x32_bf16 v[58:61], v[178:181], v[206:209], v[58:61]
	v_mfma_f32_16x16x32_bf16 v[42:45], v[178:181], v[214:217], v[42:45]
	v_mfma_f32_16x16x32_bf16 v[42:45], v[182:185], v[218:221], v[42:45]
	v_mfma_f32_16x16x32_bf16 v[26:29], v[182:185], v[226:229], v[26:29]
	v_mfma_f32_16x16x32_bf16 v[26:29], v[178:181], v[222:225], v[26:29]
	s_setprio 0
	s_setprio 1
	v_mfma_f32_16x16x32_bf16 v[22:25], v[186:189], v[222:225], v[22:25]
	v_mfma_f32_16x16x32_bf16 v[22:25], v[190:193], v[226:229], v[22:25]
	v_mfma_f32_16x16x32_bf16 v[54:57], v[190:193], v[210:213], v[54:57]
	v_mfma_f32_16x16x32_bf16 v[54:57], v[186:189], v[206:209], v[54:57]
	v_mfma_f32_16x16x32_bf16 v[38:41], v[186:189], v[214:217], v[38:41]
	v_mfma_f32_16x16x32_bf16 v[38:41], v[190:193], v[218:221], v[38:41]
	v_mfma_f32_16x16x32_bf16 v[6:9], v[190:193], v[234:237], v[6:9]
	v_mfma_f32_16x16x32_bf16 v[6:9], v[186:189], v[230:233], v[6:9]
	v_mfma_f32_16x16x32_bf16 v[2:5], v[196:199], v[230:233], v[2:5]
	v_mfma_f32_16x16x32_bf16 v[2:5], v[202:205], v[234:237], v[2:5]
	v_mfma_f32_16x16x32_bf16 v[50:53], v[202:205], v[210:213], v[50:53]
	v_mfma_f32_16x16x32_bf16 v[50:53], v[196:199], v[206:209], v[50:53]
	v_mfma_f32_16x16x32_bf16 v[34:37], v[196:199], v[214:217], v[34:37]
	v_mfma_f32_16x16x32_bf16 v[34:37], v[202:205], v[218:221], v[34:37]
	v_mfma_f32_16x16x32_bf16 v[18:21], v[202:205], v[226:229], v[18:21]
	v_mfma_f32_16x16x32_bf16 v[18:21], v[196:199], v[222:225], v[18:21]
	s_barrier
	s_setprio 0
	s_add_i32 s57, 0, 0x18000
	v_add_u32_e32 v169, s57, v148
	s_add_i32 s58, 0, 0x1c000
	ds_read_b128 v[170:173], v169
	ds_read_b128 v[174:177], v169 offset:1024
	ds_read_b128 v[178:181], v169 offset:2048
	ds_read_b128 v[182:185], v169 offset:3072
	v_add_u32_e32 v169, s58, v148
	ds_read_b128 v[186:189], v169
	ds_read_b128 v[190:193], v169 offset:1024
	ds_read_b128 v[196:199], v169 offset:2048
	ds_read_b128 v[202:205], v169 offset:3072
	s_add_u32 s40, s52, 0x2b0000
	s_addc_u32 s41, s53, 0
	s_mov_b32 m0, s25
	v_lshl_add_u64 v[242:243], s[40:41], 0, v[130:131]
	ds_read_b128 v[206:209], v168 offset:32768
	ds_read_b128 v[210:213], v168 offset:33792
	ds_read_b128 v[214:217], v168 offset:34816
	ds_read_b128 v[218:221], v168 offset:35840
	ds_read_b128 v[222:225], v168 offset:36864
	ds_read_b128 v[226:229], v168 offset:37888
	ds_read_b128 v[230:233], v168 offset:38912
	ds_read_b128 v[234:237], v168 offset:39936
	global_load_lds_dwordx4 v[242:243], off
	v_lshl_add_u64 v[242:243], s[40:41], 0, v[134:135]
	s_mov_b32 m0, s26
	s_nop 0
	global_load_lds_dwordx4 v[242:243], off
	s_waitcnt vmcnt(8)
	s_waitcnt lgkmcnt(0)
	s_setprio 1
	s_barrier
	v_mfma_f32_16x16x32_bf16 v[126:129], v[170:173], v[206:209], v[126:129]
	v_mfma_f32_16x16x32_bf16 v[126:129], v[174:177], v[210:213], v[126:129]
	v_mfma_f32_16x16x32_bf16 v[110:113], v[174:177], v[218:221], v[110:113]
	v_mfma_f32_16x16x32_bf16 v[110:113], v[170:173], v[214:217], v[110:113]
	v_mfma_f32_16x16x32_bf16 v[94:97], v[170:173], v[222:225], v[94:97]
	v_mfma_f32_16x16x32_bf16 v[94:97], v[174:177], v[226:229], v[94:97]
	v_mfma_f32_16x16x32_bf16 v[78:81], v[174:177], v[234:237], v[78:81]
	v_mfma_f32_16x16x32_bf16 v[78:81], v[170:173], v[230:233], v[78:81]
	v_mfma_f32_16x16x32_bf16 v[74:77], v[178:181], v[230:233], v[74:77]
	v_mfma_f32_16x16x32_bf16 v[74:77], v[182:185], v[234:237], v[74:77]
	v_mfma_f32_16x16x32_bf16 v[122:125], v[182:185], v[210:213], v[122:125]
	v_mfma_f32_16x16x32_bf16 v[122:125], v[178:181], v[206:209], v[122:125]
	v_mfma_f32_16x16x32_bf16 v[106:109], v[178:181], v[214:217], v[106:109]
	v_mfma_f32_16x16x32_bf16 v[106:109], v[182:185], v[218:221], v[106:109]
	v_mfma_f32_16x16x32_bf16 v[90:93], v[182:185], v[226:229], v[90:93]
	v_mfma_f32_16x16x32_bf16 v[90:93], v[178:181], v[222:225], v[90:93]
	s_setprio 0
	s_setprio 1
	v_mfma_f32_16x16x32_bf16 v[86:89], v[186:189], v[222:225], v[86:89]
	v_mfma_f32_16x16x32_bf16 v[86:89], v[190:193], v[226:229], v[86:89]
	v_mfma_f32_16x16x32_bf16 v[118:121], v[190:193], v[210:213], v[118:121]
	v_mfma_f32_16x16x32_bf16 v[118:121], v[186:189], v[206:209], v[118:121]
	v_mfma_f32_16x16x32_bf16 v[102:105], v[186:189], v[214:217], v[102:105]
	v_mfma_f32_16x16x32_bf16 v[102:105], v[190:193], v[218:221], v[102:105]
	v_mfma_f32_16x16x32_bf16 v[70:73], v[190:193], v[234:237], v[70:73]
	v_mfma_f32_16x16x32_bf16 v[70:73], v[186:189], v[230:233], v[70:73]
	v_mfma_f32_16x16x32_bf16 v[66:69], v[196:199], v[230:233], v[66:69]
	v_mfma_f32_16x16x32_bf16 v[66:69], v[202:205], v[234:237], v[66:69]
	v_mfma_f32_16x16x32_bf16 v[114:117], v[202:205], v[210:213], v[114:117]
	v_mfma_f32_16x16x32_bf16 v[114:117], v[196:199], v[206:209], v[114:117]
	v_mfma_f32_16x16x32_bf16 v[98:101], v[196:199], v[214:217], v[98:101]
	v_mfma_f32_16x16x32_bf16 v[98:101], v[202:205], v[218:221], v[98:101]
	v_mfma_f32_16x16x32_bf16 v[82:85], v[202:205], v[226:229], v[82:85]
	v_mfma_f32_16x16x32_bf16 v[82:85], v[196:199], v[222:225], v[82:85]
	s_barrier
; #define PG8_STAGE(bufoff, gbase, voff) do { _Pragma("unroll") for (int _i = 0; _i < 2; ++_i) \
;         __builtin_amdgcn_global_load_lds((const unsigned*)((const char*)(gbase) + (voff)[_i]), (PG8_LAS unsigned*)(lds + (bufoff) + ldsw + _i * 8192), 16, 0, 0); } while (0)
; #define PG8_LDA(dst, b, h) do { _Pragma("unroll") for (int m = 0; m < 4; ++m) _Pragma("unroll") for (int k = 0; k < 2; ++k) dst[m][k] = *(const PG8_LAS bf16x8*)(lds + PG8_SA(b, h) + aoff + m * 2048 + k * 1024); } while (0)
; #define PG8_MMA(ai, bj, At, Bt) do { __builtin_amdgcn_s_setprio(1); _Pragma("unroll") for (int m = 0; m < 4; ++m) _Pragma("unroll") for (int n = 0; n < 2; ++n) _Pragma("unroll") for (int k = 0; k < 2; ++k) \
;         acc[ai][bj][m][n] = __builtin_amdgcn_mfma_f32_16x16x32_bf16(Bt[n][k], At[m][k], acc[ai][bj][m][n], 0, 0, 0); __builtin_amdgcn_s_setprio(0); } while (0)
; #define PG8_WAIT_V(n) asm volatile("s_waitcnt vmcnt(" #n ")" ::: "memory")
; #define PG8_WAIT_L(n) asm volatile("s_waitcnt lgkmcnt(" #n ")" ::: "memory")
; #define PG8_BAR __builtin_amdgcn_s_barrier()
; #define PG8_SCHED __builtin_amdgcn_sched_barrier(0)
; template <class Epi, class Sched, bool ALIGN_EPI = false, bool SP2 = false>
; __device__ __forceinline__ void gemm_phase(PG8_LAS unsigned char* lds, const Gemm g, const Sched& S, const Epi& E) {
;     ...
;             PG8_LDA(At, 1, 1); PG8_STAGE(PG8_SB(1, 0), b3, voffB); PG8_STAGE(PG8_SB(1, 1), b3 + hstep, voffB); PG8_STAGE(PG8_SA(1, 0), a3, voffA);
;             PG8_WAIT_V(8); PG8_WAIT_L(0); PG8_BAR; PG8_MMA(1, 0, At, B0); PG8_MMA(1, 1, At, B1); PG8_BAR; PG8_SCHED;
;     ...
;         if constexpr (ALIGN_EPI) { if (wr == 0) PG8_BAR; }
	s_setprio 0
	s_add_i32 s40, s57, s3
	v_lshl_add_u64 v[146:147], v[146:147], 0, s[10:11]
	s_mov_b32 m0, s40
	ds_read_b128 v[206:209], v168 offset:49152
	ds_read_b128 v[210:213], v168 offset:50176
	ds_read_b128 v[214:217], v168 offset:51200
	ds_read_b128 v[218:221], v168 offset:52224
	ds_read_b128 v[222:225], v168 offset:53248
	ds_read_b128 v[226:229], v168 offset:54272
	ds_read_b128 v[230:233], v168 offset:55296
	ds_read_b128 v[234:237], v168 offset:56320
	global_load_lds_dwordx4 v[146:147], off
	s_add_i32 m0, s40, 0x2000
	s_add_u32 s40, s50, 0x2b0080
	v_lshl_add_u64 v[146:147], v[194:195], 0, s[10:11]
	s_addc_u32 s41, s51, 0
	s_add_i32 s50, s58, s3
	global_load_lds_dwordx4 v[146:147], off
	v_lshl_add_u64 v[146:147], s[40:41], 0, v[132:133]
	s_mov_b32 m0, s50
	s_nop 0
	global_load_lds_dwordx4 v[146:147], off
	v_lshl_add_u64 v[146:147], s[40:41], 0, v[136:137]
	s_add_i32 m0, s50, 0x2000
	s_nop 0
	global_load_lds_dwordx4 v[146:147], off
	v_lshl_add_u64 v[146:147], v[238:239], 0, s[10:11]
	s_mov_b32 m0, s28
	s_nop 0
	global_load_lds_dwordx4 v[146:147], off
	v_lshl_add_u64 v[146:147], v[240:241], 0, s[10:11]
	s_mov_b32 m0, s29
	s_nop 0
	global_load_lds_dwordx4 v[146:147], off
	s_waitcnt vmcnt(8)
	s_waitcnt lgkmcnt(0)
	s_setprio 1
	s_barrier
	v_mfma_f32_16x16x32_bf16 v[62:65], v[170:173], v[206:209], v[62:65]
	v_mfma_f32_16x16x32_bf16 v[62:65], v[174:177], v[210:213], v[62:65]
	v_mfma_f32_16x16x32_bf16 v[46:49], v[174:177], v[218:221], v[46:49]
	v_mfma_f32_16x16x32_bf16 v[46:49], v[170:173], v[214:217], v[46:49]
	v_mfma_f32_16x16x32_bf16 v[30:33], v[170:173], v[222:225], v[30:33]
	v_mfma_f32_16x16x32_bf16 v[30:33], v[174:177], v[226:229], v[30:33]
	v_mfma_f32_16x16x32_bf16 v[14:17], v[174:177], v[234:237], v[14:17]
	v_mfma_f32_16x16x32_bf16 v[14:17], v[170:173], v[230:233], v[14:17]
	v_mfma_f32_16x16x32_bf16 v[10:13], v[178:181], v[230:233], v[10:13]
	v_mfma_f32_16x16x32_bf16 v[10:13], v[182:185], v[234:237], v[10:13]
	v_mfma_f32_16x16x32_bf16 v[58:61], v[182:185], v[210:213], v[58:61]
	v_mfma_f32_16x16x32_bf16 v[58:61], v[178:181], v[206:209], v[58:61]
	v_mfma_f32_16x16x32_bf16 v[42:45], v[178:181], v[214:217], v[42:45]
	v_mfma_f32_16x16x32_bf16 v[42:45], v[182:185], v[218:221], v[42:45]
	v_mfma_f32_16x16x32_bf16 v[26:29], v[182:185], v[226:229], v[26:29]
	v_mfma_f32_16x16x32_bf16 v[26:29], v[178:181], v[222:225], v[26:29]
	s_setprio 0
	s_setprio 1
	v_mfma_f32_16x16x32_bf16 v[22:25], v[186:189], v[222:225], v[22:25]
	v_mfma_f32_16x16x32_bf16 v[22:25], v[190:193], v[226:229], v[22:25]
	v_mfma_f32_16x16x32_bf16 v[54:57], v[190:193], v[210:213], v[54:57]
	v_mfma_f32_16x16x32_bf16 v[54:57], v[186:189], v[206:209], v[54:57]
	v_mfma_f32_16x16x32_bf16 v[38:41], v[186:189], v[214:217], v[38:41]
	v_mfma_f32_16x16x32_bf16 v[38:41], v[190:193], v[218:221], v[38:41]
	v_mfma_f32_16x16x32_bf16 v[6:9], v[190:193], v[234:237], v[6:9]
	v_mfma_f32_16x16x32_bf16 v[6:9], v[186:189], v[230:233], v[6:9]
	v_mfma_f32_16x16x32_bf16 v[2:5], v[196:199], v[230:233], v[2:5]
	v_mfma_f32_16x16x32_bf16 v[2:5], v[202:205], v[234:237], v[2:5]
	v_mfma_f32_16x16x32_bf16 v[50:53], v[202:205], v[210:213], v[50:53]
	v_mfma_f32_16x16x32_bf16 v[50:53], v[196:199], v[206:209], v[50:53]
	v_mfma_f32_16x16x32_bf16 v[34:37], v[196:199], v[214:217], v[34:37]
	v_mfma_f32_16x16x32_bf16 v[34:37], v[202:205], v[218:221], v[34:37]
	v_mfma_f32_16x16x32_bf16 v[18:21], v[202:205], v[226:229], v[18:21]
	v_mfma_f32_16x16x32_bf16 v[18:21], v[196:199], v[222:225], v[18:21]
	s_barrier
	s_setprio 0
	s_add_i32 s56, s56, 2
	s_add_u32 s54, s54, 0x100
	s_addc_u32 s55, s55, 0
	s_cmpk_gt_u32 s56, 0xa9
	s_mov_b64 s[40:41], s[48:49]
	s_cbranch_scc0 .LBB0_1731
	s_and_b64 vcc, exec, s[12:13]
	s_cbranch_vccz .LBB0_1734
	s_barrier

; #define PG8_STAGE(bufoff, gbase, voff) do { _Pragma("unroll") for (int _i = 0; _i < 2; ++_i) \
;         __builtin_amdgcn_global_load_lds((const unsigned*)((const char*)(gbase) + (voff)[_i]), (PG8_LAS unsigned*)(lds + (bufoff) + ldsw + _i * 8192), 16, 0, 0); } while (0)
; #define PG8_LDA(dst, b, h) do { _Pragma("unroll") for (int m = 0; m < 4; ++m) _Pragma("unroll") for (int k = 0; k < 2; ++k) dst[m][k] = *(const PG8_LAS bf16x8*)(lds + PG8_SA(b, h) + aoff + m * 2048 + k * 1024); } while (0)
; #define PG8_LDB(dst, b, h) do { _Pragma("unroll") for (int n = 0; n < 2; ++n) _Pragma("unroll") for (int k = 0; k < 2; ++k) dst[n][k] = *(const PG8_LAS bf16x8*)(lds + PG8_SB(b, h) + boff + n * 2048 + k * 1024); } while (0)
; #define PG8_MMA(ai, bj, At, Bt) do { __builtin_amdgcn_s_setprio(1); _Pragma("unroll") for (int m = 0; m < 4; ++m) _Pragma("unroll") for (int n = 0; n < 2; ++n) _Pragma("unroll") for (int k = 0; k < 2; ++k) \
;         acc[ai][bj][m][n] = __builtin_amdgcn_mfma_f32_16x16x32_bf16(Bt[n][k], At[m][k], acc[ai][bj][m][n], 0, 0, 0); __builtin_amdgcn_s_setprio(0); } while (0)
; #define PG8_WAIT_V(n) asm volatile("s_waitcnt vmcnt(" #n ")" ::: "memory")
; #define PG8_WAIT_L(n) asm volatile("s_waitcnt lgkmcnt(" #n ")" ::: "memory")
; template <class Epi, class Sched, bool ALIGN_EPI = false, bool SP2 = false>
; __device__ __forceinline__ void gemm_phase(PG8_LAS unsigned char* lds, const Gemm g, const Sched& S, const Epi& E) {
;     ...
;             const bool last = (t == nt - 2);
;             const char* a1 = cA + (size_t)(t + 1) * kstep;
;             const char* a2 = last ? nA : cA + (size_t)(t + 2) * kstep; const char* b2 = last ? nB : cB + (size_t)(t + 2) * kstep;
;             const char* a3 = a2 + kstep; const char* b3 = b2 + kstep;
;             if (last && has_next) S.a_ready(nxt);
;             if constexpr (SP2) {
;             PG8_LDB(B0, 0, 0); PG8_LDB(B1, 0, 1); PG8_SCHED; PG8_LDA(At, 0, 0); PG8_STAGE(PG8_SA(1, 1), a1 + hstep, voffA);
;             PG8_WAIT_V(8); PG8_WAIT_L(0); PG8_BAR; PG8_MMA(0, 0, At, B0); PG8_MMA(0, 1, At, B1); PG8_BAR; PG8_SCHED;
;             PG8_LDA(At, 0, 1); PG8_STAGE(PG8_SB(0, 0), b2, voffB); PG8_STAGE(PG8_SB(0, 1), b2 + hstep, voffB); PG8_STAGE(PG8_SA(0, 0), a2, voffA);
;             PG8_WAIT_V(8); PG8_WAIT_L(0); PG8_BAR; PG8_MMA(1, 0, At, B0); PG8_MMA(1, 1, At, B1); PG8_BAR; PG8_SCHED;
.LBB0_1746:
	ds_read_b128 v[140:143], v134
	ds_read_b128 v[144:147], v134 offset:1024
	ds_read_b128 v[148:151], v134 offset:2048
	ds_read_b128 v[152:155], v134 offset:3072
	ds_read_b128 v[156:159], v135
	ds_read_b128 v[160:163], v135 offset:1024
	ds_read_b128 v[164:167], v135 offset:2048
	ds_read_b128 v[168:171], v135 offset:3072
	s_add_i32 s36, s38, 2
	s_mov_b32 s37, s11
	s_or_b32 s10, s38, 1
	s_lshl_b64 s[40:41], s[36:37], 7
	s_cmp_lg_u32 s38, s42
	s_cselect_b32 s38, s40, 0
	s_cselect_b32 s37, s41, 0
	s_add_u32 s40, s6, s38
	s_addc_u32 s41, s7, s37
	s_add_u32 s38, s2, s38
	s_addc_u32 s39, s3, s37
	s_lshl_b64 s[52:53], s[10:11], 7
	s_add_u32 s52, s8, s52
	s_addc_u32 s53, s9, s53
	s_mov_b32 m0, s43
	v_lshl_add_u64 v[192:193], s[52:53], 0, v[128:129]
	ds_read_b128 v[172:175], v136
	ds_read_b128 v[176:179], v136 offset:1024
	ds_read_b128 v[180:183], v136 offset:2048
	ds_read_b128 v[184:187], v136 offset:3072
	ds_read_b128 v[188:191], v136 offset:4096
	ds_read_b128 v[196:199], v136 offset:5120
	ds_read_b128 v[202:205], v136 offset:6144
	ds_read_b128 v[206:209], v136 offset:7168
	global_load_lds_dwordx4 v[192:193], off
	v_lshl_add_u64 v[192:193], s[52:53], 0, v[130:131]
	s_mov_b32 m0, s44
	s_nop 0
	global_load_lds_dwordx4 v[192:193], off
	s_waitcnt vmcnt(8)
	s_waitcnt lgkmcnt(0)
	s_setprio 1
	s_barrier
	v_mfma_f32_16x16x32_bf16 v[124:127], v[140:143], v[172:175], v[124:127]
	v_mfma_f32_16x16x32_bf16 v[124:127], v[144:147], v[176:179], v[124:127]
	v_mfma_f32_16x16x32_bf16 v[116:119], v[144:147], v[184:187], v[116:119]
	v_mfma_f32_16x16x32_bf16 v[116:119], v[140:143], v[180:183], v[116:119]
	v_mfma_f32_16x16x32_bf16 v[104:107], v[140:143], v[188:191], v[104:107]
	v_mfma_f32_16x16x32_bf16 v[104:107], v[144:147], v[196:199], v[104:107]
	v_mfma_f32_16x16x32_bf16 v[88:91], v[144:147], v[206:209], v[88:91]
	v_mfma_f32_16x16x32_bf16 v[88:91], v[140:143], v[202:205], v[88:91]
	v_mfma_f32_16x16x32_bf16 v[80:83], v[148:151], v[202:205], v[80:83]
	v_mfma_f32_16x16x32_bf16 v[80:83], v[152:155], v[206:209], v[80:83]
	v_mfma_f32_16x16x32_bf16 v[120:123], v[152:155], v[176:179], v[120:123]
	v_mfma_f32_16x16x32_bf16 v[120:123], v[148:151], v[172:175], v[120:123]
	v_mfma_f32_16x16x32_bf16 v[112:115], v[148:151], v[180:183], v[112:115]
	v_mfma_f32_16x16x32_bf16 v[112:115], v[152:155], v[184:187], v[112:115]
	v_mfma_f32_16x16x32_bf16 v[96:99], v[152:155], v[196:199], v[96:99]
	v_mfma_f32_16x16x32_bf16 v[96:99], v[148:151], v[188:191], v[96:99]
	s_setprio 0
	s_setprio 1
	v_mfma_f32_16x16x32_bf16 v[76:79], v[156:159], v[188:191], v[76:79]
	v_mfma_f32_16x16x32_bf16 v[76:79], v[160:163], v[196:199], v[76:79]
	v_mfma_f32_16x16x32_bf16 v[108:111], v[160:163], v[176:179], v[108:111]
	v_mfma_f32_16x16x32_bf16 v[108:111], v[156:159], v[172:175], v[108:111]
	v_mfma_f32_16x16x32_bf16 v[92:95], v[156:159], v[180:183], v[92:95]
	v_mfma_f32_16x16x32_bf16 v[92:95], v[160:163], v[184:187], v[92:95]
	v_mfma_f32_16x16x32_bf16 v[68:71], v[160:163], v[206:209], v[68:71]
	v_mfma_f32_16x16x32_bf16 v[68:71], v[156:159], v[202:205], v[68:71]
	v_mfma_f32_16x16x32_bf16 v[64:67], v[164:167], v[202:205], v[64:67]
	v_mfma_f32_16x16x32_bf16 v[64:67], v[168:171], v[206:209], v[64:67]
	v_mfma_f32_16x16x32_bf16 v[100:103], v[168:171], v[176:179], v[100:103]
	v_mfma_f32_16x16x32_bf16 v[100:103], v[164:167], v[172:175], v[100:103]
	v_mfma_f32_16x16x32_bf16 v[84:87], v[164:167], v[180:183], v[84:87]
	v_mfma_f32_16x16x32_bf16 v[84:87], v[168:171], v[184:187], v[84:87]
	v_mfma_f32_16x16x32_bf16 v[72:75], v[168:171], v[196:199], v[72:75]
	v_mfma_f32_16x16x32_bf16 v[72:75], v[164:167], v[188:191], v[72:75]
	s_barrier
	s_setprio 0
	s_mov_b32 m0, s31
	v_lshl_add_u64 v[192:193], s[38:39], 0, v[128:129]
	s_add_u32 s52, s38, 0x2b0000
	ds_read_b128 v[172:175], v136 offset:16384
	ds_read_b128 v[176:179], v136 offset:17408
	ds_read_b128 v[180:183], v136 offset:18432
	ds_read_b128 v[184:187], v136 offset:19456
	ds_read_b128 v[188:191], v136 offset:20480
	ds_read_b128 v[196:199], v136 offset:21504
	ds_read_b128 v[202:205], v136 offset:22528
	ds_read_b128 v[206:209], v136 offset:23552
	global_load_lds_dwordx4 v[192:193], off
	v_lshl_add_u64 v[194:195], s[38:39], 0, v[130:131]
	s_mov_b32 m0, s45
	s_addc_u32 s53, s39, 0
	global_load_lds_dwordx4 v[194:195], off
	v_lshl_add_u64 v[210:211], s[52:53], 0, v[128:129]
	s_mov_b32 m0, s46
	v_lshl_add_u64 v[212:213], s[40:41], 0, v[130:131]
	global_load_lds_dwordx4 v[210:211], off
	v_lshl_add_u64 v[210:211], s[52:53], 0, v[130:131]
	s_mov_b32 m0, s47
	s_nop 0
	global_load_lds_dwordx4 v[210:211], off
	v_lshl_add_u64 v[210:211], s[40:41], 0, v[128:129]
	s_mov_b32 m0, s26
	s_nop 0
	global_load_lds_dwordx4 v[210:211], off
	s_mov_b32 m0, s27
	s_nop 0
	global_load_lds_dwordx4 v[212:213], off
	s_waitcnt vmcnt(8)
	s_waitcnt lgkmcnt(0)
	s_setprio 1
	s_barrier
; #define PG8_STAGE(bufoff, gbase, voff) do { _Pragma("unroll") for (int _i = 0; _i < 2; ++_i) \
;         __builtin_amdgcn_global_load_lds((const unsigned*)((const char*)(gbase) + (voff)[_i]), (PG8_LAS unsigned*)(lds + (bufoff) + ldsw + _i * 8192), 16, 0, 0); } while (0)
; #define PG8_LDA(dst, b, h) do { _Pragma("unroll") for (int m = 0; m < 4; ++m) _Pragma("unroll") for (int k = 0; k < 2; ++k) dst[m][k] = *(const PG8_LAS bf16x8*)(lds + PG8_SA(b, h) + aoff + m * 2048 + k * 1024); } while (0)
; #define PG8_LDB(dst, b, h) do { _Pragma("unroll") for (int n = 0; n < 2; ++n) _Pragma("unroll") for (int k = 0; k < 2; ++k) dst[n][k] = *(const PG8_LAS bf16x8*)(lds + PG8_SB(b, h) + boff + n * 2048 + k * 1024); } while (0)
; #define PG8_MMA(ai, bj, At, Bt) do { __builtin_amdgcn_s_setprio(1); _Pragma("unroll") for (int m = 0; m < 4; ++m) _Pragma("unroll") for (int n = 0; n < 2; ++n) _Pragma("unroll") for (int k = 0; k < 2; ++k) \
;         acc[ai][bj][m][n] = __builtin_amdgcn_mfma_f32_16x16x32_bf16(Bt[n][k], At[m][k], acc[ai][bj][m][n], 0, 0, 0); __builtin_amdgcn_s_setprio(0); } while (0)
; #define PG8_WAIT_V(n) asm volatile("s_waitcnt vmcnt(" #n ")" ::: "memory")
; #define PG8_WAIT_L(n) asm volatile("s_waitcnt lgkmcnt(" #n ")" ::: "memory")
; #define PG8_BAR __builtin_amdgcn_s_barrier()
; #define PG8_SCHED __builtin_amdgcn_sched_barrier(0)
; template <class Epi, class Sched, bool ALIGN_EPI = false, bool SP2 = false>
; __device__ __forceinline__ void gemm_phase(PG8_LAS unsigned char* lds, const Gemm g, const Sched& S, const Epi& E) {
;     ...
;             PG8_WAIT_V(8); PG8_WAIT_L(0); PG8_BAR; PG8_MMA(1, 0, At, B0); PG8_MMA(1, 1, At, B1); PG8_BAR; PG8_SCHED;
;             PG8_LDB(B0, 1, 0); PG8_LDB(B1, 1, 1); PG8_SCHED; PG8_LDA(At, 1, 0); PG8_STAGE(PG8_SA(0, 1), a2 + hstep, voffA);
;             PG8_WAIT_V(8); PG8_WAIT_L(0); PG8_BAR; PG8_MMA(0, 0, At, B0); PG8_MMA(0, 1, At, B1); PG8_BAR; PG8_SCHED;
	v_mfma_f32_16x16x32_bf16 v[60:63], v[140:143], v[172:175], v[60:63]
	v_mfma_f32_16x16x32_bf16 v[60:63], v[144:147], v[176:179], v[60:63]
	v_mfma_f32_16x16x32_bf16 v[52:55], v[144:147], v[184:187], v[52:55]
	v_mfma_f32_16x16x32_bf16 v[52:55], v[140:143], v[180:183], v[52:55]
	v_mfma_f32_16x16x32_bf16 v[40:43], v[140:143], v[188:191], v[40:43]
	v_mfma_f32_16x16x32_bf16 v[40:43], v[144:147], v[196:199], v[40:43]
	v_mfma_f32_16x16x32_bf16 v[24:27], v[144:147], v[206:209], v[24:27]
	v_mfma_f32_16x16x32_bf16 v[24:27], v[140:143], v[202:205], v[24:27]
	v_mfma_f32_16x16x32_bf16 v[16:19], v[148:151], v[202:205], v[16:19]
	v_mfma_f32_16x16x32_bf16 v[16:19], v[152:155], v[206:209], v[16:19]
	v_mfma_f32_16x16x32_bf16 v[56:59], v[152:155], v[176:179], v[56:59]
	v_mfma_f32_16x16x32_bf16 v[56:59], v[148:151], v[172:175], v[56:59]
	v_mfma_f32_16x16x32_bf16 v[48:51], v[148:151], v[180:183], v[48:51]
	v_mfma_f32_16x16x32_bf16 v[48:51], v[152:155], v[184:187], v[48:51]
	v_mfma_f32_16x16x32_bf16 v[32:35], v[152:155], v[196:199], v[32:35]
	v_mfma_f32_16x16x32_bf16 v[32:35], v[148:151], v[188:191], v[32:35]
	s_setprio 0
	s_setprio 1
	v_mfma_f32_16x16x32_bf16 v[12:15], v[156:159], v[188:191], v[12:15]
	v_mfma_f32_16x16x32_bf16 v[12:15], v[160:163], v[196:199], v[12:15]
	v_mfma_f32_16x16x32_bf16 v[44:47], v[160:163], v[176:179], v[44:47]
	v_mfma_f32_16x16x32_bf16 v[44:47], v[156:159], v[172:175], v[44:47]
	v_mfma_f32_16x16x32_bf16 v[28:31], v[156:159], v[180:183], v[28:31]
	v_mfma_f32_16x16x32_bf16 v[28:31], v[160:163], v[184:187], v[28:31]
	v_mfma_f32_16x16x32_bf16 v[4:7], v[160:163], v[206:209], v[4:7]
	v_mfma_f32_16x16x32_bf16 v[4:7], v[156:159], v[202:205], v[4:7]
	v_mfma_f32_16x16x32_bf16 v[0:3], v[164:167], v[202:205], v[0:3]
	v_mfma_f32_16x16x32_bf16 v[0:3], v[168:171], v[206:209], v[0:3]
	v_mfma_f32_16x16x32_bf16 v[36:39], v[168:171], v[176:179], v[36:39]
	v_mfma_f32_16x16x32_bf16 v[36:39], v[164:167], v[172:175], v[36:39]
	v_mfma_f32_16x16x32_bf16 v[20:23], v[164:167], v[180:183], v[20:23]
	v_mfma_f32_16x16x32_bf16 v[20:23], v[168:171], v[184:187], v[20:23]
	v_mfma_f32_16x16x32_bf16 v[8:11], v[168:171], v[196:199], v[8:11]
	v_mfma_f32_16x16x32_bf16 v[8:11], v[164:167], v[188:191], v[8:11]
	s_barrier
	s_setprio 0
	ds_read_b128 v[140:143], v137
	ds_read_b128 v[144:147], v137 offset:1024
	ds_read_b128 v[148:151], v137 offset:2048
	ds_read_b128 v[152:155], v137 offset:3072
	ds_read_b128 v[156:159], v138
	ds_read_b128 v[160:163], v138 offset:1024
	ds_read_b128 v[164:167], v138 offset:2048
	ds_read_b128 v[168:171], v138 offset:3072
	s_add_u32 s40, s40, 0x2b0000
	s_addc_u32 s41, s41, 0
	s_mov_b32 m0, s28
	v_lshl_add_u64 v[214:215], s[40:41], 0, v[128:129]
	ds_read_b128 v[172:175], v136 offset:32768
	ds_read_b128 v[176:179], v136 offset:33792
	ds_read_b128 v[180:183], v136 offset:34816
	ds_read_b128 v[184:187], v136 offset:35840
	ds_read_b128 v[188:191], v136 offset:36864
	ds_read_b128 v[196:199], v136 offset:37888
	ds_read_b128 v[202:205], v136 offset:38912
	ds_read_b128 v[206:209], v136 offset:39936
	global_load_lds_dwordx4 v[214:215], off
	v_lshl_add_u64 v[214:215], s[40:41], 0, v[130:131]
	s_mov_b32 m0, s30
	s_nop 0
	global_load_lds_dwordx4 v[214:215], off
	s_waitcnt vmcnt(8)
	s_waitcnt lgkmcnt(0)
	s_setprio 1
	s_barrier
	v_mfma_f32_16x16x32_bf16 v[124:127], v[140:143], v[172:175], v[124:127]
	v_mfma_f32_16x16x32_bf16 v[124:127], v[144:147], v[176:179], v[124:127]
	v_mfma_f32_16x16x32_bf16 v[116:119], v[144:147], v[184:187], v[116:119]
	v_mfma_f32_16x16x32_bf16 v[116:119], v[140:143], v[180:183], v[116:119]
	v_mfma_f32_16x16x32_bf16 v[104:107], v[140:143], v[188:191], v[104:107]
	v_mfma_f32_16x16x32_bf16 v[104:107], v[144:147], v[196:199], v[104:107]
	v_mfma_f32_16x16x32_bf16 v[88:91], v[144:147], v[206:209], v[88:91]
	v_mfma_f32_16x16x32_bf16 v[88:91], v[140:143], v[202:205], v[88:91]
	v_mfma_f32_16x16x32_bf16 v[80:83], v[148:151], v[202:205], v[80:83]
	v_mfma_f32_16x16x32_bf16 v[80:83], v[152:155], v[206:209], v[80:83]
	v_mfma_f32_16x16x32_bf16 v[120:123], v[152:155], v[176:179], v[120:123]
	v_mfma_f32_16x16x32_bf16 v[120:123], v[148:151], v[172:175], v[120:123]
	v_mfma_f32_16x16x32_bf16 v[112:115], v[148:151], v[180:183], v[112:115]
	v_mfma_f32_16x16x32_bf16 v[112:115], v[152:155], v[184:187], v[112:115]
	v_mfma_f32_16x16x32_bf16 v[96:99], v[152:155], v[196:199], v[96:99]
	v_mfma_f32_16x16x32_bf16 v[96:99], v[148:151], v[188:191], v[96:99]
	s_setprio 0
	s_setprio 1
	v_mfma_f32_16x16x32_bf16 v[76:79], v[156:159], v[188:191], v[76:79]
	v_mfma_f32_16x16x32_bf16 v[76:79], v[160:163], v[196:199], v[76:79]
	v_mfma_f32_16x16x32_bf16 v[108:111], v[160:163], v[176:179], v[108:111]
	v_mfma_f32_16x16x32_bf16 v[108:111], v[156:159], v[172:175], v[108:111]
	v_mfma_f32_16x16x32_bf16 v[92:95], v[156:159], v[180:183], v[92:95]
	v_mfma_f32_16x16x32_bf16 v[92:95], v[160:163], v[184:187], v[92:95]
	v_mfma_f32_16x16x32_bf16 v[68:71], v[160:163], v[206:209], v[68:71]
	v_mfma_f32_16x16x32_bf16 v[68:71], v[156:159], v[202:205], v[68:71]
	v_mfma_f32_16x16x32_bf16 v[64:67], v[164:167], v[202:205], v[64:67]
	v_mfma_f32_16x16x32_bf16 v[64:67], v[168:171], v[206:209], v[64:67]
	v_mfma_f32_16x16x32_bf16 v[100:103], v[168:171], v[176:179], v[100:103]
	v_mfma_f32_16x16x32_bf16 v[100:103], v[164:167], v[172:175], v[100:103]
	v_mfma_f32_16x16x32_bf16 v[84:87], v[164:167], v[180:183], v[84:87]
	v_mfma_f32_16x16x32_bf16 v[84:87], v[168:171], v[184:187], v[84:87]
	v_mfma_f32_16x16x32_bf16 v[72:75], v[168:171], v[196:199], v[72:75]
	v_mfma_f32_16x16x32_bf16 v[72:75], v[164:167], v[188:191], v[72:75]
	s_barrier
; #define PG8_STAGE(bufoff, gbase, voff) do { _Pragma("unroll") for (int _i = 0; _i < 2; ++_i) \
;         __builtin_amdgcn_global_load_lds((const unsigned*)((const char*)(gbase) + (voff)[_i]), (PG8_LAS unsigned*)(lds + (bufoff) + ldsw + _i * 8192), 16, 0, 0); } while (0)
; #define PG8_LDA(dst, b, h) do { _Pragma("unroll") for (int m = 0; m < 4; ++m) _Pragma("unroll") for (int k = 0; k < 2; ++k) dst[m][k] = *(const PG8_LAS bf16x8*)(lds + PG8_SA(b, h) + aoff + m * 2048 + k * 1024); } while (0)
; #define PG8_MMA(ai, bj, At, Bt) do { __builtin_amdgcn_s_setprio(1); _Pragma("unroll") for (int m = 0; m < 4; ++m) _Pragma("unroll") for (int n = 0; n < 2; ++n) _Pragma("unroll") for (int k = 0; k < 2; ++k) \
;         acc[ai][bj][m][n] = __builtin_amdgcn_mfma_f32_16x16x32_bf16(Bt[n][k], At[m][k], acc[ai][bj][m][n], 0, 0, 0); __builtin_amdgcn_s_setprio(0); } while (0)
; #define PG8_WAIT_V(n) asm volatile("s_waitcnt vmcnt(" #n ")" ::: "memory")
; #define PG8_WAIT_L(n) asm volatile("s_waitcnt lgkmcnt(" #n ")" ::: "memory")
; #define PG8_BAR __builtin_amdgcn_s_barrier()
; #define PG8_SCHED __builtin_amdgcn_sched_barrier(0)
; template <class Epi, class Sched, bool ALIGN_EPI = false, bool SP2 = false>
; __device__ __forceinline__ void gemm_phase(PG8_LAS unsigned char* lds, const Gemm g, const Sched& S, const Epi& E) {
;     ...
;             PG8_LDA(At, 1, 1); PG8_STAGE(PG8_SB(1, 0), b3, voffB); PG8_STAGE(PG8_SB(1, 1), b3 + hstep, voffB); PG8_STAGE(PG8_SA(1, 0), a3, voffA);
;             PG8_WAIT_V(8); PG8_WAIT_L(0); PG8_BAR; PG8_MMA(1, 0, At, B0); PG8_MMA(1, 1, At, B1); PG8_BAR; PG8_SCHED;
;     ...
;         if constexpr (ALIGN_EPI) { if (wr == 0) PG8_BAR; }
	s_setprio 0
	s_mov_b32 m0, s48
	v_lshl_add_u64 v[192:193], v[192:193], 0, s[12:13]
	s_add_u32 s38, s38, 0x2b0080
	ds_read_b128 v[172:175], v136 offset:49152
	ds_read_b128 v[176:179], v136 offset:50176
	ds_read_b128 v[180:183], v136 offset:51200
	ds_read_b128 v[184:187], v136 offset:52224
	ds_read_b128 v[188:191], v136 offset:53248
	ds_read_b128 v[196:199], v136 offset:54272
	ds_read_b128 v[202:205], v136 offset:55296
	ds_read_b128 v[206:209], v136 offset:56320
	global_load_lds_dwordx4 v[192:193], off
	v_lshl_add_u64 v[192:193], v[194:195], 0, s[12:13]
	s_mov_b32 m0, s49
	s_addc_u32 s39, s39, 0
	global_load_lds_dwordx4 v[192:193], off
	v_lshl_add_u64 v[192:193], s[38:39], 0, v[128:129]
	s_mov_b32 m0, s50
	s_nop 0
	global_load_lds_dwordx4 v[192:193], off
	v_lshl_add_u64 v[192:193], s[38:39], 0, v[130:131]
	s_mov_b32 m0, s51
	s_nop 0
	global_load_lds_dwordx4 v[192:193], off
	v_lshl_add_u64 v[192:193], v[210:211], 0, s[12:13]
	s_mov_b32 m0, s34
	s_nop 0
	global_load_lds_dwordx4 v[192:193], off
	v_lshl_add_u64 v[192:193], v[212:213], 0, s[12:13]
	s_mov_b32 m0, s35
	s_nop 0
	global_load_lds_dwordx4 v[192:193], off
	s_waitcnt vmcnt(8)
	s_waitcnt lgkmcnt(0)
	s_setprio 1
	s_barrier
	v_mfma_f32_16x16x32_bf16 v[60:63], v[140:143], v[172:175], v[60:63]
	v_mfma_f32_16x16x32_bf16 v[60:63], v[144:147], v[176:179], v[60:63]
	v_mfma_f32_16x16x32_bf16 v[52:55], v[144:147], v[184:187], v[52:55]
	v_mfma_f32_16x16x32_bf16 v[52:55], v[140:143], v[180:183], v[52:55]
	v_mfma_f32_16x16x32_bf16 v[40:43], v[140:143], v[188:191], v[40:43]
	v_mfma_f32_16x16x32_bf16 v[40:43], v[144:147], v[196:199], v[40:43]
	v_mfma_f32_16x16x32_bf16 v[24:27], v[144:147], v[206:209], v[24:27]
	v_mfma_f32_16x16x32_bf16 v[24:27], v[140:143], v[202:205], v[24:27]
	v_mfma_f32_16x16x32_bf16 v[16:19], v[148:151], v[202:205], v[16:19]
	v_mfma_f32_16x16x32_bf16 v[16:19], v[152:155], v[206:209], v[16:19]
	v_mfma_f32_16x16x32_bf16 v[56:59], v[152:155], v[176:179], v[56:59]
	v_mfma_f32_16x16x32_bf16 v[56:59], v[148:151], v[172:175], v[56:59]
	v_mfma_f32_16x16x32_bf16 v[48:51], v[148:151], v[180:183], v[48:51]
	v_mfma_f32_16x16x32_bf16 v[48:51], v[152:155], v[184:187], v[48:51]
	v_mfma_f32_16x16x32_bf16 v[32:35], v[152:155], v[196:199], v[32:35]
	v_mfma_f32_16x16x32_bf16 v[32:35], v[148:151], v[188:191], v[32:35]
	s_setprio 0
	s_setprio 1
	v_mfma_f32_16x16x32_bf16 v[12:15], v[156:159], v[188:191], v[12:15]
	v_mfma_f32_16x16x32_bf16 v[12:15], v[160:163], v[196:199], v[12:15]
	v_mfma_f32_16x16x32_bf16 v[44:47], v[160:163], v[176:179], v[44:47]
	v_mfma_f32_16x16x32_bf16 v[44:47], v[156:159], v[172:175], v[44:47]
	v_mfma_f32_16x16x32_bf16 v[28:31], v[156:159], v[180:183], v[28:31]
	v_mfma_f32_16x16x32_bf16 v[28:31], v[160:163], v[184:187], v[28:31]
	v_mfma_f32_16x16x32_bf16 v[4:7], v[160:163], v[206:209], v[4:7]
	v_mfma_f32_16x16x32_bf16 v[4:7], v[156:159], v[202:205], v[4:7]
	v_mfma_f32_16x16x32_bf16 v[0:3], v[164:167], v[202:205], v[0:3]
	v_mfma_f32_16x16x32_bf16 v[0:3], v[168:171], v[206:209], v[0:3]
	v_mfma_f32_16x16x32_bf16 v[36:39], v[168:171], v[176:179], v[36:39]
	v_mfma_f32_16x16x32_bf16 v[36:39], v[164:167], v[172:175], v[36:39]
	v_mfma_f32_16x16x32_bf16 v[20:23], v[164:167], v[180:183], v[20:23]
	v_mfma_f32_16x16x32_bf16 v[20:23], v[168:171], v[184:187], v[20:23]
	v_mfma_f32_16x16x32_bf16 v[8:11], v[168:171], v[196:199], v[8:11]
	v_mfma_f32_16x16x32_bf16 v[8:11], v[164:167], v[188:191], v[8:11]
	s_barrier
	s_setprio 0
	s_cmp_ge_u32 s36, s5
	s_mov_b32 s38, s36
	s_cbranch_scc0 .LBB0_1746
	s_cmpk_lt_u32 s16, 0x100
	s_cbranch_scc0 .LBB0_1749
	s_barrier
